# resid prompt loops: late loads issued before the first wait; ssd_out k-loop fragment loads hoisted
# speedup vs baseline: 1.0005x; 1.0005x over previous
.LBB0_1290:
	s_or_b64 exec, exec, s[4:5]
	v_readlane_b32 s2, v254, 53
	s_waitcnt lgkmcnt(0)
	s_barrier
	v_mov_b32_e32 v0, s2
	ds_read_b32 v0, v0
	s_mov_b64 s[4:5], -1
	s_waitcnt lgkmcnt(0)
	v_readfirstlane_b32 s2, v0
	s_cmpk_gt_i32 s2, 0xff
	s_cbranch_scc1 .LBB0_1285
	s_ashr_i32 s4, s2, 5
	s_and_b32 s3, s2, 31
	s_ashr_i32 s5, s4, 31
	s_lshl_b32 s2, s2, 2
	s_lshl_b32 s16, s3, 6
	s_lshl_b64 s[14:15], s[4:5], 7
	s_and_b32 s2, s2, 0x78
	s_add_u32 s3, s14, s88
	s_addc_u32 s14, s15, 0
	s_add_u32 s2, s3, s2
	s_addc_u32 s3, s14, 0
	s_lshl_b64 s[2:3], s[2:3], 14
	v_lshl_add_u64 v[4:5], v[86:87], 0, s[2:3]
	v_mov_b32_e32 v103, v96
	v_mov_b32_e32 v105, v96
	s_lshl_b64 s[4:5], s[4:5], 11
	v_lshl_add_u64 v[80:81], v[4:5], 0, v[102:103]
	v_lshl_add_u64 v[82:83], v[4:5], 0, v[104:105]
	s_or_b32 s4, s4, s16
	global_load_dwordx4 v[0:3], v[80:81], off
	global_load_dwordx4 v[4:7], v[82:83], off
	s_lshl_b64 s[14:15], s[4:5], 9
	v_lshl_add_u64 v[12:13], v[88:89], 0, s[14:15]
	v_mov_b32_e32 v107, v96
	v_mov_b32_e32 v109, v96
	v_lshl_add_u64 v[110:111], v[12:13], 0, v[106:107]
	v_lshl_add_u64 v[112:113], v[12:13], 0, v[108:109]
	global_load_dwordx4 v[8:11], v[110:111], off
	global_load_dwordx4 v[12:15], v[112:113], off
	global_load_dwordx4 v[64:67], v[80:81], off offset:32
	global_load_dwordx4 v[68:71], v[82:83], off offset:32
	global_load_dwordx4 v[72:75], v[110:111], off offset:32
	global_load_dwordx4 v[76:79], v[112:113], off offset:32
	global_load_dwordx4 v[116:119], v[80:81], off offset:64
	global_load_dwordx4 v[120:123], v[82:83], off offset:64
	global_load_dwordx4 v[132:135], v[110:111], off offset:64
	global_load_dwordx4 v[136:139], v[112:113], off offset:64
	global_load_dwordx4 v[140:143], v[80:81], off offset:96
	global_load_dwordx4 v[148:151], v[82:83], off offset:96
	global_load_dwordx4 v[152:155], v[110:111], off offset:96
	global_load_dwordx4 v[158:161], v[112:113], off offset:96
	global_load_dwordx4 v[162:165], v[80:81], off offset:128
	global_load_dwordx4 v[166:169], v[82:83], off offset:128
	global_load_dwordx4 v[170:173], v[110:111], off offset:128
	global_load_dwordx4 v[186:189], v[112:113], off offset:128
	global_load_dwordx4 v[190:193], v[80:81], off offset:160
	global_load_dwordx4 v[194:197], v[82:83], off offset:160
	global_load_dwordx4 v[198:201], v[110:111], off offset:160
	global_load_dwordx4 v[202:205], v[112:113], off offset:160
	global_load_dwordx4 v[206:209], v[80:81], off offset:192
	global_load_dwordx4 v[210:213], v[82:83], off offset:192
	global_load_dwordx4 v[214:217], v[110:111], off offset:192
	global_load_dwordx4 v[218:221], v[112:113], off offset:192
	global_load_dwordx4 v[222:225], v[80:81], off offset:224
	global_load_dwordx4 v[226:229], v[82:83], off offset:224
	global_load_dwordx4 v[230:233], v[110:111], off offset:224
	global_load_dwordx4 v[236:239], v[112:113], off offset:224
	s_waitcnt vmcnt(29)
	v_mfma_f32_32x32x16_bf16 v[48:63], v[0:3], v[8:11], 0
	v_mfma_f32_32x32x16_bf16 v[32:47], v[4:7], v[8:11], 0
	s_waitcnt vmcnt(28)
	v_mfma_f32_32x32x16_bf16 v[16:31], v[0:3], v[12:15], 0
	v_mfma_f32_32x32x16_bf16 v[0:15], v[4:7], v[12:15], 0
	s_waitcnt vmcnt(25)
	v_mfma_f32_32x32x16_bf16 v[48:63], v[64:67], v[72:75], v[48:63]
	v_mfma_f32_32x32x16_bf16 v[32:47], v[68:71], v[72:75], v[32:47]
	s_waitcnt vmcnt(24)
	v_mfma_f32_32x32x16_bf16 v[16:31], v[64:67], v[76:79], v[16:31]
	v_mfma_f32_32x32x16_bf16 v[0:15], v[68:71], v[76:79], v[0:15]
	s_waitcnt vmcnt(21)
	v_mfma_f32_32x32x16_bf16 v[48:63], v[116:119], v[132:135], v[48:63]
	v_mfma_f32_32x32x16_bf16 v[32:47], v[120:123], v[132:135], v[32:47]
	s_waitcnt vmcnt(20)
	v_mfma_f32_32x32x16_bf16 v[16:31], v[116:119], v[136:139], v[16:31]
	v_mfma_f32_32x32x16_bf16 v[0:15], v[120:123], v[136:139], v[0:15]
	s_waitcnt vmcnt(17)
	v_mfma_f32_32x32x16_bf16 v[48:63], v[140:143], v[152:155], v[48:63]
	v_mfma_f32_32x32x16_bf16 v[32:47], v[148:151], v[152:155], v[32:47]
	s_waitcnt vmcnt(16)
	v_mfma_f32_32x32x16_bf16 v[16:31], v[140:143], v[158:161], v[16:31]
	v_mfma_f32_32x32x16_bf16 v[0:15], v[148:151], v[158:161], v[0:15]
	s_waitcnt vmcnt(13)
	v_mfma_f32_32x32x16_bf16 v[48:63], v[162:165], v[170:173], v[48:63]
	v_mfma_f32_32x32x16_bf16 v[32:47], v[166:169], v[170:173], v[32:47]
	s_waitcnt vmcnt(12)
	v_mfma_f32_32x32x16_bf16 v[16:31], v[162:165], v[186:189], v[16:31]
	v_mfma_f32_32x32x16_bf16 v[0:15], v[166:169], v[186:189], v[0:15]
	s_waitcnt vmcnt(9)
	v_mfma_f32_32x32x16_bf16 v[48:63], v[190:193], v[198:201], v[48:63]
	v_mfma_f32_32x32x16_bf16 v[32:47], v[194:197], v[198:201], v[32:47]
	s_waitcnt vmcnt(8)
	v_mfma_f32_32x32x16_bf16 v[16:31], v[190:193], v[202:205], v[16:31]
	v_mfma_f32_32x32x16_bf16 v[0:15], v[194:197], v[202:205], v[0:15]
	s_waitcnt vmcnt(5)
	v_mfma_f32_32x32x16_bf16 v[48:63], v[206:209], v[214:217], v[48:63]
	v_mfma_f32_32x32x16_bf16 v[32:47], v[210:213], v[214:217], v[32:47]
	s_waitcnt vmcnt(4)
	v_mfma_f32_32x32x16_bf16 v[16:31], v[206:209], v[218:221], v[16:31]
	v_mfma_f32_32x32x16_bf16 v[0:15], v[210:213], v[218:221], v[0:15]
	s_barrier
	s_waitcnt vmcnt(1)
	v_mfma_f32_32x32x16_bf16 v[32:47], v[226:229], v[230:233], v[32:47]
	s_waitcnt vmcnt(0)
	v_mfma_f32_32x32x16_bf16 v[0:15], v[226:229], v[236:239], v[0:15]
	v_mov_b32_e32 v69, s5
	v_or_b32_e32 v68, s4, v84
	v_lshlrev_b64 v[110:111], 11, v[68:69]
	v_mad_u64_u32 v[130:131], s[2:3], v68, s42, v[98:99]
	v_lshl_add_u64 v[128:129], v[94:95], 0, v[110:111]
	v_mfma_f32_32x32x16_bf16 v[48:63], v[222:225], v[230:233], v[48:63]
	v_mfma_f32_32x32x16_bf16 v[16:31], v[222:225], v[236:239], v[16:31]
	v_lshlrev_b64 v[64:65], 5, v[68:69]
	v_lshl_add_u64 v[64:65], s[8:9], 0, v[64:65]
	global_load_dword v64, v[64:65], off
	v_mov_b32_e32 v68, 0x2800
	v_mad_i32_i24 v131, s5, v68, v131
	s_waitcnt vmcnt(0)
	v_exp_f32_e32 v124, v64
	global_load_dwordx4 v[64:67], v[128:129], off
	global_load_dwordx4 v[112:115], v[130:131], off
	global_load_dwordx4 v[120:123], v[128:129], off offset:32
	global_load_dwordx4 v[132:135], v[130:131], off offset:32
	global_load_dwordx4 v[80:83], v[128:129], off offset:64
	global_load_dwordx4 v[76:79], v[130:131], off offset:64
	global_load_dwordx4 v[72:75], v[128:129], off offset:96
	global_load_dwordx4 v[68:71], v[130:131], off offset:96
	s_waitcnt vmcnt(6)
	v_mul_f32_e32 v103, 0xbfb8aa3b, v112
	v_fma_f32 v105, v112, s43, -v103
	v_rndne_f32_e32 v107, v103
	v_fmac_f32_e32 v105, 0xb2a5705f, v112
	v_sub_f32_e32 v103, v103, v107
	v_add_f32_e32 v103, v103, v105
	v_exp_f32_e32 v103, v103
	v_cvt_i32_f32_e32 v105, v107
	v_cmp_nlt_f32_e32 vcc, s34, v112
	v_pk_fma_f32 v[48:49], v[48:49], v[124:125], v[64:65] op_sel_hi:[1,0,1]
	v_pk_fma_f32 v[50:51], v[50:51], v[124:125], v[66:67] op_sel_hi:[1,0,1]
	v_ldexp_f32 v103, v103, v105
	v_cndmask_b32_e32 v103, 0, v103, vcc
	v_cmp_ngt_f32_e32 vcc, s35, v112
	s_waitcnt vmcnt(5)
	v_pk_fma_f32 v[52:53], v[52:53], v[124:125], v[120:121] op_sel_hi:[1,0,1]
	v_cndmask_b32_e32 v116, v179, v103, vcc
	v_mul_f32_e32 v103, 0xbfb8aa3b, v113
	v_fma_f32 v105, v113, s43, -v103
	v_rndne_f32_e32 v107, v103
	v_fmac_f32_e32 v105, 0xb2a5705f, v113
	v_sub_f32_e32 v103, v103, v107
	v_add_f32_e32 v103, v103, v105
	v_exp_f32_e32 v103, v103
	v_cvt_i32_f32_e32 v105, v107
	v_cmp_nlt_f32_e32 vcc, s34, v113
	v_ldexp_f32 v103, v103, v105
	s_nop 0
	v_cndmask_b32_e32 v103, 0, v103, vcc
	v_cmp_ngt_f32_e32 vcc, s35, v113
	s_nop 1
	v_cndmask_b32_e32 v117, v179, v103, vcc
	v_pk_add_f32 v[64:65], v[116:117], 1.0 op_sel_hi:[1,0]
	s_nop 0
	v_div_scale_f32 v103, s[2:3], v65, v65, v113
	v_rcp_f32_e32 v105, v103
	s_nop 0
	v_fma_f32 v107, -v103, v105, 1.0
	v_fmac_f32_e32 v105, v107, v105
	v_div_scale_f32 v107, vcc, v113, v65, v113
	v_mul_f32_e32 v109, v107, v105
	v_fma_f32 v116, -v103, v109, v107
	v_fmac_f32_e32 v109, v116, v105
	v_fma_f32 v103, -v103, v109, v107
	v_div_fmas_f32 v103, v103, v105, v109
	v_div_fixup_f32 v65, v103, v65, v113
	v_div_scale_f32 v103, s[2:3], v64, v64, v112
	v_rcp_f32_e32 v105, v103
	s_nop 0
	v_fma_f32 v107, -v103, v105, 1.0
	v_fmac_f32_e32 v105, v107, v105
	v_div_scale_f32 v107, vcc, v112, v64, v112
	v_mul_f32_e32 v109, v107, v105
	v_fma_f32 v113, -v103, v109, v107
	v_fmac_f32_e32 v109, v113, v105
	v_fma_f32 v103, -v103, v109, v107
	v_div_fmas_f32 v103, v103, v105, v109
	v_div_fixup_f32 v64, v103, v64, v112
	v_pk_mul_f32 v[116:117], v[48:49], v[64:65]
	v_mul_f32_e32 v64, 0xbfb8aa3b, v114
	v_fma_f32 v65, v114, s43, -v64
	v_rndne_f32_e32 v103, v64
	v_fmac_f32_e32 v65, 0xb2a5705f, v114
	v_sub_f32_e32 v64, v64, v103
	v_add_f32_e32 v64, v64, v65
	v_exp_f32_e32 v64, v64
	v_cvt_i32_f32_e32 v65, v103
	v_cmp_nlt_f32_e32 vcc, s34, v114
	v_mul_f32_e32 v48, v117, v117
	v_pk_fma_f32 v[48:49], v[116:117], v[116:117], v[48:49] op_sel_hi:[1,1,0]
	v_ldexp_f32 v64, v64, v65
	v_mul_f32_e32 v65, 0xbfb8aa3b, v115
	v_fma_f32 v103, v115, s43, -v65
	v_rndne_f32_e32 v105, v65
	v_fmac_f32_e32 v103, 0xb2a5705f, v115
	v_sub_f32_e32 v65, v65, v105
	v_add_f32_e32 v65, v65, v103
	v_exp_f32_e32 v65, v65
	v_cvt_i32_f32_e32 v103, v105
	v_cndmask_b32_e32 v64, 0, v64, vcc
	v_cmp_ngt_f32_e32 vcc, s35, v114
	v_ldexp_f32 v65, v65, v103
	s_nop 0
	v_cndmask_b32_e32 v64, v179, v64, vcc
	v_cmp_nlt_f32_e32 vcc, s34, v115
	s_nop 1
	v_cndmask_b32_e32 v65, 0, v65, vcc
	v_cmp_ngt_f32_e32 vcc, s35, v115
	s_nop 1
	v_cndmask_b32_e32 v65, v179, v65, vcc
	v_pk_add_f32 v[64:65], v[64:65], 1.0 op_sel_hi:[1,0]
	s_nop 0
	v_div_scale_f32 v66, s[2:3], v65, v65, v115
	v_rcp_f32_e32 v67, v66
	s_nop 0
	v_fma_f32 v103, -v66, v67, 1.0
	v_fmac_f32_e32 v67, v103, v67
	v_div_scale_f32 v103, vcc, v115, v65, v115
	v_mul_f32_e32 v105, v103, v67
	v_fma_f32 v107, -v66, v105, v103
	v_fmac_f32_e32 v105, v107, v67
	v_fma_f32 v66, -v66, v105, v103
	v_div_fmas_f32 v66, v66, v67, v105
	v_div_fixup_f32 v65, v66, v65, v115
	v_div_scale_f32 v66, s[2:3], v64, v64, v114
	v_rcp_f32_e32 v67, v66
	s_nop 0
	v_fma_f32 v103, -v66, v67, 1.0
	v_fmac_f32_e32 v67, v103, v67
	v_div_scale_f32 v103, vcc, v114, v64, v114
	v_mul_f32_e32 v105, v103, v67
	v_fma_f32 v107, -v66, v105, v103
	v_fmac_f32_e32 v105, v107, v67
	v_fma_f32 v66, -v66, v105, v103
	v_div_fmas_f32 v66, v66, v67, v105
	v_div_fixup_f32 v64, v66, v64, v114
	v_pk_mul_f32 v[118:119], v[50:51], v[64:65]
	s_waitcnt vmcnt(4)
	v_cmp_nlt_f32_e32 vcc, s34, v132
	v_pk_fma_f32 v[48:49], v[118:119], v[118:119], v[48:49]
	v_mul_f32_e32 v50, v119, v119
	v_pk_add_f32 v[48:49], v[50:51], v[48:49] op_sel_hi:[0,1]
	v_mul_f32_e32 v50, 0xbfb8aa3b, v132
	v_fma_f32 v51, v132, s43, -v50
	v_rndne_f32_e32 v64, v50
	v_fmac_f32_e32 v51, 0xb2a5705f, v132
	v_sub_f32_e32 v50, v50, v64
	v_add_f32_e32 v50, v50, v51
	v_exp_f32_e32 v50, v50
	v_cvt_i32_f32_e32 v51, v64
	v_ldexp_f32 v50, v50, v51
	v_mul_f32_e32 v51, 0xbfb8aa3b, v133
	v_fma_f32 v64, v133, s43, -v51
	v_rndne_f32_e32 v65, v51
	v_fmac_f32_e32 v64, 0xb2a5705f, v133
	v_sub_f32_e32 v51, v51, v65
	v_add_f32_e32 v51, v51, v64
	v_exp_f32_e32 v51, v51
	v_cvt_i32_f32_e32 v64, v65
	v_cndmask_b32_e32 v50, 0, v50, vcc
	v_cmp_ngt_f32_e32 vcc, s35, v132
	v_ldexp_f32 v51, v51, v64
	s_nop 0
	v_cndmask_b32_e32 v50, v179, v50, vcc
	v_cmp_nlt_f32_e32 vcc, s34, v133
	s_nop 1
	v_cndmask_b32_e32 v51, 0, v51, vcc
	v_cmp_ngt_f32_e32 vcc, s35, v133
	s_nop 1
	v_cndmask_b32_e32 v51, v179, v51, vcc
	v_pk_add_f32 v[50:51], v[50:51], 1.0 op_sel_hi:[1,0]
	s_nop 0
	v_div_scale_f32 v64, s[2:3], v51, v51, v133
	v_rcp_f32_e32 v65, v64
	s_nop 0
	v_fma_f32 v66, -v64, v65, 1.0
	v_fmac_f32_e32 v65, v66, v65
	v_div_scale_f32 v66, vcc, v133, v51, v133
	v_mul_f32_e32 v67, v66, v65
	v_fma_f32 v103, -v64, v67, v66
	v_fmac_f32_e32 v67, v103, v65
	v_fma_f32 v64, -v64, v67, v66
	v_div_fmas_f32 v64, v64, v65, v67
	v_div_fixup_f32 v51, v64, v51, v133
	v_div_scale_f32 v64, s[2:3], v50, v50, v132
	v_rcp_f32_e32 v65, v64
	s_nop 0
	v_fma_f32 v66, -v64, v65, 1.0
	v_fmac_f32_e32 v65, v66, v65
	v_div_scale_f32 v66, vcc, v132, v50, v132
	v_mul_f32_e32 v67, v66, v65
	v_fma_f32 v103, -v64, v67, v66
	v_fmac_f32_e32 v67, v103, v65
	v_fma_f32 v64, -v64, v67, v66
	v_div_fmas_f32 v64, v64, v65, v67
	v_div_fixup_f32 v50, v64, v50, v132
	v_pk_mul_f32 v[112:113], v[52:53], v[50:51]
	v_cmp_nlt_f32_e32 vcc, s34, v134
	v_pk_fma_f32 v[48:49], v[112:113], v[112:113], v[48:49]
	v_mul_f32_e32 v50, v113, v113
	v_pk_add_f32 v[48:49], v[50:51], v[48:49] op_sel_hi:[0,1]
	v_mul_f32_e32 v50, 0xbfb8aa3b, v134
	v_fma_f32 v51, v134, s43, -v50
	v_rndne_f32_e32 v52, v50
	v_fmac_f32_e32 v51, 0xb2a5705f, v134
	v_sub_f32_e32 v50, v50, v52
	v_add_f32_e32 v50, v50, v51
	v_exp_f32_e32 v50, v50
	v_cvt_i32_f32_e32 v51, v52
	v_ldexp_f32 v50, v50, v51
	v_mul_f32_e32 v51, 0xbfb8aa3b, v135
	v_fma_f32 v52, v135, s43, -v51
	v_rndne_f32_e32 v53, v51
	v_fmac_f32_e32 v52, 0xb2a5705f, v135
	v_sub_f32_e32 v51, v51, v53
	v_add_f32_e32 v51, v51, v52
	v_exp_f32_e32 v51, v51
	v_cvt_i32_f32_e32 v52, v53
	v_cndmask_b32_e32 v50, 0, v50, vcc
	v_cmp_ngt_f32_e32 vcc, s35, v134
	v_ldexp_f32 v51, v51, v52
	s_nop 0
	v_cndmask_b32_e32 v50, v179, v50, vcc
	v_cmp_nlt_f32_e32 vcc, s34, v135
	v_pk_fma_f32 v[52:53], v[54:55], v[124:125], v[122:123] op_sel_hi:[1,0,1]
	s_nop 0
	v_cndmask_b32_e32 v51, 0, v51, vcc
	v_cmp_ngt_f32_e32 vcc, s35, v135
	s_nop 1
	v_cndmask_b32_e32 v51, v179, v51, vcc
	v_pk_add_f32 v[50:51], v[50:51], 1.0 op_sel_hi:[1,0]
	s_nop 0
	v_div_scale_f32 v54, s[2:3], v51, v51, v135
	v_rcp_f32_e32 v55, v54
	s_nop 0
	v_fma_f32 v64, -v54, v55, 1.0
	v_fmac_f32_e32 v55, v64, v55
	v_div_scale_f32 v64, vcc, v135, v51, v135
	v_mul_f32_e32 v65, v64, v55
	v_fma_f32 v66, -v54, v65, v64
	v_fmac_f32_e32 v65, v66, v55
	v_fma_f32 v54, -v54, v65, v64
	v_div_fmas_f32 v54, v54, v55, v65
	v_div_fixup_f32 v51, v54, v51, v135
	v_div_scale_f32 v54, s[2:3], v50, v50, v134
	v_rcp_f32_e32 v55, v54
	s_nop 0
	v_fma_f32 v64, -v54, v55, 1.0
	v_fmac_f32_e32 v55, v64, v55
	v_div_scale_f32 v64, vcc, v134, v50, v134
	v_mul_f32_e32 v65, v64, v55
	v_fma_f32 v66, -v54, v65, v64
	v_fmac_f32_e32 v65, v66, v55
	v_fma_f32 v54, -v54, v65, v64
	v_div_fmas_f32 v54, v54, v55, v65
	v_div_fixup_f32 v50, v54, v50, v134
	v_pk_mul_f32 v[114:115], v[52:53], v[50:51]
	s_waitcnt vmcnt(2)
	v_cmp_nlt_f32_e32 vcc, s34, v76
	v_pk_fma_f32 v[48:49], v[114:115], v[114:115], v[48:49]
	v_mul_f32_e32 v50, v115, v115
	v_pk_add_f32 v[48:49], v[50:51], v[48:49] op_sel_hi:[0,1]
	v_mul_f32_e32 v50, 0xbfb8aa3b, v76
	v_fma_f32 v51, v76, s43, -v50
	v_rndne_f32_e32 v52, v50
	v_fmac_f32_e32 v51, 0xb2a5705f, v76
	v_sub_f32_e32 v50, v50, v52
	v_add_f32_e32 v50, v50, v51
	v_exp_f32_e32 v50, v50
	v_cvt_i32_f32_e32 v51, v52
	v_ldexp_f32 v50, v50, v51
	v_mul_f32_e32 v51, 0xbfb8aa3b, v77
	v_fma_f32 v52, v77, s43, -v51
	v_rndne_f32_e32 v53, v51
	v_fmac_f32_e32 v52, 0xb2a5705f, v77
	v_sub_f32_e32 v51, v51, v53
	v_add_f32_e32 v51, v51, v52
	v_exp_f32_e32 v51, v51
	v_cvt_i32_f32_e32 v52, v53
	v_cndmask_b32_e32 v50, 0, v50, vcc
	v_cmp_ngt_f32_e32 vcc, s35, v76
	v_ldexp_f32 v51, v51, v52
	s_nop 0
	v_cndmask_b32_e32 v50, v179, v50, vcc
	v_cmp_nlt_f32_e32 vcc, s34, v77
	v_pk_fma_f32 v[52:53], v[56:57], v[124:125], v[80:81] op_sel_hi:[1,0,1]
	s_nop 0
	v_cndmask_b32_e32 v51, 0, v51, vcc
	v_cmp_ngt_f32_e32 vcc, s35, v77
	s_nop 1
	v_cndmask_b32_e32 v51, v179, v51, vcc
	v_pk_add_f32 v[50:51], v[50:51], 1.0 op_sel_hi:[1,0]
	s_nop 0
	v_div_scale_f32 v54, s[2:3], v51, v51, v77
	v_rcp_f32_e32 v55, v54
	s_nop 0
	v_fma_f32 v56, -v54, v55, 1.0
	v_fmac_f32_e32 v55, v56, v55
	v_div_scale_f32 v56, vcc, v77, v51, v77
	v_mul_f32_e32 v57, v56, v55
	v_fma_f32 v64, -v54, v57, v56
	v_fmac_f32_e32 v57, v64, v55
	v_fma_f32 v54, -v54, v57, v56
	v_div_fmas_f32 v54, v54, v55, v57
	v_div_fixup_f32 v51, v54, v51, v77
	v_div_scale_f32 v54, s[2:3], v50, v50, v76
	v_rcp_f32_e32 v55, v54
	s_nop 0
	v_fma_f32 v56, -v54, v55, 1.0
	v_fmac_f32_e32 v55, v56, v55
	v_div_scale_f32 v56, vcc, v76, v50, v76
	v_mul_f32_e32 v57, v56, v55
	v_fma_f32 v64, -v54, v57, v56
	v_fmac_f32_e32 v57, v64, v55
	v_fma_f32 v54, -v54, v57, v56
	v_div_fmas_f32 v54, v54, v55, v57
	v_div_fixup_f32 v50, v54, v50, v76
	v_pk_mul_f32 v[80:81], v[52:53], v[50:51]
	v_cmp_nlt_f32_e32 vcc, s34, v78
	v_pk_fma_f32 v[48:49], v[80:81], v[80:81], v[48:49]
	v_mul_f32_e32 v50, v81, v81
	v_pk_add_f32 v[48:49], v[50:51], v[48:49] op_sel_hi:[0,1]
	v_mul_f32_e32 v50, 0xbfb8aa3b, v78
	v_fma_f32 v51, v78, s43, -v50
	v_rndne_f32_e32 v52, v50
	v_fmac_f32_e32 v51, 0xb2a5705f, v78
	v_sub_f32_e32 v50, v50, v52
	v_add_f32_e32 v50, v50, v51
	v_exp_f32_e32 v50, v50
	v_cvt_i32_f32_e32 v51, v52
	v_ldexp_f32 v50, v50, v51
	v_mul_f32_e32 v51, 0xbfb8aa3b, v79
	v_fma_f32 v52, v79, s43, -v51
	v_rndne_f32_e32 v53, v51
	v_fmac_f32_e32 v52, 0xb2a5705f, v79
	v_sub_f32_e32 v51, v51, v53
	v_add_f32_e32 v51, v51, v52
	v_exp_f32_e32 v51, v51
	v_cvt_i32_f32_e32 v52, v53
	v_cndmask_b32_e32 v50, 0, v50, vcc
	v_cmp_ngt_f32_e32 vcc, s35, v78
	v_ldexp_f32 v51, v51, v52
	s_nop 0
	v_cndmask_b32_e32 v50, v179, v50, vcc
	v_cmp_nlt_f32_e32 vcc, s34, v79
	v_pk_fma_f32 v[52:53], v[58:59], v[124:125], v[82:83] op_sel_hi:[1,0,1]
	s_nop 0
	v_cndmask_b32_e32 v51, 0, v51, vcc
	v_cmp_ngt_f32_e32 vcc, s35, v79
	s_nop 1
	v_cndmask_b32_e32 v51, v179, v51, vcc
	v_pk_add_f32 v[50:51], v[50:51], 1.0 op_sel_hi:[1,0]
	s_nop 0
	v_div_scale_f32 v54, s[2:3], v51, v51, v79
	v_rcp_f32_e32 v55, v54
	s_nop 0
	v_fma_f32 v56, -v54, v55, 1.0
	v_fmac_f32_e32 v55, v56, v55
	v_div_scale_f32 v56, vcc, v79, v51, v79
	v_mul_f32_e32 v57, v56, v55
	v_fma_f32 v58, -v54, v57, v56
	v_fmac_f32_e32 v57, v58, v55
	v_fma_f32 v54, -v54, v57, v56
	v_div_fmas_f32 v54, v54, v55, v57
	v_div_fixup_f32 v51, v54, v51, v79
	v_div_scale_f32 v54, s[2:3], v50, v50, v78
	v_rcp_f32_e32 v55, v54
	s_nop 0
	v_fma_f32 v56, -v54, v55, 1.0
	v_fmac_f32_e32 v55, v56, v55
	v_div_scale_f32 v56, vcc, v78, v50, v78
	v_mul_f32_e32 v57, v56, v55
	v_fma_f32 v58, -v54, v57, v56
	v_fmac_f32_e32 v57, v58, v55
	v_fma_f32 v54, -v54, v57, v56
	v_div_fmas_f32 v54, v54, v55, v57
	v_div_fixup_f32 v50, v54, v50, v78
	v_pk_mul_f32 v[82:83], v[52:53], v[50:51]
	s_waitcnt vmcnt(0)
	v_cmp_nlt_f32_e32 vcc, s34, v68
	v_pk_fma_f32 v[48:49], v[82:83], v[82:83], v[48:49]
	v_mul_f32_e32 v50, v83, v83
	v_pk_add_f32 v[48:49], v[50:51], v[48:49] op_sel_hi:[0,1]
	v_mul_f32_e32 v50, 0xbfb8aa3b, v68
	v_fma_f32 v51, v68, s43, -v50
	v_rndne_f32_e32 v52, v50
	v_fmac_f32_e32 v51, 0xb2a5705f, v68
	v_sub_f32_e32 v50, v50, v52
	v_add_f32_e32 v50, v50, v51
	v_exp_f32_e32 v50, v50
	v_cvt_i32_f32_e32 v51, v52
	v_ldexp_f32 v50, v50, v51
	v_mul_f32_e32 v51, 0xbfb8aa3b, v69
	v_fma_f32 v52, v69, s43, -v51
	v_rndne_f32_e32 v53, v51
	v_fmac_f32_e32 v52, 0xb2a5705f, v69
	v_sub_f32_e32 v51, v51, v53
	v_add_f32_e32 v51, v51, v52
	v_exp_f32_e32 v51, v51
	v_cvt_i32_f32_e32 v52, v53
	v_cndmask_b32_e32 v50, 0, v50, vcc
	v_cmp_ngt_f32_e32 vcc, s35, v68
	v_ldexp_f32 v51, v51, v52
	s_nop 0
	v_cndmask_b32_e32 v50, v179, v50, vcc
	v_cmp_nlt_f32_e32 vcc, s34, v69
	v_pk_fma_f32 v[52:53], v[60:61], v[124:125], v[72:73] op_sel_hi:[1,0,1]
	s_nop 0
	v_cndmask_b32_e32 v51, 0, v51, vcc
	v_cmp_ngt_f32_e32 vcc, s35, v69
	s_nop 1
	v_cndmask_b32_e32 v51, v179, v51, vcc
	v_pk_add_f32 v[50:51], v[50:51], 1.0 op_sel_hi:[1,0]
	s_nop 0
	v_div_scale_f32 v54, s[2:3], v51, v51, v69
	v_rcp_f32_e32 v55, v54
	s_nop 0
	v_fma_f32 v56, -v54, v55, 1.0
	v_fmac_f32_e32 v55, v56, v55
	v_div_scale_f32 v56, vcc, v69, v51, v69
	v_mul_f32_e32 v57, v56, v55
	v_fma_f32 v58, -v54, v57, v56
	v_fmac_f32_e32 v57, v58, v55
	v_fma_f32 v54, -v54, v57, v56
	v_div_fmas_f32 v54, v54, v55, v57
	v_div_fixup_f32 v51, v54, v51, v69
	v_div_scale_f32 v54, s[2:3], v50, v50, v68
	v_rcp_f32_e32 v55, v54
	s_nop 0
	v_fma_f32 v56, -v54, v55, 1.0
	v_fmac_f32_e32 v55, v56, v55
	v_div_scale_f32 v56, vcc, v68, v50, v68
	v_mul_f32_e32 v57, v56, v55
	v_fma_f32 v58, -v54, v57, v56
	v_fmac_f32_e32 v57, v58, v55
	v_fma_f32 v54, -v54, v57, v56
	v_div_fmas_f32 v54, v54, v55, v57
	v_div_fixup_f32 v50, v54, v50, v68
	v_pk_mul_f32 v[120:121], v[52:53], v[50:51]
	v_cmp_nlt_f32_e32 vcc, s34, v70
	v_pk_fma_f32 v[48:49], v[120:121], v[120:121], v[48:49]
	v_mul_f32_e32 v50, v121, v121
	v_pk_add_f32 v[48:49], v[50:51], v[48:49] op_sel_hi:[0,1]
	v_mul_f32_e32 v50, 0xbfb8aa3b, v70
	v_fma_f32 v51, v70, s43, -v50
	v_rndne_f32_e32 v52, v50
	v_fmac_f32_e32 v51, 0xb2a5705f, v70
	v_sub_f32_e32 v50, v50, v52
	v_add_f32_e32 v50, v50, v51
	v_exp_f32_e32 v50, v50
	v_cvt_i32_f32_e32 v51, v52
	v_ldexp_f32 v50, v50, v51
	v_mul_f32_e32 v51, 0xbfb8aa3b, v71
	v_fma_f32 v52, v71, s43, -v51
	v_rndne_f32_e32 v53, v51
	v_fmac_f32_e32 v52, 0xb2a5705f, v71
	v_sub_f32_e32 v51, v51, v53
	v_add_f32_e32 v51, v51, v52
	v_exp_f32_e32 v51, v51
	v_cvt_i32_f32_e32 v52, v53
	v_cndmask_b32_e32 v50, 0, v50, vcc
	v_cmp_ngt_f32_e32 vcc, s35, v70
	v_ldexp_f32 v51, v51, v52
	s_nop 0
	v_cndmask_b32_e32 v50, v179, v50, vcc
	v_cmp_nlt_f32_e32 vcc, s34, v71
	v_pk_fma_f32 v[52:53], v[62:63], v[124:125], v[74:75] op_sel_hi:[1,0,1]
	s_nop 0
	v_cndmask_b32_e32 v51, 0, v51, vcc
	v_cmp_ngt_f32_e32 vcc, s35, v71
	s_nop 1
	v_cndmask_b32_e32 v51, v179, v51, vcc
	v_pk_add_f32 v[50:51], v[50:51], 1.0 op_sel_hi:[1,0]
	s_nop 0
	v_div_scale_f32 v54, s[2:3], v51, v51, v71
	v_rcp_f32_e32 v55, v54
	s_nop 0
	v_fma_f32 v56, -v54, v55, 1.0
	v_fmac_f32_e32 v55, v56, v55
	v_div_scale_f32 v56, vcc, v71, v51, v71
	v_mul_f32_e32 v57, v56, v55
	v_fma_f32 v58, -v54, v57, v56
	v_fmac_f32_e32 v57, v58, v55
	v_fma_f32 v54, -v54, v57, v56
	v_div_fmas_f32 v54, v54, v55, v57
	v_div_fixup_f32 v51, v54, v51, v71
	v_div_scale_f32 v54, s[2:3], v50, v50, v70
	v_rcp_f32_e32 v55, v54
	s_nop 0
	v_fma_f32 v56, -v54, v55, 1.0
	v_fmac_f32_e32 v55, v56, v55
	v_div_scale_f32 v56, vcc, v70, v50, v70
	v_mul_f32_e32 v57, v56, v55
	v_fma_f32 v58, -v54, v57, v56
	v_fmac_f32_e32 v57, v58, v55
	v_fma_f32 v54, -v54, v57, v56
	v_div_fmas_f32 v54, v54, v55, v57
	v_div_fixup_f32 v50, v54, v50, v70
	v_pk_mul_f32 v[122:123], v[52:53], v[50:51]
	s_nop 0
	v_pk_fma_f32 v[48:49], v[122:123], v[122:123], v[48:49]
	v_mul_f32_e32 v50, v123, v123
	v_pk_add_f32 v[126:127], v[50:51], v[48:49] op_sel_hi:[0,1]
	global_load_dwordx4 v[68:71], v[128:129], off offset:128
	global_load_dwordx4 v[64:67], v[130:131], off offset:128
	global_load_dwordx4 v[60:63], v[128:129], off offset:160
	global_load_dwordx4 v[56:59], v[130:131], off offset:160
	global_load_dwordx4 v[52:55], v[128:129], off offset:192
	global_load_dwordx4 v[48:51], v[130:131], off offset:192
	global_load_dwordx4 v[76:79], v[128:129], off offset:224
	global_load_dwordx4 v[72:75], v[130:131], off offset:224
	s_waitcnt vmcnt(7)
	v_pk_fma_f32 v[32:33], v[32:33], v[124:125], v[68:69] op_sel_hi:[1,0,1]
	s_waitcnt vmcnt(6)
	v_mul_f32_e32 v103, 0xbfb8aa3b, v64
	v_fma_f32 v105, v64, s43, -v103
	v_rndne_f32_e32 v107, v103
	v_fmac_f32_e32 v105, 0xb2a5705f, v64
	v_sub_f32_e32 v103, v103, v107
	v_add_f32_e32 v103, v103, v105
	v_exp_f32_e32 v103, v103
	v_cvt_i32_f32_e32 v105, v107
	v_cmp_nlt_f32_e32 vcc, s34, v64
	v_ldexp_f32 v103, v103, v105
	s_nop 0
	v_cndmask_b32_e32 v103, 0, v103, vcc
	v_cmp_ngt_f32_e32 vcc, s35, v64
	s_nop 1
	v_cndmask_b32_e32 v128, v179, v103, vcc
	v_mul_f32_e32 v103, 0xbfb8aa3b, v65
	v_fma_f32 v105, v65, s43, -v103
	v_rndne_f32_e32 v107, v103
	v_fmac_f32_e32 v105, 0xb2a5705f, v65
	v_sub_f32_e32 v103, v103, v107
	v_add_f32_e32 v103, v103, v105
	v_exp_f32_e32 v103, v103
	v_cvt_i32_f32_e32 v105, v107
	v_cmp_nlt_f32_e32 vcc, s34, v65
	v_ldexp_f32 v103, v103, v105
	s_nop 0
	v_cndmask_b32_e32 v103, 0, v103, vcc
	v_cmp_ngt_f32_e32 vcc, s35, v65
	s_nop 1
	v_cndmask_b32_e32 v129, v179, v103, vcc
	v_pk_add_f32 v[68:69], v[128:129], 1.0 op_sel_hi:[1,0]
	s_nop 0
	v_div_scale_f32 v103, s[2:3], v69, v69, v65
	v_rcp_f32_e32 v105, v103
	s_nop 0
	v_fma_f32 v107, -v103, v105, 1.0
	v_fmac_f32_e32 v105, v107, v105
	v_div_scale_f32 v107, vcc, v65, v69, v65
	v_mul_f32_e32 v109, v107, v105
	v_fma_f32 v125, -v103, v109, v107
	v_fmac_f32_e32 v109, v125, v105
	v_fma_f32 v103, -v103, v109, v107
	v_div_fmas_f32 v103, v103, v105, v109
	v_div_fixup_f32 v65, v103, v69, v65
	v_div_scale_f32 v69, s[2:3], v68, v68, v64
	v_rcp_f32_e32 v103, v69
	v_pk_fma_f32 v[34:35], v[34:35], v[124:125], v[70:71] op_sel_hi:[1,0,1]
	s_waitcnt vmcnt(5)
	v_pk_fma_f32 v[36:37], v[36:37], v[124:125], v[60:61] op_sel_hi:[1,0,1]
	v_fma_f32 v105, -v69, v103, 1.0
	v_fmac_f32_e32 v103, v105, v103
	v_div_scale_f32 v105, vcc, v64, v68, v64
	v_mul_f32_e32 v107, v105, v103
	v_fma_f32 v109, -v69, v107, v105
	v_fmac_f32_e32 v107, v109, v103
	v_fma_f32 v69, -v69, v107, v105
	v_div_fmas_f32 v69, v69, v103, v107
	v_div_fixup_f32 v64, v69, v68, v64
	v_pk_mul_f32 v[64:65], v[32:33], v[64:65]
	v_cmp_nlt_f32_e32 vcc, s34, v66
	v_pk_fma_f32 v[32:33], v[64:65], v[64:65], v[126:127]
	v_mul_f32_e32 v68, v65, v65
	v_pk_add_f32 v[32:33], v[68:69], v[32:33] op_sel_hi:[0,1]
	v_mul_f32_e32 v68, 0xbfb8aa3b, v66
	v_fma_f32 v69, v66, s43, -v68
	v_rndne_f32_e32 v103, v68
	v_fmac_f32_e32 v69, 0xb2a5705f, v66
	v_sub_f32_e32 v68, v68, v103
	v_add_f32_e32 v68, v68, v69
	v_exp_f32_e32 v68, v68
	v_cvt_i32_f32_e32 v69, v103
	v_ldexp_f32 v68, v68, v69
	v_mul_f32_e32 v69, 0xbfb8aa3b, v67
	v_fma_f32 v103, v67, s43, -v69
	v_rndne_f32_e32 v105, v69
	v_fmac_f32_e32 v103, 0xb2a5705f, v67
	v_sub_f32_e32 v69, v69, v105
	v_add_f32_e32 v69, v69, v103
	v_exp_f32_e32 v69, v69
	v_cvt_i32_f32_e32 v103, v105
	v_cndmask_b32_e32 v68, 0, v68, vcc
	v_cmp_ngt_f32_e32 vcc, s35, v66
	v_ldexp_f32 v69, v69, v103
	s_nop 0
	v_cndmask_b32_e32 v68, v179, v68, vcc
	v_cmp_nlt_f32_e32 vcc, s34, v67
	s_nop 1
	v_cndmask_b32_e32 v69, 0, v69, vcc
	v_cmp_ngt_f32_e32 vcc, s35, v67
	s_nop 1
	v_cndmask_b32_e32 v69, v179, v69, vcc
	v_pk_add_f32 v[68:69], v[68:69], 1.0 op_sel_hi:[1,0]
	s_nop 0
	v_div_scale_f32 v70, s[2:3], v69, v69, v67
	v_rcp_f32_e32 v71, v70
	s_nop 0
	v_fma_f32 v103, -v70, v71, 1.0
	v_fmac_f32_e32 v71, v103, v71
	v_div_scale_f32 v103, vcc, v67, v69, v67
	v_mul_f32_e32 v105, v103, v71
	v_fma_f32 v107, -v70, v105, v103
	v_fmac_f32_e32 v105, v107, v71
	v_fma_f32 v70, -v70, v105, v103
	v_div_fmas_f32 v70, v70, v71, v105
	v_div_fixup_f32 v67, v70, v69, v67
	v_div_scale_f32 v69, s[2:3], v68, v68, v66
	v_rcp_f32_e32 v70, v69
	s_nop 0
	v_fma_f32 v71, -v69, v70, 1.0
	v_fmac_f32_e32 v70, v71, v70
	v_div_scale_f32 v71, vcc, v66, v68, v66
	v_mul_f32_e32 v103, v71, v70
	v_fma_f32 v105, -v69, v103, v71
	v_fmac_f32_e32 v103, v105, v70
	v_fma_f32 v69, -v69, v103, v71
	v_div_fmas_f32 v69, v69, v70, v103
	v_div_fixup_f32 v66, v69, v68, v66
	v_pk_mul_f32 v[66:67], v[34:35], v[66:67]
	s_waitcnt vmcnt(4)
	v_cmp_nlt_f32_e32 vcc, s34, v56
	v_pk_fma_f32 v[32:33], v[66:67], v[66:67], v[32:33]
	v_mul_f32_e32 v34, v67, v67
	v_pk_add_f32 v[32:33], v[34:35], v[32:33] op_sel_hi:[0,1]
	v_mul_f32_e32 v34, 0xbfb8aa3b, v56
	v_fma_f32 v35, v56, s43, -v34
	v_rndne_f32_e32 v68, v34
	v_fmac_f32_e32 v35, 0xb2a5705f, v56
	v_sub_f32_e32 v34, v34, v68
	v_add_f32_e32 v34, v34, v35
	v_exp_f32_e32 v34, v34
	v_cvt_i32_f32_e32 v35, v68
	v_ldexp_f32 v34, v34, v35
	v_mul_f32_e32 v35, 0xbfb8aa3b, v57
	v_fma_f32 v68, v57, s43, -v35
	v_rndne_f32_e32 v69, v35
	v_fmac_f32_e32 v68, 0xb2a5705f, v57
	v_sub_f32_e32 v35, v35, v69
	v_add_f32_e32 v35, v35, v68
	v_exp_f32_e32 v35, v35
	v_cvt_i32_f32_e32 v68, v69
	v_cndmask_b32_e32 v34, 0, v34, vcc
	v_cmp_ngt_f32_e32 vcc, s35, v56
	v_ldexp_f32 v35, v35, v68
	s_nop 0
	v_cndmask_b32_e32 v34, v179, v34, vcc
	v_cmp_nlt_f32_e32 vcc, s34, v57
	s_nop 1
	v_cndmask_b32_e32 v35, 0, v35, vcc
	v_cmp_ngt_f32_e32 vcc, s35, v57
	s_nop 1
	v_cndmask_b32_e32 v35, v179, v35, vcc
	v_pk_add_f32 v[34:35], v[34:35], 1.0 op_sel_hi:[1,0]
	s_nop 0
	v_div_scale_f32 v60, s[2:3], v35, v35, v57
	v_rcp_f32_e32 v61, v60
	s_nop 0
	v_fma_f32 v68, -v60, v61, 1.0
	v_fmac_f32_e32 v61, v68, v61
	v_div_scale_f32 v68, vcc, v57, v35, v57
	v_mul_f32_e32 v69, v68, v61
	v_fma_f32 v70, -v60, v69, v68
	v_fmac_f32_e32 v69, v70, v61
	v_fma_f32 v60, -v60, v69, v68
	v_div_fmas_f32 v60, v60, v61, v69
	v_div_fixup_f32 v35, v60, v35, v57
	v_div_scale_f32 v57, s[2:3], v34, v34, v56
	v_rcp_f32_e32 v60, v57
	s_nop 0
	v_fma_f32 v61, -v57, v60, 1.0
	v_fmac_f32_e32 v60, v61, v60
	v_div_scale_f32 v61, vcc, v56, v34, v56
	v_mul_f32_e32 v68, v61, v60
	v_fma_f32 v69, -v57, v68, v61
	v_fmac_f32_e32 v68, v69, v60
	v_fma_f32 v57, -v57, v68, v61
	v_div_fmas_f32 v57, v57, v60, v68
	v_div_fixup_f32 v34, v57, v34, v56
	v_pk_mul_f32 v[56:57], v[36:37], v[34:35]
	v_cmp_nlt_f32_e32 vcc, s34, v58
	v_pk_fma_f32 v[32:33], v[56:57], v[56:57], v[32:33]
	v_mul_f32_e32 v34, v57, v57
	v_pk_add_f32 v[32:33], v[34:35], v[32:33] op_sel_hi:[0,1]
	v_mul_f32_e32 v34, 0xbfb8aa3b, v58
	v_fma_f32 v35, v58, s43, -v34
	v_rndne_f32_e32 v36, v34
	v_fmac_f32_e32 v35, 0xb2a5705f, v58
	v_sub_f32_e32 v34, v34, v36
	v_add_f32_e32 v34, v34, v35
	v_exp_f32_e32 v34, v34
	v_cvt_i32_f32_e32 v35, v36
	v_ldexp_f32 v34, v34, v35
	v_mul_f32_e32 v35, 0xbfb8aa3b, v59
	v_fma_f32 v36, v59, s43, -v35
	v_rndne_f32_e32 v37, v35
	v_fmac_f32_e32 v36, 0xb2a5705f, v59
	v_sub_f32_e32 v35, v35, v37
	v_add_f32_e32 v35, v35, v36
	v_exp_f32_e32 v35, v35
	v_cvt_i32_f32_e32 v36, v37
	v_cndmask_b32_e32 v34, 0, v34, vcc
	v_cmp_ngt_f32_e32 vcc, s35, v58
	v_ldexp_f32 v35, v35, v36
	s_nop 0
	v_cndmask_b32_e32 v34, v179, v34, vcc
	v_cmp_nlt_f32_e32 vcc, s34, v59
	v_pk_fma_f32 v[36:37], v[38:39], v[124:125], v[62:63] op_sel_hi:[1,0,1]
	s_nop 0
	v_cndmask_b32_e32 v35, 0, v35, vcc
	v_cmp_ngt_f32_e32 vcc, s35, v59
	s_nop 1
	v_cndmask_b32_e32 v35, v179, v35, vcc
	v_pk_add_f32 v[34:35], v[34:35], 1.0 op_sel_hi:[1,0]
	s_nop 0
	v_div_scale_f32 v38, s[2:3], v35, v35, v59
	v_rcp_f32_e32 v39, v38
	s_nop 0
	v_fma_f32 v60, -v38, v39, 1.0
	v_fmac_f32_e32 v39, v60, v39
	v_div_scale_f32 v60, vcc, v59, v35, v59
	v_mul_f32_e32 v61, v60, v39
	v_fma_f32 v62, -v38, v61, v60
	v_fmac_f32_e32 v61, v62, v39
	v_fma_f32 v38, -v38, v61, v60
	v_div_fmas_f32 v38, v38, v39, v61
	v_div_fixup_f32 v35, v38, v35, v59
	v_div_scale_f32 v38, s[2:3], v34, v34, v58
	v_rcp_f32_e32 v39, v38
	s_nop 0
	v_fma_f32 v59, -v38, v39, 1.0
	v_fmac_f32_e32 v39, v59, v39
	v_div_scale_f32 v59, vcc, v58, v34, v58
	v_mul_f32_e32 v60, v59, v39
	v_fma_f32 v61, -v38, v60, v59
	v_fmac_f32_e32 v60, v61, v39
	v_fma_f32 v38, -v38, v60, v59
	v_div_fmas_f32 v38, v38, v39, v60
	v_div_fixup_f32 v34, v38, v34, v58
	v_pk_mul_f32 v[58:59], v[36:37], v[34:35]
	s_waitcnt vmcnt(2)
	v_cmp_nlt_f32_e32 vcc, s34, v48
	v_pk_fma_f32 v[32:33], v[58:59], v[58:59], v[32:33]
	v_mul_f32_e32 v34, v59, v59
	v_pk_add_f32 v[32:33], v[34:35], v[32:33] op_sel_hi:[0,1]
	v_mul_f32_e32 v34, 0xbfb8aa3b, v48
	v_fma_f32 v35, v48, s43, -v34
	v_rndne_f32_e32 v36, v34
	v_fmac_f32_e32 v35, 0xb2a5705f, v48
	v_sub_f32_e32 v34, v34, v36
	v_add_f32_e32 v34, v34, v35
	v_exp_f32_e32 v34, v34
	v_cvt_i32_f32_e32 v35, v36
	v_ldexp_f32 v34, v34, v35
	v_mul_f32_e32 v35, 0xbfb8aa3b, v49
	v_fma_f32 v36, v49, s43, -v35
	v_rndne_f32_e32 v37, v35
	v_fmac_f32_e32 v36, 0xb2a5705f, v49
	v_sub_f32_e32 v35, v35, v37
	v_add_f32_e32 v35, v35, v36
	v_exp_f32_e32 v35, v35
	v_cvt_i32_f32_e32 v36, v37
	v_cndmask_b32_e32 v34, 0, v34, vcc
	v_cmp_ngt_f32_e32 vcc, s35, v48
	v_ldexp_f32 v35, v35, v36
	s_nop 0
	v_cndmask_b32_e32 v34, v179, v34, vcc
	v_cmp_nlt_f32_e32 vcc, s34, v49
	v_pk_fma_f32 v[36:37], v[40:41], v[124:125], v[52:53] op_sel_hi:[1,0,1]
	s_nop 0
	v_cndmask_b32_e32 v35, 0, v35, vcc
	v_cmp_ngt_f32_e32 vcc, s35, v49
	s_nop 1
	v_cndmask_b32_e32 v35, v179, v35, vcc
	v_pk_add_f32 v[34:35], v[34:35], 1.0 op_sel_hi:[1,0]
	s_nop 0
	v_div_scale_f32 v38, s[2:3], v35, v35, v49
	v_rcp_f32_e32 v39, v38
	s_nop 0
	v_fma_f32 v40, -v38, v39, 1.0
	v_fmac_f32_e32 v39, v40, v39
	v_div_scale_f32 v40, vcc, v49, v35, v49
	v_mul_f32_e32 v41, v40, v39
	v_fma_f32 v52, -v38, v41, v40
	v_fmac_f32_e32 v41, v52, v39
	v_fma_f32 v38, -v38, v41, v40
	v_div_fmas_f32 v38, v38, v39, v41
	v_div_fixup_f32 v35, v38, v35, v49
	v_div_scale_f32 v38, s[2:3], v34, v34, v48
	v_rcp_f32_e32 v39, v38
	s_nop 0
	v_fma_f32 v40, -v38, v39, 1.0
	v_fmac_f32_e32 v39, v40, v39
	v_div_scale_f32 v40, vcc, v48, v34, v48
	v_mul_f32_e32 v41, v40, v39
	v_fma_f32 v49, -v38, v41, v40
	v_fmac_f32_e32 v41, v49, v39
	v_fma_f32 v38, -v38, v41, v40
	v_div_fmas_f32 v38, v38, v39, v41
	v_div_fixup_f32 v34, v38, v34, v48
	v_pk_mul_f32 v[48:49], v[36:37], v[34:35]
	v_cmp_nlt_f32_e32 vcc, s34, v50
	v_pk_fma_f32 v[32:33], v[48:49], v[48:49], v[32:33]
	v_mul_f32_e32 v34, v49, v49
	v_pk_add_f32 v[32:33], v[34:35], v[32:33] op_sel_hi:[0,1]
	v_mul_f32_e32 v34, 0xbfb8aa3b, v50
	v_fma_f32 v35, v50, s43, -v34
	v_rndne_f32_e32 v36, v34
	v_fmac_f32_e32 v35, 0xb2a5705f, v50
	v_sub_f32_e32 v34, v34, v36
	v_add_f32_e32 v34, v34, v35
	v_exp_f32_e32 v34, v34
	v_cvt_i32_f32_e32 v35, v36
	v_ldexp_f32 v34, v34, v35
	v_mul_f32_e32 v35, 0xbfb8aa3b, v51
	v_fma_f32 v36, v51, s43, -v35
	v_rndne_f32_e32 v37, v35
	v_fmac_f32_e32 v36, 0xb2a5705f, v51
	v_sub_f32_e32 v35, v35, v37
	v_add_f32_e32 v35, v35, v36
	v_exp_f32_e32 v35, v35
	v_cvt_i32_f32_e32 v36, v37
	v_cndmask_b32_e32 v34, 0, v34, vcc
	v_cmp_ngt_f32_e32 vcc, s35, v50
	v_ldexp_f32 v35, v35, v36
	s_nop 0
	v_cndmask_b32_e32 v34, v179, v34, vcc
	v_cmp_nlt_f32_e32 vcc, s34, v51
	v_pk_fma_f32 v[36:37], v[42:43], v[124:125], v[54:55] op_sel_hi:[1,0,1]
	s_nop 0
	v_cndmask_b32_e32 v35, 0, v35, vcc
	v_cmp_ngt_f32_e32 vcc, s35, v51
	s_nop 1
	v_cndmask_b32_e32 v35, v179, v35, vcc
	v_pk_add_f32 v[34:35], v[34:35], 1.0 op_sel_hi:[1,0]
	s_nop 0
	v_div_scale_f32 v38, s[2:3], v35, v35, v51
	v_rcp_f32_e32 v39, v38
	s_nop 0
	v_fma_f32 v40, -v38, v39, 1.0
	v_fmac_f32_e32 v39, v40, v39
	v_div_scale_f32 v40, vcc, v51, v35, v51
	v_mul_f32_e32 v41, v40, v39
	v_fma_f32 v42, -v38, v41, v40
	v_fmac_f32_e32 v41, v42, v39
	v_fma_f32 v38, -v38, v41, v40
	v_div_fmas_f32 v38, v38, v39, v41
	v_div_fixup_f32 v35, v38, v35, v51
	v_div_scale_f32 v38, s[2:3], v34, v34, v50
	v_rcp_f32_e32 v39, v38
	s_nop 0
	v_fma_f32 v40, -v38, v39, 1.0
	v_fmac_f32_e32 v39, v40, v39
	v_div_scale_f32 v40, vcc, v50, v34, v50
	v_mul_f32_e32 v41, v40, v39
	v_fma_f32 v42, -v38, v41, v40
	v_fmac_f32_e32 v41, v42, v39
	v_fma_f32 v38, -v38, v41, v40
	v_div_fmas_f32 v38, v38, v39, v41
	v_div_fixup_f32 v34, v38, v34, v50
	v_pk_mul_f32 v[52:53], v[36:37], v[34:35]
	s_waitcnt vmcnt(0)
	v_cmp_nlt_f32_e32 vcc, s34, v72
	v_pk_fma_f32 v[32:33], v[52:53], v[52:53], v[32:33]
	v_mul_f32_e32 v34, v53, v53
	v_pk_add_f32 v[32:33], v[34:35], v[32:33] op_sel_hi:[0,1]
	v_mul_f32_e32 v34, 0xbfb8aa3b, v72
	v_fma_f32 v35, v72, s43, -v34
	v_rndne_f32_e32 v36, v34
	v_fmac_f32_e32 v35, 0xb2a5705f, v72
	v_sub_f32_e32 v34, v34, v36
	v_add_f32_e32 v34, v34, v35
	v_exp_f32_e32 v34, v34
	v_cvt_i32_f32_e32 v35, v36
	v_ldexp_f32 v34, v34, v35
	v_mul_f32_e32 v35, 0xbfb8aa3b, v73
	v_fma_f32 v36, v73, s43, -v35
	v_rndne_f32_e32 v37, v35
	v_fmac_f32_e32 v36, 0xb2a5705f, v73
	v_sub_f32_e32 v35, v35, v37
	v_add_f32_e32 v35, v35, v36
	v_exp_f32_e32 v35, v35
	v_cvt_i32_f32_e32 v36, v37
	v_cndmask_b32_e32 v34, 0, v34, vcc
	v_cmp_ngt_f32_e32 vcc, s35, v72
	v_ldexp_f32 v35, v35, v36
	s_nop 0
	v_cndmask_b32_e32 v34, v179, v34, vcc
	v_cmp_nlt_f32_e32 vcc, s34, v73
	v_pk_fma_f32 v[36:37], v[44:45], v[124:125], v[76:77] op_sel_hi:[1,0,1]
	s_nop 0
	v_cndmask_b32_e32 v35, 0, v35, vcc
	v_cmp_ngt_f32_e32 vcc, s35, v73
	s_nop 1
	v_cndmask_b32_e32 v35, v179, v35, vcc
	v_pk_add_f32 v[34:35], v[34:35], 1.0 op_sel_hi:[1,0]
	s_nop 0
	v_div_scale_f32 v38, s[2:3], v35, v35, v73
	v_rcp_f32_e32 v39, v38
	s_nop 0
	v_fma_f32 v40, -v38, v39, 1.0
	v_fmac_f32_e32 v39, v40, v39
	v_div_scale_f32 v40, vcc, v73, v35, v73
	v_mul_f32_e32 v41, v40, v39
	v_fma_f32 v42, -v38, v41, v40
	v_fmac_f32_e32 v41, v42, v39
	v_fma_f32 v38, -v38, v41, v40
	v_div_fmas_f32 v38, v38, v39, v41
	v_div_fixup_f32 v35, v38, v35, v73
	v_div_scale_f32 v38, s[2:3], v34, v34, v72
	v_rcp_f32_e32 v39, v38
	s_nop 0
	v_fma_f32 v40, -v38, v39, 1.0
	v_fmac_f32_e32 v39, v40, v39
	v_div_scale_f32 v40, vcc, v72, v34, v72
	v_mul_f32_e32 v41, v40, v39
	v_fma_f32 v42, -v38, v41, v40
	v_fmac_f32_e32 v41, v42, v39
	v_fma_f32 v38, -v38, v41, v40
	v_div_fmas_f32 v38, v38, v39, v41
	v_div_fixup_f32 v34, v38, v34, v72
	v_pk_mul_f32 v[60:61], v[36:37], v[34:35]
	v_cmp_nlt_f32_e32 vcc, s34, v74
	v_pk_fma_f32 v[32:33], v[60:61], v[60:61], v[32:33]
	v_mul_f32_e32 v34, v61, v61
	v_pk_add_f32 v[32:33], v[34:35], v[32:33] op_sel_hi:[0,1]
	v_mul_f32_e32 v34, 0xbfb8aa3b, v74
	v_fma_f32 v35, v74, s43, -v34
	v_rndne_f32_e32 v36, v34
	v_fmac_f32_e32 v35, 0xb2a5705f, v74
	v_sub_f32_e32 v34, v34, v36
	v_add_f32_e32 v34, v34, v35
	v_exp_f32_e32 v34, v34
	v_cvt_i32_f32_e32 v35, v36
	v_ldexp_f32 v34, v34, v35
	v_mul_f32_e32 v35, 0xbfb8aa3b, v75
	v_fma_f32 v36, v75, s43, -v35
	v_rndne_f32_e32 v37, v35
	v_fmac_f32_e32 v36, 0xb2a5705f, v75
	v_sub_f32_e32 v35, v35, v37
	v_add_f32_e32 v35, v35, v36
	v_exp_f32_e32 v35, v35
	v_cvt_i32_f32_e32 v36, v37
	v_cndmask_b32_e32 v34, 0, v34, vcc
	v_cmp_ngt_f32_e32 vcc, s35, v74
	v_ldexp_f32 v35, v35, v36
	s_nop 0
	v_cndmask_b32_e32 v34, v179, v34, vcc
	v_cmp_nlt_f32_e32 vcc, s34, v75
	v_pk_fma_f32 v[36:37], v[46:47], v[124:125], v[78:79] op_sel_hi:[1,0,1]
	s_nop 0
	v_cndmask_b32_e32 v35, 0, v35, vcc
	v_cmp_ngt_f32_e32 vcc, s35, v75
	s_nop 1
	v_cndmask_b32_e32 v35, v179, v35, vcc
	v_pk_add_f32 v[34:35], v[34:35], 1.0 op_sel_hi:[1,0]
	s_nop 0
	v_div_scale_f32 v38, s[2:3], v35, v35, v75
	v_rcp_f32_e32 v39, v38
	s_nop 0
	v_fma_f32 v40, -v38, v39, 1.0
	v_fmac_f32_e32 v39, v40, v39
	v_div_scale_f32 v40, vcc, v75, v35, v75
	v_mul_f32_e32 v41, v40, v39
	v_fma_f32 v42, -v38, v41, v40
	v_fmac_f32_e32 v41, v42, v39
	v_fma_f32 v38, -v38, v41, v40
	v_div_fmas_f32 v38, v38, v39, v41
	v_div_fixup_f32 v35, v38, v35, v75
	v_div_scale_f32 v38, s[2:3], v34, v34, v74
	v_rcp_f32_e32 v39, v38
	s_nop 0
	v_fma_f32 v40, -v38, v39, 1.0
	v_fmac_f32_e32 v39, v40, v39
	v_div_scale_f32 v40, vcc, v74, v34, v74
	v_mul_f32_e32 v41, v40, v39
	v_fma_f32 v42, -v38, v41, v40
	v_fmac_f32_e32 v41, v42, v39
	v_fma_f32 v38, -v38, v41, v40
	v_div_fmas_f32 v38, v38, v39, v41
	v_div_fixup_f32 v34, v38, v34, v74
	v_pk_mul_f32 v[78:79], v[36:37], v[34:35]
	s_nop 0
	v_pk_fma_f32 v[32:33], v[78:79], v[78:79], v[32:33]
	v_mul_f32_e32 v34, v79, v79
	v_pk_add_f32 v[32:33], v[34:35], v[32:33] op_sel_hi:[0,1]
	v_mov_b32_e32 v33, v32
	s_nop 1
	v_permlane32_swap_b32_e32 v32, v33
	s_and_saveexec_b64 s[14:15], s[48:49]
	v_add_f32_e32 v32, v32, v33
	ds_write_b32 v97, v32
	s_or_b64 exec, exec, s[14:15]
	v_mov_b32_e32 v33, s5
	v_or_b32_e32 v32, s4, v92
	v_lshlrev_b64 v[34:35], 5, v[32:33]
	v_lshl_add_u64 v[34:35], s[8:9], 0, v[34:35]
	global_load_dword v34, v[34:35], off
	v_mad_u64_u32 v[132:133], s[2:3], v32, s42, v[98:99]
	v_lshlrev_b64 v[50:51], 11, v[32:33]
	s_mul_i32 s2, s5, 0x2800
	v_lshl_add_u64 v[130:131], v[94:95], 0, v[50:51]
	v_add_u32_e32 v133, s2, v133
	global_load_dwordx4 v[70:73], v[130:131], off
	s_waitcnt vmcnt(1)
	v_exp_f32_e32 v126, v34
	global_load_dwordx4 v[74:77], v[132:133], off
	global_load_dwordx4 v[134:137], v[130:131], off offset:32
	global_load_dwordx4 v[138:141], v[132:133], off offset:32
	global_load_dwordx4 v[44:47], v[130:131], off offset:64
	global_load_dwordx4 v[40:43], v[132:133], off offset:64
	global_load_dwordx4 v[36:39], v[130:131], off offset:96
	global_load_dwordx4 v[32:35], v[132:133], off offset:96
	s_waitcnt vmcnt(7)
	v_pk_fma_f32 v[16:17], v[16:17], v[126:127], v[70:71] op_sel_hi:[1,0,1]
	v_pk_fma_f32 v[18:19], v[18:19], v[126:127], v[72:73] op_sel_hi:[1,0,1]
	s_waitcnt vmcnt(6)
	v_mul_f32_e32 v54, 0xbfb8aa3b, v74
	v_fma_f32 v55, v74, s43, -v54
	v_rndne_f32_e32 v62, v54
	v_fmac_f32_e32 v55, 0xb2a5705f, v74
	v_sub_f32_e32 v54, v54, v62
	v_add_f32_e32 v54, v54, v55
	v_exp_f32_e32 v54, v54
	v_cvt_i32_f32_e32 v55, v62
	v_cmp_nlt_f32_e32 vcc, s34, v74
	s_waitcnt vmcnt(5)
	v_pk_fma_f32 v[20:21], v[20:21], v[126:127], v[134:135] op_sel_hi:[1,0,1]
	v_ldexp_f32 v54, v54, v55
	v_mul_f32_e32 v55, 0xbfb8aa3b, v75
	v_fma_f32 v62, v75, s43, -v55
	v_rndne_f32_e32 v63, v55
	v_fmac_f32_e32 v62, 0xb2a5705f, v75
	v_sub_f32_e32 v55, v55, v63
	v_add_f32_e32 v55, v55, v62
	v_exp_f32_e32 v55, v55
	v_cvt_i32_f32_e32 v62, v63
	v_cndmask_b32_e32 v54, 0, v54, vcc
	v_cmp_ngt_f32_e32 vcc, s35, v74
	v_ldexp_f32 v55, v55, v62
	s_nop 0
	v_cndmask_b32_e32 v54, v179, v54, vcc
	v_cmp_nlt_f32_e32 vcc, s34, v75
	s_nop 1
	v_cndmask_b32_e32 v55, 0, v55, vcc
	v_cmp_ngt_f32_e32 vcc, s35, v75
	s_nop 1
	v_cndmask_b32_e32 v55, v179, v55, vcc
	v_pk_add_f32 v[54:55], v[54:55], 1.0 op_sel_hi:[1,0]
	s_nop 0
	v_div_scale_f32 v62, s[2:3], v55, v55, v75
	v_rcp_f32_e32 v63, v62
	s_nop 0
	v_fma_f32 v68, -v62, v63, 1.0
	v_fmac_f32_e32 v63, v68, v63
	v_div_scale_f32 v68, vcc, v75, v55, v75
	v_mul_f32_e32 v69, v68, v63
	v_fma_f32 v70, -v62, v69, v68
	v_fmac_f32_e32 v69, v70, v63
	v_fma_f32 v62, -v62, v69, v68
	v_div_fmas_f32 v62, v62, v63, v69
	v_div_fixup_f32 v55, v62, v55, v75
	v_div_scale_f32 v62, s[2:3], v54, v54, v74
	v_rcp_f32_e32 v63, v62
	s_nop 0
	v_fma_f32 v68, -v62, v63, 1.0
	v_fmac_f32_e32 v63, v68, v63
	v_div_scale_f32 v68, vcc, v74, v54, v74
	v_mul_f32_e32 v69, v68, v63
	v_fma_f32 v70, -v62, v69, v68
	v_fmac_f32_e32 v69, v70, v63
	v_fma_f32 v62, -v62, v69, v68
	v_div_fmas_f32 v62, v62, v63, v69
	v_div_fixup_f32 v54, v62, v54, v74
	v_pk_mul_f32 v[70:71], v[16:17], v[54:55]
	v_mul_f32_e32 v54, 0xbfb8aa3b, v76
	v_fma_f32 v55, v76, s43, -v54
	v_rndne_f32_e32 v62, v54
	v_fmac_f32_e32 v55, 0xb2a5705f, v76
	v_sub_f32_e32 v54, v54, v62
	v_add_f32_e32 v54, v54, v55
	v_exp_f32_e32 v54, v54
	v_cvt_i32_f32_e32 v55, v62
	v_cmp_nlt_f32_e32 vcc, s34, v76
	v_mul_f32_e32 v16, v71, v71
	v_pk_fma_f32 v[16:17], v[70:71], v[70:71], v[16:17] op_sel_hi:[1,1,0]
	v_ldexp_f32 v54, v54, v55
	v_mul_f32_e32 v55, 0xbfb8aa3b, v77
	v_fma_f32 v62, v77, s43, -v55
	v_rndne_f32_e32 v63, v55
	v_fmac_f32_e32 v62, 0xb2a5705f, v77
	v_sub_f32_e32 v55, v55, v63
	v_add_f32_e32 v55, v55, v62
	v_exp_f32_e32 v55, v55
	v_cvt_i32_f32_e32 v62, v63
	v_cndmask_b32_e32 v54, 0, v54, vcc
	v_cmp_ngt_f32_e32 vcc, s35, v76
	v_ldexp_f32 v55, v55, v62
	s_nop 0
	v_cndmask_b32_e32 v54, v179, v54, vcc
	v_cmp_nlt_f32_e32 vcc, s34, v77
	s_nop 1
	v_cndmask_b32_e32 v55, 0, v55, vcc
	v_cmp_ngt_f32_e32 vcc, s35, v77
	s_nop 1
	v_cndmask_b32_e32 v55, v179, v55, vcc
	v_pk_add_f32 v[54:55], v[54:55], 1.0 op_sel_hi:[1,0]
	s_nop 0
	v_div_scale_f32 v62, s[2:3], v55, v55, v77
	v_rcp_f32_e32 v63, v62
	s_nop 0
	v_fma_f32 v68, -v62, v63, 1.0
	v_fmac_f32_e32 v63, v68, v63
	v_div_scale_f32 v68, vcc, v77, v55, v77
	v_mul_f32_e32 v69, v68, v63
	v_fma_f32 v72, -v62, v69, v68
	v_fmac_f32_e32 v69, v72, v63
	v_fma_f32 v62, -v62, v69, v68
	v_div_fmas_f32 v62, v62, v63, v69
	v_div_fixup_f32 v55, v62, v55, v77
	v_div_scale_f32 v62, s[2:3], v54, v54, v76
	v_rcp_f32_e32 v63, v62
	s_nop 0
	v_fma_f32 v68, -v62, v63, 1.0
	v_fmac_f32_e32 v63, v68, v63
	v_div_scale_f32 v68, vcc, v76, v54, v76
	v_mul_f32_e32 v69, v68, v63
	v_fma_f32 v72, -v62, v69, v68
	v_fmac_f32_e32 v69, v72, v63
	v_fma_f32 v62, -v62, v69, v68
	v_div_fmas_f32 v62, v62, v63, v69
	v_div_fixup_f32 v54, v62, v54, v76
	v_pk_mul_f32 v[74:75], v[18:19], v[54:55]
	s_waitcnt vmcnt(4)
	v_cmp_nlt_f32_e32 vcc, s34, v138
	v_pk_fma_f32 v[16:17], v[74:75], v[74:75], v[16:17]
	v_mul_f32_e32 v18, v75, v75
	v_pk_add_f32 v[16:17], v[18:19], v[16:17] op_sel_hi:[0,1]
	v_mul_f32_e32 v18, 0xbfb8aa3b, v138
	v_fma_f32 v19, v138, s43, -v18
	v_rndne_f32_e32 v54, v18
	v_fmac_f32_e32 v19, 0xb2a5705f, v138
	v_sub_f32_e32 v18, v18, v54
	v_add_f32_e32 v18, v18, v19
	v_exp_f32_e32 v18, v18
	v_cvt_i32_f32_e32 v19, v54
	v_ldexp_f32 v18, v18, v19
	v_mul_f32_e32 v19, 0xbfb8aa3b, v139
	v_fma_f32 v54, v139, s43, -v19
	v_rndne_f32_e32 v55, v19
	v_fmac_f32_e32 v54, 0xb2a5705f, v139
	v_sub_f32_e32 v19, v19, v55
	v_add_f32_e32 v19, v19, v54
	v_exp_f32_e32 v19, v19
	v_cvt_i32_f32_e32 v54, v55
	v_cndmask_b32_e32 v18, 0, v18, vcc
	v_cmp_ngt_f32_e32 vcc, s35, v138
	v_ldexp_f32 v19, v19, v54
	s_nop 0
	v_cndmask_b32_e32 v18, v179, v18, vcc
	v_cmp_nlt_f32_e32 vcc, s34, v139
	s_nop 1
	v_cndmask_b32_e32 v19, 0, v19, vcc
	v_cmp_ngt_f32_e32 vcc, s35, v139
	s_nop 1
	v_cndmask_b32_e32 v19, v179, v19, vcc
	v_pk_add_f32 v[18:19], v[18:19], 1.0 op_sel_hi:[1,0]
	s_nop 0
	v_div_scale_f32 v54, s[2:3], v19, v19, v139
	v_rcp_f32_e32 v55, v54
	s_nop 0
	v_fma_f32 v62, -v54, v55, 1.0
	v_fmac_f32_e32 v55, v62, v55
	v_div_scale_f32 v62, vcc, v139, v19, v139
	v_mul_f32_e32 v63, v62, v55
	v_fma_f32 v68, -v54, v63, v62
	v_fmac_f32_e32 v63, v68, v55
	v_fma_f32 v54, -v54, v63, v62
	v_div_fmas_f32 v54, v54, v55, v63
	v_div_fixup_f32 v19, v54, v19, v139
	v_div_scale_f32 v54, s[2:3], v18, v18, v138
	v_rcp_f32_e32 v55, v54
	s_nop 0
	v_fma_f32 v62, -v54, v55, 1.0
	v_fmac_f32_e32 v55, v62, v55
	v_div_scale_f32 v62, vcc, v138, v18, v138
	v_mul_f32_e32 v63, v62, v55
	v_fma_f32 v68, -v54, v63, v62
	v_fmac_f32_e32 v63, v68, v55
	v_fma_f32 v54, -v54, v63, v62
	v_div_fmas_f32 v54, v54, v55, v63
	v_div_fixup_f32 v18, v54, v18, v138
	v_pk_mul_f32 v[54:55], v[20:21], v[18:19]
	v_cmp_nlt_f32_e32 vcc, s34, v140
	v_pk_fma_f32 v[16:17], v[54:55], v[54:55], v[16:17]
	v_mul_f32_e32 v18, v55, v55
	v_pk_add_f32 v[16:17], v[18:19], v[16:17] op_sel_hi:[0,1]
	v_mul_f32_e32 v18, 0xbfb8aa3b, v140
	v_fma_f32 v19, v140, s43, -v18
	v_rndne_f32_e32 v20, v18
	v_fmac_f32_e32 v19, 0xb2a5705f, v140
	v_sub_f32_e32 v18, v18, v20
	v_add_f32_e32 v18, v18, v19
	v_exp_f32_e32 v18, v18
	v_cvt_i32_f32_e32 v19, v20
	v_ldexp_f32 v18, v18, v19
	v_mul_f32_e32 v19, 0xbfb8aa3b, v141
	v_fma_f32 v20, v141, s43, -v19
	v_rndne_f32_e32 v21, v19
	v_fmac_f32_e32 v20, 0xb2a5705f, v141
	v_sub_f32_e32 v19, v19, v21
	v_add_f32_e32 v19, v19, v20
	v_exp_f32_e32 v19, v19
	v_cvt_i32_f32_e32 v20, v21
	v_cndmask_b32_e32 v18, 0, v18, vcc
	v_cmp_ngt_f32_e32 vcc, s35, v140
	v_ldexp_f32 v19, v19, v20
	s_nop 0
	v_cndmask_b32_e32 v18, v179, v18, vcc
	v_cmp_nlt_f32_e32 vcc, s34, v141
	v_pk_fma_f32 v[20:21], v[22:23], v[126:127], v[136:137] op_sel_hi:[1,0,1]
	s_nop 0
	v_cndmask_b32_e32 v19, 0, v19, vcc
	v_cmp_ngt_f32_e32 vcc, s35, v141
	s_nop 1
	v_cndmask_b32_e32 v19, v179, v19, vcc
	v_pk_add_f32 v[18:19], v[18:19], 1.0 op_sel_hi:[1,0]
	s_nop 0
	v_div_scale_f32 v22, s[2:3], v19, v19, v141
	v_rcp_f32_e32 v23, v22
	s_nop 0
	v_fma_f32 v62, -v22, v23, 1.0
	v_fmac_f32_e32 v23, v62, v23
	v_div_scale_f32 v62, vcc, v141, v19, v141
	v_mul_f32_e32 v63, v62, v23
	v_fma_f32 v68, -v22, v63, v62
	v_fmac_f32_e32 v63, v68, v23
	v_fma_f32 v22, -v22, v63, v62
	v_div_fmas_f32 v22, v22, v23, v63
	v_div_fixup_f32 v19, v22, v19, v141
	v_div_scale_f32 v22, s[2:3], v18, v18, v140
	v_rcp_f32_e32 v23, v22
	s_nop 0
	v_fma_f32 v62, -v22, v23, 1.0
	v_fmac_f32_e32 v23, v62, v23
	v_div_scale_f32 v62, vcc, v140, v18, v140
	v_mul_f32_e32 v63, v62, v23
	v_fma_f32 v68, -v22, v63, v62
	v_fmac_f32_e32 v63, v68, v23
	v_fma_f32 v22, -v22, v63, v62
	v_div_fmas_f32 v22, v22, v23, v63
	v_div_fixup_f32 v18, v22, v18, v140
	v_pk_mul_f32 v[62:63], v[20:21], v[18:19]
	s_waitcnt vmcnt(2)
	v_cmp_nlt_f32_e32 vcc, s34, v40
	v_pk_fma_f32 v[16:17], v[62:63], v[62:63], v[16:17]
	v_mul_f32_e32 v18, v63, v63
	v_pk_add_f32 v[16:17], v[18:19], v[16:17] op_sel_hi:[0,1]
	v_mul_f32_e32 v18, 0xbfb8aa3b, v40
	v_fma_f32 v19, v40, s43, -v18
	v_rndne_f32_e32 v20, v18
	v_fmac_f32_e32 v19, 0xb2a5705f, v40
	v_sub_f32_e32 v18, v18, v20
	v_add_f32_e32 v18, v18, v19
	v_exp_f32_e32 v18, v18
	v_cvt_i32_f32_e32 v19, v20
	v_ldexp_f32 v18, v18, v19
	v_mul_f32_e32 v19, 0xbfb8aa3b, v41
	v_fma_f32 v20, v41, s43, -v19
	v_rndne_f32_e32 v21, v19
	v_fmac_f32_e32 v20, 0xb2a5705f, v41
	v_sub_f32_e32 v19, v19, v21
	v_add_f32_e32 v19, v19, v20
	v_exp_f32_e32 v19, v19
	v_cvt_i32_f32_e32 v20, v21
	v_cndmask_b32_e32 v18, 0, v18, vcc
	v_cmp_ngt_f32_e32 vcc, s35, v40
	v_ldexp_f32 v19, v19, v20
	s_nop 0
	v_cndmask_b32_e32 v18, v179, v18, vcc
	v_cmp_nlt_f32_e32 vcc, s34, v41
	v_pk_fma_f32 v[20:21], v[24:25], v[126:127], v[44:45] op_sel_hi:[1,0,1]
	s_nop 0
	v_cndmask_b32_e32 v19, 0, v19, vcc
	v_cmp_ngt_f32_e32 vcc, s35, v41
	s_nop 1
	v_cndmask_b32_e32 v19, v179, v19, vcc
	v_pk_add_f32 v[18:19], v[18:19], 1.0 op_sel_hi:[1,0]
	s_nop 0
	v_div_scale_f32 v22, s[2:3], v19, v19, v41
	v_rcp_f32_e32 v23, v22
	s_nop 0
	v_fma_f32 v24, -v22, v23, 1.0
	v_fmac_f32_e32 v23, v24, v23
	v_div_scale_f32 v24, vcc, v41, v19, v41
	v_mul_f32_e32 v25, v24, v23
	v_fma_f32 v44, -v22, v25, v24
	v_fmac_f32_e32 v25, v44, v23
	v_fma_f32 v22, -v22, v25, v24
	v_div_fmas_f32 v22, v22, v23, v25
	v_div_fixup_f32 v19, v22, v19, v41
	v_div_scale_f32 v22, s[2:3], v18, v18, v40
	v_rcp_f32_e32 v23, v22
	s_nop 0
	v_fma_f32 v24, -v22, v23, 1.0
	v_fmac_f32_e32 v23, v24, v23
	v_div_scale_f32 v24, vcc, v40, v18, v40
	v_mul_f32_e32 v25, v24, v23
	v_fma_f32 v41, -v22, v25, v24
	v_fmac_f32_e32 v25, v41, v23
	v_fma_f32 v22, -v22, v25, v24
	v_div_fmas_f32 v22, v22, v23, v25
	v_div_fixup_f32 v18, v22, v18, v40
	v_pk_mul_f32 v[68:69], v[20:21], v[18:19]
	v_cmp_nlt_f32_e32 vcc, s34, v42
	v_pk_fma_f32 v[16:17], v[68:69], v[68:69], v[16:17]
	v_mul_f32_e32 v18, v69, v69
	v_pk_add_f32 v[16:17], v[18:19], v[16:17] op_sel_hi:[0,1]
	v_mul_f32_e32 v18, 0xbfb8aa3b, v42
	v_fma_f32 v19, v42, s43, -v18
	v_rndne_f32_e32 v20, v18
	v_fmac_f32_e32 v19, 0xb2a5705f, v42
	v_sub_f32_e32 v18, v18, v20
	v_add_f32_e32 v18, v18, v19
	v_exp_f32_e32 v18, v18
	v_cvt_i32_f32_e32 v19, v20
	v_ldexp_f32 v18, v18, v19
	v_mul_f32_e32 v19, 0xbfb8aa3b, v43
	v_fma_f32 v20, v43, s43, -v19
	v_rndne_f32_e32 v21, v19
	v_fmac_f32_e32 v20, 0xb2a5705f, v43
	v_sub_f32_e32 v19, v19, v21
	v_add_f32_e32 v19, v19, v20
	v_exp_f32_e32 v19, v19
	v_cvt_i32_f32_e32 v20, v21
	v_cndmask_b32_e32 v18, 0, v18, vcc
	v_cmp_ngt_f32_e32 vcc, s35, v42
	v_ldexp_f32 v19, v19, v20
	s_nop 0
	v_cndmask_b32_e32 v18, v179, v18, vcc
	v_cmp_nlt_f32_e32 vcc, s34, v43
	v_pk_fma_f32 v[20:21], v[26:27], v[126:127], v[46:47] op_sel_hi:[1,0,1]
	s_nop 0
	v_cndmask_b32_e32 v19, 0, v19, vcc
	v_cmp_ngt_f32_e32 vcc, s35, v43
	s_nop 1
	v_cndmask_b32_e32 v19, v179, v19, vcc
	v_pk_add_f32 v[18:19], v[18:19], 1.0 op_sel_hi:[1,0]
	s_nop 0
	v_div_scale_f32 v22, s[2:3], v19, v19, v43
	v_rcp_f32_e32 v23, v22
	s_nop 0
	v_fma_f32 v24, -v22, v23, 1.0
	v_fmac_f32_e32 v23, v24, v23
	v_div_scale_f32 v24, vcc, v43, v19, v43
	v_mul_f32_e32 v25, v24, v23
	v_fma_f32 v26, -v22, v25, v24
	v_fmac_f32_e32 v25, v26, v23
	v_fma_f32 v22, -v22, v25, v24
	v_div_fmas_f32 v22, v22, v23, v25
	v_div_fixup_f32 v19, v22, v19, v43
	v_div_scale_f32 v22, s[2:3], v18, v18, v42
	v_rcp_f32_e32 v23, v22
	s_nop 0
	v_fma_f32 v24, -v22, v23, 1.0
	v_fmac_f32_e32 v23, v24, v23
	v_div_scale_f32 v24, vcc, v42, v18, v42
	v_mul_f32_e32 v25, v24, v23
	v_fma_f32 v26, -v22, v25, v24
	v_fmac_f32_e32 v25, v26, v23
	v_fma_f32 v22, -v22, v25, v24
	v_div_fmas_f32 v22, v22, v23, v25
	v_div_fixup_f32 v18, v22, v18, v42
	v_pk_mul_f32 v[72:73], v[20:21], v[18:19]
	s_waitcnt vmcnt(0)
	v_cmp_nlt_f32_e32 vcc, s34, v32
	v_pk_fma_f32 v[16:17], v[72:73], v[72:73], v[16:17]
	v_mul_f32_e32 v18, v73, v73
	v_pk_add_f32 v[16:17], v[18:19], v[16:17] op_sel_hi:[0,1]
	v_mul_f32_e32 v18, 0xbfb8aa3b, v32
	v_fma_f32 v19, v32, s43, -v18
	v_rndne_f32_e32 v20, v18
	v_fmac_f32_e32 v19, 0xb2a5705f, v32
	v_sub_f32_e32 v18, v18, v20
	v_add_f32_e32 v18, v18, v19
	v_exp_f32_e32 v18, v18
	v_cvt_i32_f32_e32 v19, v20
	v_ldexp_f32 v18, v18, v19
	v_mul_f32_e32 v19, 0xbfb8aa3b, v33
	v_fma_f32 v20, v33, s43, -v19
	v_rndne_f32_e32 v21, v19
	v_fmac_f32_e32 v20, 0xb2a5705f, v33
	v_sub_f32_e32 v19, v19, v21
	v_add_f32_e32 v19, v19, v20
	v_exp_f32_e32 v19, v19
	v_cvt_i32_f32_e32 v20, v21
	v_cndmask_b32_e32 v18, 0, v18, vcc
	v_cmp_ngt_f32_e32 vcc, s35, v32
	v_ldexp_f32 v19, v19, v20
	s_nop 0
	v_cndmask_b32_e32 v18, v179, v18, vcc
	v_cmp_nlt_f32_e32 vcc, s34, v33
	v_pk_fma_f32 v[20:21], v[28:29], v[126:127], v[36:37] op_sel_hi:[1,0,1]
	s_nop 0
	v_cndmask_b32_e32 v19, 0, v19, vcc
	v_cmp_ngt_f32_e32 vcc, s35, v33
	s_nop 1
	v_cndmask_b32_e32 v19, v179, v19, vcc
	v_pk_add_f32 v[18:19], v[18:19], 1.0 op_sel_hi:[1,0]
	s_nop 0
	v_div_scale_f32 v22, s[2:3], v19, v19, v33
	v_rcp_f32_e32 v23, v22
	s_nop 0
	v_fma_f32 v24, -v22, v23, 1.0
	v_fmac_f32_e32 v23, v24, v23
	v_div_scale_f32 v24, vcc, v33, v19, v33
	v_mul_f32_e32 v25, v24, v23
	v_fma_f32 v26, -v22, v25, v24
	v_fmac_f32_e32 v25, v26, v23
	v_fma_f32 v22, -v22, v25, v24
	v_div_fmas_f32 v22, v22, v23, v25
	v_div_fixup_f32 v19, v22, v19, v33
	v_div_scale_f32 v22, s[2:3], v18, v18, v32
	v_rcp_f32_e32 v23, v22
	s_nop 0
	v_fma_f32 v24, -v22, v23, 1.0
	v_fmac_f32_e32 v23, v24, v23
	v_div_scale_f32 v24, vcc, v32, v18, v32
	v_mul_f32_e32 v25, v24, v23
	v_fma_f32 v26, -v22, v25, v24
	v_fmac_f32_e32 v25, v26, v23
	v_fma_f32 v22, -v22, v25, v24
	v_div_fmas_f32 v22, v22, v23, v25
	v_div_fixup_f32 v18, v22, v18, v32
	v_pk_mul_f32 v[76:77], v[20:21], v[18:19]
	v_cmp_nlt_f32_e32 vcc, s34, v34
	v_pk_fma_f32 v[16:17], v[76:77], v[76:77], v[16:17]
	v_mul_f32_e32 v18, v77, v77
	v_pk_add_f32 v[16:17], v[18:19], v[16:17] op_sel_hi:[0,1]
	v_mul_f32_e32 v18, 0xbfb8aa3b, v34
	v_fma_f32 v19, v34, s43, -v18
	v_rndne_f32_e32 v20, v18
	v_fmac_f32_e32 v19, 0xb2a5705f, v34
	v_sub_f32_e32 v18, v18, v20
	v_add_f32_e32 v18, v18, v19
	v_exp_f32_e32 v18, v18
	v_cvt_i32_f32_e32 v19, v20
	v_ldexp_f32 v18, v18, v19
	v_mul_f32_e32 v19, 0xbfb8aa3b, v35
	v_fma_f32 v20, v35, s43, -v19
	v_rndne_f32_e32 v21, v19
	v_fmac_f32_e32 v20, 0xb2a5705f, v35
	v_sub_f32_e32 v19, v19, v21
	v_add_f32_e32 v19, v19, v20
	v_exp_f32_e32 v19, v19
	v_cvt_i32_f32_e32 v20, v21
	v_cndmask_b32_e32 v18, 0, v18, vcc
	v_cmp_ngt_f32_e32 vcc, s35, v34
	v_ldexp_f32 v19, v19, v20
	s_nop 0
	v_cndmask_b32_e32 v18, v179, v18, vcc
	v_cmp_nlt_f32_e32 vcc, s34, v35
	v_pk_fma_f32 v[20:21], v[30:31], v[126:127], v[38:39] op_sel_hi:[1,0,1]
	s_nop 0
	v_cndmask_b32_e32 v19, 0, v19, vcc
	v_cmp_ngt_f32_e32 vcc, s35, v35
	s_nop 1
	v_cndmask_b32_e32 v19, v179, v19, vcc
	v_pk_add_f32 v[18:19], v[18:19], 1.0 op_sel_hi:[1,0]
	s_nop 0
	v_div_scale_f32 v22, s[2:3], v19, v19, v35
	v_rcp_f32_e32 v23, v22
	s_nop 0
	v_fma_f32 v24, -v22, v23, 1.0
	v_fmac_f32_e32 v23, v24, v23
	v_div_scale_f32 v24, vcc, v35, v19, v35
	v_mul_f32_e32 v25, v24, v23
	v_fma_f32 v26, -v22, v25, v24
	v_fmac_f32_e32 v25, v26, v23
	v_fma_f32 v22, -v22, v25, v24
	v_div_fmas_f32 v22, v22, v23, v25
	v_div_fixup_f32 v19, v22, v19, v35
	v_div_scale_f32 v22, s[2:3], v18, v18, v34
	v_rcp_f32_e32 v23, v22
	s_nop 0
	v_fma_f32 v24, -v22, v23, 1.0
	v_fmac_f32_e32 v23, v24, v23
	v_div_scale_f32 v24, vcc, v34, v18, v34
	v_mul_f32_e32 v25, v24, v23
	v_fma_f32 v26, -v22, v25, v24
	v_fmac_f32_e32 v25, v26, v23
	v_fma_f32 v22, -v22, v25, v24
	v_div_fmas_f32 v22, v22, v23, v25
	v_div_fixup_f32 v18, v22, v18, v34
	v_pk_mul_f32 v[124:125], v[20:21], v[18:19]
	s_nop 0
	v_pk_fma_f32 v[16:17], v[124:125], v[124:125], v[16:17]
	v_mul_f32_e32 v18, v125, v125
	v_pk_add_f32 v[128:129], v[18:19], v[16:17] op_sel_hi:[0,1]
	global_load_dwordx4 v[36:39], v[130:131], off offset:128
	global_load_dwordx4 v[32:35], v[132:133], off offset:128
	global_load_dwordx4 v[28:31], v[130:131], off offset:160
	global_load_dwordx4 v[24:27], v[132:133], off offset:160
	global_load_dwordx4 v[20:23], v[130:131], off offset:192
	global_load_dwordx4 v[16:19], v[132:133], off offset:192
	global_load_dwordx4 v[44:47], v[130:131], off offset:224
	global_load_dwordx4 v[40:43], v[132:133], off offset:224
	s_waitcnt vmcnt(7)
	v_pk_fma_f32 v[0:1], v[0:1], v[126:127], v[36:37] op_sel_hi:[1,0,1]
	s_waitcnt vmcnt(6)
	v_mul_f32_e32 v103, 0xbfb8aa3b, v32
	v_fma_f32 v105, v32, s43, -v103
	v_rndne_f32_e32 v107, v103
	v_fmac_f32_e32 v105, 0xb2a5705f, v32
	v_sub_f32_e32 v103, v103, v107
	v_add_f32_e32 v103, v103, v105
	v_exp_f32_e32 v103, v103
	v_cvt_i32_f32_e32 v105, v107
	v_cmp_nlt_f32_e32 vcc, s34, v32
	v_ldexp_f32 v103, v103, v105
	s_nop 0
	v_cndmask_b32_e32 v103, 0, v103, vcc
	v_cmp_ngt_f32_e32 vcc, s35, v32
	s_nop 1
	v_cndmask_b32_e32 v130, v179, v103, vcc
	v_mul_f32_e32 v103, 0xbfb8aa3b, v33
	v_fma_f32 v105, v33, s43, -v103
	v_rndne_f32_e32 v107, v103
	v_fmac_f32_e32 v105, 0xb2a5705f, v33
	v_sub_f32_e32 v103, v103, v107
	v_add_f32_e32 v103, v103, v105
	v_exp_f32_e32 v103, v103
	v_cvt_i32_f32_e32 v105, v107
	v_cmp_nlt_f32_e32 vcc, s34, v33
	v_ldexp_f32 v103, v103, v105
	s_nop 0
	v_cndmask_b32_e32 v103, 0, v103, vcc
	v_cmp_ngt_f32_e32 vcc, s35, v33
	s_nop 1
	v_cndmask_b32_e32 v131, v179, v103, vcc
	v_pk_add_f32 v[36:37], v[130:131], 1.0 op_sel_hi:[1,0]
	s_nop 0
	v_div_scale_f32 v103, s[2:3], v37, v37, v33
	v_rcp_f32_e32 v105, v103
	s_nop 0
	v_fma_f32 v107, -v103, v105, 1.0
	v_fmac_f32_e32 v105, v107, v105
	v_div_scale_f32 v107, vcc, v33, v37, v33
	v_mul_f32_e32 v109, v107, v105
	v_fma_f32 v127, -v103, v109, v107
	v_fmac_f32_e32 v109, v127, v105
	v_fma_f32 v103, -v103, v109, v107
	v_div_fmas_f32 v103, v103, v105, v109
	v_div_fixup_f32 v33, v103, v37, v33
	v_div_scale_f32 v37, s[2:3], v36, v36, v32
	v_rcp_f32_e32 v103, v37
	v_pk_fma_f32 v[2:3], v[2:3], v[126:127], v[38:39] op_sel_hi:[1,0,1]
	s_waitcnt vmcnt(5)
	v_pk_fma_f32 v[4:5], v[4:5], v[126:127], v[28:29] op_sel_hi:[1,0,1]
	v_pk_fma_f32 v[6:7], v[6:7], v[126:127], v[30:31] op_sel_hi:[1,0,1]
	v_fma_f32 v105, -v37, v103, 1.0
	v_fmac_f32_e32 v103, v105, v103
	v_div_scale_f32 v105, vcc, v32, v36, v32
	v_mul_f32_e32 v107, v105, v103
	v_fma_f32 v109, -v37, v107, v105
	v_fmac_f32_e32 v107, v109, v103
	v_fma_f32 v37, -v37, v107, v105
	v_div_fmas_f32 v37, v37, v103, v107
	v_div_fixup_f32 v32, v37, v36, v32
	v_pk_mul_f32 v[0:1], v[0:1], v[32:33]
	v_cmp_nlt_f32_e32 vcc, s34, v34
	v_pk_fma_f32 v[32:33], v[0:1], v[0:1], v[128:129]
	v_mul_f32_e32 v36, v1, v1
	v_pk_add_f32 v[32:33], v[36:37], v[32:33] op_sel_hi:[0,1]
	v_mul_f32_e32 v36, 0xbfb8aa3b, v34
	v_fma_f32 v37, v34, s43, -v36
	v_rndne_f32_e32 v103, v36
	v_fmac_f32_e32 v37, 0xb2a5705f, v34
	v_sub_f32_e32 v36, v36, v103
	v_add_f32_e32 v36, v36, v37
	v_exp_f32_e32 v36, v36
	v_cvt_i32_f32_e32 v37, v103
	s_waitcnt vmcnt(3)
	v_pk_fma_f32 v[8:9], v[8:9], v[126:127], v[20:21] op_sel_hi:[1,0,1]
	v_pk_fma_f32 v[10:11], v[10:11], v[126:127], v[22:23] op_sel_hi:[1,0,1]
	s_waitcnt vmcnt(1)
	v_pk_fma_f32 v[12:13], v[12:13], v[126:127], v[44:45] op_sel_hi:[1,0,1]
	v_ldexp_f32 v36, v36, v37
	v_mul_f32_e32 v37, 0xbfb8aa3b, v35
	v_fma_f32 v103, v35, s43, -v37
	v_rndne_f32_e32 v105, v37
	v_fmac_f32_e32 v103, 0xb2a5705f, v35
	v_sub_f32_e32 v37, v37, v105
	v_add_f32_e32 v37, v37, v103
	v_exp_f32_e32 v37, v37
	v_cvt_i32_f32_e32 v103, v105
	v_cndmask_b32_e32 v36, 0, v36, vcc
	v_cmp_ngt_f32_e32 vcc, s35, v34
	v_pk_fma_f32 v[14:15], v[14:15], v[126:127], v[46:47] op_sel_hi:[1,0,1]
	v_ldexp_f32 v37, v37, v103
	v_cndmask_b32_e32 v36, v179, v36, vcc
	v_cmp_nlt_f32_e32 vcc, s34, v35
	s_nop 1
	v_cndmask_b32_e32 v37, 0, v37, vcc
	v_cmp_ngt_f32_e32 vcc, s35, v35
	s_nop 1
	v_cndmask_b32_e32 v37, v179, v37, vcc
	v_pk_add_f32 v[36:37], v[36:37], 1.0 op_sel_hi:[1,0]
	s_nop 0
	v_div_scale_f32 v38, s[2:3], v37, v37, v35
	v_rcp_f32_e32 v39, v38
	s_nop 0
	v_fma_f32 v103, -v38, v39, 1.0
	v_fmac_f32_e32 v39, v103, v39
	v_div_scale_f32 v103, vcc, v35, v37, v35
	v_mul_f32_e32 v105, v103, v39
	v_fma_f32 v107, -v38, v105, v103
	v_fmac_f32_e32 v105, v107, v39
	v_fma_f32 v38, -v38, v105, v103
	v_div_fmas_f32 v38, v38, v39, v105
	v_div_fixup_f32 v35, v38, v37, v35
	v_div_scale_f32 v37, s[2:3], v36, v36, v34
	v_rcp_f32_e32 v38, v37
	s_nop 0
	v_fma_f32 v39, -v37, v38, 1.0
	v_fmac_f32_e32 v38, v39, v38
	v_div_scale_f32 v39, vcc, v34, v36, v34
	v_mul_f32_e32 v103, v39, v38
	v_fma_f32 v105, -v37, v103, v39
	v_fmac_f32_e32 v103, v105, v38
	v_fma_f32 v37, -v37, v103, v39
	v_div_fmas_f32 v37, v37, v38, v103
	v_div_fixup_f32 v34, v37, v36, v34
	v_pk_mul_f32 v[2:3], v[2:3], v[34:35]
	v_cmp_nlt_f32_e32 vcc, s34, v24
	v_pk_fma_f32 v[32:33], v[2:3], v[2:3], v[32:33]
	v_mul_f32_e32 v34, v3, v3
	v_pk_add_f32 v[32:33], v[34:35], v[32:33] op_sel_hi:[0,1]
	v_mul_f32_e32 v34, 0xbfb8aa3b, v24
	v_fma_f32 v35, v24, s43, -v34
	v_rndne_f32_e32 v36, v34
	v_fmac_f32_e32 v35, 0xb2a5705f, v24
	v_sub_f32_e32 v34, v34, v36
	v_add_f32_e32 v34, v34, v35
	v_exp_f32_e32 v34, v34
	v_cvt_i32_f32_e32 v35, v36
	v_ldexp_f32 v34, v34, v35
	v_mul_f32_e32 v35, 0xbfb8aa3b, v25
	v_fma_f32 v36, v25, s43, -v35
	v_rndne_f32_e32 v37, v35
	v_fmac_f32_e32 v36, 0xb2a5705f, v25
	v_sub_f32_e32 v35, v35, v37
	v_add_f32_e32 v35, v35, v36
	v_exp_f32_e32 v35, v35
	v_cvt_i32_f32_e32 v36, v37
	v_cndmask_b32_e32 v34, 0, v34, vcc
	v_cmp_ngt_f32_e32 vcc, s35, v24
	v_ldexp_f32 v35, v35, v36
	s_nop 0
	v_cndmask_b32_e32 v34, v179, v34, vcc
	v_cmp_nlt_f32_e32 vcc, s34, v25
	s_nop 1
	v_cndmask_b32_e32 v35, 0, v35, vcc
	v_cmp_ngt_f32_e32 vcc, s35, v25
	s_nop 1
	v_cndmask_b32_e32 v35, v179, v35, vcc
	v_pk_add_f32 v[28:29], v[34:35], 1.0 op_sel_hi:[1,0]
	s_nop 0
	v_div_scale_f32 v34, s[2:3], v29, v29, v25
	v_rcp_f32_e32 v35, v34
	s_nop 0
	v_fma_f32 v36, -v34, v35, 1.0
	v_fmac_f32_e32 v35, v36, v35
	v_div_scale_f32 v36, vcc, v25, v29, v25
	v_mul_f32_e32 v37, v36, v35
	v_fma_f32 v38, -v34, v37, v36
	v_fmac_f32_e32 v37, v38, v35
	v_fma_f32 v34, -v34, v37, v36
	v_div_fmas_f32 v34, v34, v35, v37
	v_div_fixup_f32 v25, v34, v29, v25
	v_div_scale_f32 v29, s[2:3], v28, v28, v24
	v_rcp_f32_e32 v34, v29
	s_nop 0
	v_fma_f32 v35, -v29, v34, 1.0
	v_fmac_f32_e32 v34, v35, v34
	v_div_scale_f32 v35, vcc, v24, v28, v24
	v_mul_f32_e32 v36, v35, v34
	v_fma_f32 v37, -v29, v36, v35
	v_fmac_f32_e32 v36, v37, v34
	v_fma_f32 v29, -v29, v36, v35
	v_div_fmas_f32 v29, v29, v34, v36
	v_div_fixup_f32 v24, v29, v28, v24
	v_pk_mul_f32 v[4:5], v[4:5], v[24:25]
	v_cmp_nlt_f32_e32 vcc, s34, v26
	v_pk_fma_f32 v[24:25], v[4:5], v[4:5], v[32:33]
	v_mul_f32_e32 v28, v5, v5
	v_pk_add_f32 v[24:25], v[28:29], v[24:25] op_sel_hi:[0,1]
	v_mul_f32_e32 v28, 0xbfb8aa3b, v26
	v_fma_f32 v29, v26, s43, -v28
	v_rndne_f32_e32 v32, v28
	v_fmac_f32_e32 v29, 0xb2a5705f, v26
	v_sub_f32_e32 v28, v28, v32
	v_add_f32_e32 v28, v28, v29
	v_exp_f32_e32 v28, v28
	v_cvt_i32_f32_e32 v29, v32
	v_ldexp_f32 v28, v28, v29
	v_mul_f32_e32 v29, 0xbfb8aa3b, v27
	v_fma_f32 v32, v27, s43, -v29
	v_rndne_f32_e32 v33, v29
	v_fmac_f32_e32 v32, 0xb2a5705f, v27
	v_sub_f32_e32 v29, v29, v33
	v_add_f32_e32 v29, v29, v32
	v_exp_f32_e32 v29, v29
	v_cvt_i32_f32_e32 v32, v33
	v_cndmask_b32_e32 v28, 0, v28, vcc
	v_cmp_ngt_f32_e32 vcc, s35, v26
	v_ldexp_f32 v29, v29, v32
	s_nop 0
	v_cndmask_b32_e32 v28, v179, v28, vcc
	v_cmp_nlt_f32_e32 vcc, s34, v27
	s_nop 1
	v_cndmask_b32_e32 v29, 0, v29, vcc
	v_cmp_ngt_f32_e32 vcc, s35, v27
	s_nop 1
	v_cndmask_b32_e32 v29, v179, v29, vcc
	v_pk_add_f32 v[28:29], v[28:29], 1.0 op_sel_hi:[1,0]
	s_nop 0
	v_div_scale_f32 v30, s[2:3], v29, v29, v27
	v_rcp_f32_e32 v31, v30
	s_nop 0
	v_fma_f32 v32, -v30, v31, 1.0
	v_fmac_f32_e32 v31, v32, v31
	v_div_scale_f32 v32, vcc, v27, v29, v27
	v_mul_f32_e32 v33, v32, v31
	v_fma_f32 v34, -v30, v33, v32
	v_fmac_f32_e32 v33, v34, v31
	v_fma_f32 v30, -v30, v33, v32
	v_div_fmas_f32 v30, v30, v31, v33
	v_div_fixup_f32 v27, v30, v29, v27
	v_div_scale_f32 v29, s[2:3], v28, v28, v26
	v_rcp_f32_e32 v30, v29
	s_nop 0
	v_fma_f32 v31, -v29, v30, 1.0
	v_fmac_f32_e32 v30, v31, v30
	v_div_scale_f32 v31, vcc, v26, v28, v26
	v_mul_f32_e32 v32, v31, v30
	v_fma_f32 v33, -v29, v32, v31
	v_fmac_f32_e32 v32, v33, v30
	v_fma_f32 v29, -v29, v32, v31
	v_div_fmas_f32 v29, v29, v30, v32
	v_div_fixup_f32 v26, v29, v28, v26
	v_pk_mul_f32 v[6:7], v[6:7], v[26:27]
	v_cmp_nlt_f32_e32 vcc, s34, v16
	v_pk_fma_f32 v[24:25], v[6:7], v[6:7], v[24:25]
	v_mul_f32_e32 v26, v7, v7
	v_pk_add_f32 v[24:25], v[26:27], v[24:25] op_sel_hi:[0,1]
	v_mul_f32_e32 v26, 0xbfb8aa3b, v16
	v_fma_f32 v27, v16, s43, -v26
	v_rndne_f32_e32 v28, v26
	v_fmac_f32_e32 v27, 0xb2a5705f, v16
	v_sub_f32_e32 v26, v26, v28
	v_add_f32_e32 v26, v26, v27
	v_exp_f32_e32 v26, v26
	v_cvt_i32_f32_e32 v27, v28
	v_ldexp_f32 v26, v26, v27
	v_mul_f32_e32 v27, 0xbfb8aa3b, v17
	v_fma_f32 v28, v17, s43, -v27
	v_rndne_f32_e32 v29, v27
	v_fmac_f32_e32 v28, 0xb2a5705f, v17
	v_sub_f32_e32 v27, v27, v29
	v_add_f32_e32 v27, v27, v28
	v_exp_f32_e32 v27, v27
	v_cvt_i32_f32_e32 v28, v29
	v_cndmask_b32_e32 v26, 0, v26, vcc
	v_cmp_ngt_f32_e32 vcc, s35, v16
	v_ldexp_f32 v27, v27, v28
	s_nop 0
	v_cndmask_b32_e32 v26, v179, v26, vcc
	v_cmp_nlt_f32_e32 vcc, s34, v17
	s_nop 1
	v_cndmask_b32_e32 v27, 0, v27, vcc
	v_cmp_ngt_f32_e32 vcc, s35, v17
	s_nop 1
	v_cndmask_b32_e32 v27, v179, v27, vcc
	v_pk_add_f32 v[20:21], v[26:27], 1.0 op_sel_hi:[1,0]
	s_nop 0
	v_div_scale_f32 v26, s[2:3], v21, v21, v17
	v_rcp_f32_e32 v27, v26
	s_nop 0
	v_fma_f32 v28, -v26, v27, 1.0
	v_fmac_f32_e32 v27, v28, v27
	v_div_scale_f32 v28, vcc, v17, v21, v17
	v_mul_f32_e32 v29, v28, v27
	v_fma_f32 v30, -v26, v29, v28
	v_fmac_f32_e32 v29, v30, v27
	v_fma_f32 v26, -v26, v29, v28
	v_div_fmas_f32 v26, v26, v27, v29
	v_div_fixup_f32 v17, v26, v21, v17
	v_div_scale_f32 v21, s[2:3], v20, v20, v16
	v_rcp_f32_e32 v26, v21
	s_nop 0
	v_fma_f32 v27, -v21, v26, 1.0
	v_fmac_f32_e32 v26, v27, v26
	v_div_scale_f32 v27, vcc, v16, v20, v16
	v_mul_f32_e32 v28, v27, v26
	v_fma_f32 v29, -v21, v28, v27
	v_fmac_f32_e32 v28, v29, v26
	v_fma_f32 v21, -v21, v28, v27
	v_div_fmas_f32 v21, v21, v26, v28
	v_div_fixup_f32 v16, v21, v20, v16
	v_pk_mul_f32 v[8:9], v[8:9], v[16:17]
	v_cmp_nlt_f32_e32 vcc, s34, v18
	v_pk_fma_f32 v[16:17], v[8:9], v[8:9], v[24:25]
	v_mul_f32_e32 v20, v9, v9
	v_pk_add_f32 v[16:17], v[20:21], v[16:17] op_sel_hi:[0,1]
	v_mul_f32_e32 v20, 0xbfb8aa3b, v18
	v_fma_f32 v21, v18, s43, -v20
	v_rndne_f32_e32 v24, v20
	v_fmac_f32_e32 v21, 0xb2a5705f, v18
	v_sub_f32_e32 v20, v20, v24
	v_add_f32_e32 v20, v20, v21
	v_exp_f32_e32 v20, v20
	v_cvt_i32_f32_e32 v21, v24
	v_ldexp_f32 v20, v20, v21
	v_mul_f32_e32 v21, 0xbfb8aa3b, v19
	v_fma_f32 v24, v19, s43, -v21
	v_rndne_f32_e32 v25, v21
	v_fmac_f32_e32 v24, 0xb2a5705f, v19
	v_sub_f32_e32 v21, v21, v25
	v_add_f32_e32 v21, v21, v24
	v_exp_f32_e32 v21, v21
	v_cvt_i32_f32_e32 v24, v25
	v_cndmask_b32_e32 v20, 0, v20, vcc
	v_cmp_ngt_f32_e32 vcc, s35, v18
	v_ldexp_f32 v21, v21, v24
	s_nop 0
	v_cndmask_b32_e32 v20, v179, v20, vcc
	v_cmp_nlt_f32_e32 vcc, s34, v19
	s_nop 1
	v_cndmask_b32_e32 v21, 0, v21, vcc
	v_cmp_ngt_f32_e32 vcc, s35, v19
	s_nop 1
	v_cndmask_b32_e32 v21, v179, v21, vcc
	v_pk_add_f32 v[20:21], v[20:21], 1.0 op_sel_hi:[1,0]
	s_nop 0
	v_div_scale_f32 v22, s[2:3], v21, v21, v19
	v_rcp_f32_e32 v23, v22
	s_nop 0
	v_fma_f32 v24, -v22, v23, 1.0
	v_fmac_f32_e32 v23, v24, v23
	v_div_scale_f32 v24, vcc, v19, v21, v19
	v_mul_f32_e32 v25, v24, v23
	v_fma_f32 v26, -v22, v25, v24
	v_fmac_f32_e32 v25, v26, v23
	v_fma_f32 v22, -v22, v25, v24
	v_div_fmas_f32 v22, v22, v23, v25
	v_div_fixup_f32 v19, v22, v21, v19
	v_div_scale_f32 v21, s[2:3], v20, v20, v18
	v_rcp_f32_e32 v22, v21
	s_nop 0
	v_fma_f32 v23, -v21, v22, 1.0
	v_fmac_f32_e32 v22, v23, v22
	v_div_scale_f32 v23, vcc, v18, v20, v18
	v_mul_f32_e32 v24, v23, v22
	v_fma_f32 v25, -v21, v24, v23
	v_fmac_f32_e32 v24, v25, v22
	v_fma_f32 v21, -v21, v24, v23
	v_div_fmas_f32 v21, v21, v22, v24
	v_div_fixup_f32 v18, v21, v20, v18
	v_pk_mul_f32 v[10:11], v[10:11], v[18:19]
	s_waitcnt vmcnt(0)
	v_cmp_nlt_f32_e32 vcc, s34, v40
	v_pk_fma_f32 v[16:17], v[10:11], v[10:11], v[16:17]
	v_mul_f32_e32 v18, v11, v11
	v_pk_add_f32 v[16:17], v[18:19], v[16:17] op_sel_hi:[0,1]
	v_mul_f32_e32 v18, 0xbfb8aa3b, v40
	v_fma_f32 v19, v40, s43, -v18
	v_rndne_f32_e32 v20, v18
	v_fmac_f32_e32 v19, 0xb2a5705f, v40
	v_sub_f32_e32 v18, v18, v20
	v_add_f32_e32 v18, v18, v19
	v_exp_f32_e32 v18, v18
	v_cvt_i32_f32_e32 v19, v20
	v_ldexp_f32 v18, v18, v19
	v_mul_f32_e32 v19, 0xbfb8aa3b, v41
	v_fma_f32 v20, v41, s43, -v19
	v_rndne_f32_e32 v21, v19
	v_fmac_f32_e32 v20, 0xb2a5705f, v41
	v_sub_f32_e32 v19, v19, v21
	v_add_f32_e32 v19, v19, v20
	v_exp_f32_e32 v19, v19
	v_cvt_i32_f32_e32 v20, v21
	v_cndmask_b32_e32 v18, 0, v18, vcc
	v_cmp_ngt_f32_e32 vcc, s35, v40
	v_ldexp_f32 v19, v19, v20
	s_nop 0
	v_cndmask_b32_e32 v18, v179, v18, vcc
	v_cmp_nlt_f32_e32 vcc, s34, v41
	s_nop 1
	v_cndmask_b32_e32 v19, 0, v19, vcc
	v_cmp_ngt_f32_e32 vcc, s35, v41
	s_nop 1
	v_cndmask_b32_e32 v19, v179, v19, vcc
	v_pk_add_f32 v[18:19], v[18:19], 1.0 op_sel_hi:[1,0]
	s_nop 0
	v_div_scale_f32 v20, s[2:3], v19, v19, v41
	v_rcp_f32_e32 v21, v20
	s_nop 0
	v_fma_f32 v22, -v20, v21, 1.0
	v_fmac_f32_e32 v21, v22, v21
	v_div_scale_f32 v22, vcc, v41, v19, v41
	v_mul_f32_e32 v23, v22, v21
	v_fma_f32 v24, -v20, v23, v22
	v_fmac_f32_e32 v23, v24, v21
	v_fma_f32 v20, -v20, v23, v22
	v_div_fmas_f32 v20, v20, v21, v23
	v_div_fixup_f32 v19, v20, v19, v41
	v_div_scale_f32 v20, s[2:3], v18, v18, v40
	v_rcp_f32_e32 v21, v20
	s_nop 0
	v_fma_f32 v22, -v20, v21, 1.0
	v_fmac_f32_e32 v21, v22, v21
	v_div_scale_f32 v22, vcc, v40, v18, v40
	v_mul_f32_e32 v23, v22, v21
	v_fma_f32 v24, -v20, v23, v22
	v_fmac_f32_e32 v23, v24, v21
	v_fma_f32 v20, -v20, v23, v22
	v_div_fmas_f32 v20, v20, v21, v23
	v_div_fixup_f32 v18, v20, v18, v40
	v_pk_mul_f32 v[12:13], v[12:13], v[18:19]
	v_cmp_nlt_f32_e32 vcc, s34, v42
	v_pk_fma_f32 v[16:17], v[12:13], v[12:13], v[16:17]
	v_mul_f32_e32 v18, v13, v13
	v_pk_add_f32 v[16:17], v[18:19], v[16:17] op_sel_hi:[0,1]
	v_mul_f32_e32 v18, 0xbfb8aa3b, v42
	v_fma_f32 v19, v42, s43, -v18
	v_rndne_f32_e32 v20, v18
	v_fmac_f32_e32 v19, 0xb2a5705f, v42
	v_sub_f32_e32 v18, v18, v20
	v_add_f32_e32 v18, v18, v19
	v_exp_f32_e32 v18, v18
	v_cvt_i32_f32_e32 v19, v20
	v_ldexp_f32 v18, v18, v19
	v_mul_f32_e32 v19, 0xbfb8aa3b, v43
	v_fma_f32 v20, v43, s43, -v19
	v_rndne_f32_e32 v21, v19
	v_fmac_f32_e32 v20, 0xb2a5705f, v43
	v_sub_f32_e32 v19, v19, v21
	v_add_f32_e32 v19, v19, v20
	v_exp_f32_e32 v19, v19
	v_cvt_i32_f32_e32 v20, v21
	v_cndmask_b32_e32 v18, 0, v18, vcc
	v_cmp_ngt_f32_e32 vcc, s35, v42
	v_ldexp_f32 v19, v19, v20
	s_nop 0
	v_cndmask_b32_e32 v18, v179, v18, vcc
	v_cmp_nlt_f32_e32 vcc, s34, v43
	s_nop 1
	v_cndmask_b32_e32 v19, 0, v19, vcc
	v_cmp_ngt_f32_e32 vcc, s35, v43
	s_nop 1
	v_cndmask_b32_e32 v19, v179, v19, vcc
	v_pk_add_f32 v[18:19], v[18:19], 1.0 op_sel_hi:[1,0]
	s_nop 0
	v_div_scale_f32 v20, s[2:3], v19, v19, v43
	v_rcp_f32_e32 v21, v20
	s_nop 0
	v_fma_f32 v22, -v20, v21, 1.0
	v_fmac_f32_e32 v21, v22, v21
	v_div_scale_f32 v22, vcc, v43, v19, v43
	v_mul_f32_e32 v23, v22, v21
	v_fma_f32 v24, -v20, v23, v22
	v_fmac_f32_e32 v23, v24, v21
	v_fma_f32 v20, -v20, v23, v22
	v_div_fmas_f32 v20, v20, v21, v23
	v_div_fixup_f32 v19, v20, v19, v43
	v_div_scale_f32 v20, s[2:3], v18, v18, v42
	v_rcp_f32_e32 v21, v20
	s_nop 0
	v_fma_f32 v22, -v20, v21, 1.0
	v_fmac_f32_e32 v21, v22, v21
	v_div_scale_f32 v22, vcc, v42, v18, v42
	v_mul_f32_e32 v23, v22, v21
	v_fma_f32 v24, -v20, v23, v22
	v_fmac_f32_e32 v23, v24, v21
	v_fma_f32 v20, -v20, v23, v22
	v_div_fmas_f32 v20, v20, v21, v23
	v_div_fixup_f32 v18, v20, v18, v42
	v_pk_mul_f32 v[14:15], v[14:15], v[18:19]
	s_nop 0
	v_pk_fma_f32 v[16:17], v[14:15], v[14:15], v[16:17]
	v_mul_f32_e32 v18, v15, v15
	v_pk_add_f32 v[16:17], v[18:19], v[16:17] op_sel_hi:[0,1]
	v_mov_b32_e32 v17, v16
	s_nop 1
	v_permlane32_swap_b32_e32 v16, v17
	s_and_saveexec_b64 s[4:5], s[48:49]
	s_cbranch_execz .LBB0_1284
	v_add_f32_e32 v16, v16, v17
	ds_write_b32 v97, v16 offset:1024
	s_branch .LBB0_1284

.LBB0_1440:
	s_ashr_i32 s17, s16, 31
	s_lshl_b64 s[18:19], s[16:17], 12
	s_waitcnt lgkmcnt(0)
	s_add_u32 s2, s4, s18
	s_addc_u32 s3, s5, s19
	s_lshl_b64 s[4:5], s[16:17], 11
	v_lshl_add_u64 v[4:5], v[82:83], 0, s[4:5]
	v_lshl_add_u64 v[28:29], v[80:81], 4, s[2:3]
	global_load_dwordx2 v[60:61], v[4:5], off
	global_load_dwordx4 v[40:43], v[28:29], off
	global_load_dwordx2 v[94:95], v[4:5], off offset:512
	global_load_dwordx4 v[24:27], v[28:29], off offset:1024
	global_load_dwordx2 v[92:93], v[4:5], off offset:1024
	global_load_dwordx4 v[12:15], v[28:29], off offset:2048
	global_load_dwordx2 v[74:75], v[4:5], off offset:1536
	global_load_dwordx4 v[0:3], v[28:29], off offset:3072
	global_load_dwordx2 v[72:73], v[4:5], off offset:2048
	v_add_co_u32_e32 v6, vcc, s79, v28
	s_movk_i32 s21, 0x2000
	s_nop 0
	v_addc_co_u32_e32 v7, vcc, 0, v29, vcc
	v_add_co_u32_e32 v30, vcc, s21, v28
	s_movk_i32 s22, 0x3000
	s_nop 0
	v_addc_co_u32_e32 v31, vcc, 0, v29, vcc
	global_load_dwordx4 v[48:51], v[30:31], off offset:-4096
	global_load_dwordx2 v[106:107], v[4:5], off offset:2560
	global_load_dwordx4 v[32:35], v[6:7], off offset:1024
	global_load_dwordx2 v[112:113], v[4:5], off offset:3072
	global_load_dwordx4 v[16:19], v[6:7], off offset:2048
	global_load_dwordx2 v[108:109], v[4:5], off offset:3584
	global_load_dwordx4 v[8:11], v[6:7], off offset:3072
	v_add_co_u32_e32 v62, vcc, s79, v4
	v_lshl_add_u64 v[160:161], v[86:87], 0, s[18:19]
	s_nop 0
	v_addc_co_u32_e32 v63, vcc, 0, v5, vcc
	global_load_dwordx2 v[110:111], v[62:63], off
	global_load_dwordx4 v[52:55], v[30:31], off
	global_load_dwordx2 v[78:79], v[62:63], off offset:512
	global_load_dwordx4 v[36:39], v[30:31], off offset:1024
	global_load_dwordx2 v[76:77], v[62:63], off offset:1024
	global_load_dwordx4 v[20:23], v[30:31], off offset:2048
	global_load_dwordx2 v[70:71], v[62:63], off offset:1536
	global_load_dwordx4 v[4:7], v[30:31], off offset:3072
	global_load_dwordx2 v[68:69], v[62:63], off offset:2048
	v_add_co_u32_e32 v28, vcc, s22, v28
	s_nop 1
	v_addc_co_u32_e32 v29, vcc, 0, v29, vcc
	global_load_dwordx4 v[64:67], v[28:29], off
	global_load_dwordx2 v[118:119], v[62:63], off offset:2560
	global_load_dwordx4 v[56:59], v[28:29], off offset:1024
	global_load_dwordx2 v[132:133], v[62:63], off offset:3072
	global_load_dwordx4 v[44:47], v[28:29], off offset:2048
	global_load_dwordx2 v[120:121], v[62:63], off offset:3584
	s_nop 0
	global_load_dwordx4 v[28:31], v[28:29], off offset:3072
	s_waitcnt vmcnt(7)
	v_and_b32_e32 v103, 0xffff0000, v94
	v_lshlrev_b32_e32 v62, 16, v60
	v_and_b32_e32 v63, 0xffff0000, v60
	v_lshlrev_b32_e32 v60, 16, v61
	v_and_b32_e32 v61, 0xffff0000, v61
	v_and_b32_e32 v105, 0xffff0000, v95
	v_mul_f32_e32 v98, v63, v63
	v_mul_f32_e32 v99, v61, v61
	v_lshlrev_b32_e32 v102, 16, v94
	v_lshlrev_b32_e32 v104, 16, v95
	v_mul_f32_e32 v94, v103, v103
	v_mul_f32_e32 v95, v105, v105
	v_fmac_f32_e32 v98, v62, v62
	v_fmac_f32_e32 v99, v60, v60
	v_fmac_f32_e32 v94, v102, v102
	v_fmac_f32_e32 v95, v104, v104
	v_add_f32_e32 v98, v98, v99
	v_add_f32_e32 v94, v94, v95
	v_and_b32_e32 v99, 0xffff0000, v92
	v_and_b32_e32 v101, 0xffff0000, v93
	v_add_f32_e32 v94, v98, v94
	v_lshlrev_b32_e32 v98, 16, v92
	v_lshlrev_b32_e32 v100, 16, v93
	v_mul_f32_e32 v92, v99, v99
	v_mul_f32_e32 v93, v101, v101
	v_fmac_f32_e32 v92, v98, v98
	v_fmac_f32_e32 v93, v100, v100
	v_add_f32_e32 v92, v92, v93
	v_and_b32_e32 v93, 0xffff0000, v74
	v_and_b32_e32 v95, 0xffff0000, v75
	v_add_f32_e32 v114, v94, v92
	v_lshlrev_b32_e32 v92, 16, v74
	v_lshlrev_b32_e32 v94, 16, v75
	v_mul_f32_e32 v74, v93, v93
	v_mul_f32_e32 v75, v95, v95
	v_fmac_f32_e32 v74, v92, v92
	v_fmac_f32_e32 v75, v94, v94
	v_add_f32_e32 v74, v74, v75
	v_add_f32_e32 v152, v114, v74
	v_lshlrev_b32_e32 v74, 16, v72
	v_and_b32_e32 v75, 0xffff0000, v72
	v_lshlrev_b32_e32 v72, 16, v73
	v_and_b32_e32 v73, 0xffff0000, v73
	v_and_b32_e32 v127, 0xffff0000, v106
	v_and_b32_e32 v129, 0xffff0000, v107
	v_mul_f32_e32 v114, v75, v75
	v_mul_f32_e32 v115, v73, v73
	v_lshlrev_b32_e32 v126, 16, v106
	v_lshlrev_b32_e32 v128, 16, v107
	v_mul_f32_e32 v106, v127, v127
	v_mul_f32_e32 v107, v129, v129
	v_fmac_f32_e32 v114, v74, v74
	v_fmac_f32_e32 v115, v72, v72
	v_fmac_f32_e32 v106, v126, v126
	v_fmac_f32_e32 v107, v128, v128
	v_add_f32_e32 v114, v114, v115
	v_add_f32_e32 v106, v106, v107
	v_and_b32_e32 v115, 0xffff0000, v112
	v_and_b32_e32 v117, 0xffff0000, v113
	v_add_f32_e32 v106, v114, v106
	v_lshlrev_b32_e32 v114, 16, v112
	v_lshlrev_b32_e32 v116, 16, v113
	v_mul_f32_e32 v107, v115, v115
	v_mul_f32_e32 v112, v117, v117
	v_fmac_f32_e32 v107, v114, v114
	v_fmac_f32_e32 v112, v116, v116
	v_add_f32_e32 v107, v107, v112
	v_add_f32_e32 v112, v106, v107
	v_lshlrev_b32_e32 v106, 16, v108
	v_and_b32_e32 v107, 0xffff0000, v108
	v_lshlrev_b32_e32 v108, 16, v109
	v_and_b32_e32 v109, 0xffff0000, v109
	v_mul_f32_e32 v113, v107, v107
	v_mul_f32_e32 v122, v109, v109
	v_and_b32_e32 v145, 0xffff0000, v110
	v_and_b32_e32 v143, 0xffff0000, v111
	v_and_b32_e32 v135, 0xffff0000, v78
	v_and_b32_e32 v137, 0xffff0000, v79
	v_fmac_f32_e32 v113, v106, v106
	v_fmac_f32_e32 v122, v108, v108
	v_lshlrev_b32_e32 v144, 16, v110
	v_lshlrev_b32_e32 v142, 16, v111
	v_mul_f32_e32 v110, v145, v145
	v_mul_f32_e32 v111, v143, v143
	v_lshlrev_b32_e32 v134, 16, v78
	v_lshlrev_b32_e32 v136, 16, v79
	v_mul_f32_e32 v78, v135, v135
	v_mul_f32_e32 v79, v137, v137
	v_add_f32_e32 v113, v113, v122
	v_fmac_f32_e32 v110, v144, v144
	v_fmac_f32_e32 v111, v142, v142
	v_fmac_f32_e32 v78, v134, v134
	v_fmac_f32_e32 v79, v136, v136
	v_add_f32_e32 v154, v112, v113
	v_add_f32_e32 v110, v110, v111
	v_add_f32_e32 v78, v78, v79
	v_and_b32_e32 v111, 0xffff0000, v70
	v_and_b32_e32 v113, 0xffff0000, v71
	v_and_b32_e32 v151, 0xffff0000, v68
	v_and_b32_e32 v149, 0xffff0000, v69
	v_add_f32_e32 v78, v110, v78
	v_lshlrev_b32_e32 v110, 16, v70
	v_lshlrev_b32_e32 v112, 16, v71
	v_mul_f32_e32 v70, v111, v111
	v_mul_f32_e32 v71, v113, v113
	v_lshlrev_b32_e32 v150, 16, v68
	v_lshlrev_b32_e32 v148, 16, v69
	v_mul_f32_e32 v68, v151, v151
	v_mul_f32_e32 v69, v149, v149
	v_fmac_f32_e32 v70, v110, v110
	v_fmac_f32_e32 v71, v112, v112
	v_fmac_f32_e32 v68, v150, v150
	v_fmac_f32_e32 v69, v148, v148
	s_waitcnt vmcnt(5)
	v_and_b32_e32 v139, 0xffff0000, v118
	v_and_b32_e32 v141, 0xffff0000, v119
	v_add_f32_e32 v70, v70, v71
	v_add_f32_e32 v68, v68, v69
	v_lshlrev_b32_e32 v138, 16, v118
	v_lshlrev_b32_e32 v140, 16, v119
	v_mul_f32_e32 v69, v139, v139
	v_mul_f32_e32 v71, v141, v141
	v_fmac_f32_e32 v69, v138, v138
	v_fmac_f32_e32 v71, v140, v140
	v_add_f32_e32 v69, v69, v71
	s_waitcnt vmcnt(3)
	v_lshlrev_b32_e32 v130, 16, v132
	v_and_b32_e32 v131, 0xffff0000, v132
	v_lshlrev_b32_e32 v132, 16, v133
	v_and_b32_e32 v133, 0xffff0000, v133
	v_add_f32_e32 v68, v68, v69
	v_mul_f32_e32 v69, v131, v131
	v_mul_f32_e32 v71, v133, v133
	v_fmac_f32_e32 v69, v130, v130
	v_fmac_f32_e32 v71, v132, v132
	v_add_f32_e32 v69, v69, v71
	s_waitcnt vmcnt(1)
	v_lshlrev_b32_e32 v118, 16, v120
	v_and_b32_e32 v119, 0xffff0000, v120
	v_lshlrev_b32_e32 v120, 16, v121
	v_and_b32_e32 v121, 0xffff0000, v121
	v_add_f32_e32 v68, v68, v69
	v_mul_f32_e32 v69, v119, v119
	v_mul_f32_e32 v71, v121, v121
	v_fmac_f32_e32 v69, v118, v118
	v_fmac_f32_e32 v71, v120, v120
	v_add_f32_e32 v69, v69, v71
	v_add_f32_e32 v68, v68, v69
	ds_bpermute_b32 v69, v97, v152
	v_and_b32_e32 v123, 0xffff0000, v76
	v_and_b32_e32 v125, 0xffff0000, v77
	v_lshlrev_b32_e32 v122, 16, v76
	v_lshlrev_b32_e32 v124, 16, v77
	s_waitcnt lgkmcnt(0)
	v_add_f32_e32 v69, v152, v69
	ds_bpermute_b32 v71, v147, v69
	v_mul_f32_e32 v76, v123, v123
	v_mul_f32_e32 v77, v125, v125
	v_fmac_f32_e32 v76, v122, v122
	v_fmac_f32_e32 v77, v124, v124
	s_waitcnt lgkmcnt(0)
	v_add_f32_e32 v69, v69, v71
	ds_bpermute_b32 v71, v153, v69
	v_add_f32_e32 v76, v76, v77
	v_add_f32_e32 v76, v78, v76
	v_add_f32_e32 v70, v76, v70
	s_waitcnt lgkmcnt(0)
	v_add_f32_e32 v69, v69, v71
	ds_bpermute_b32 v71, v155, v69
	s_waitcnt lgkmcnt(0)
	v_add_f32_e32 v69, v69, v71
	ds_bpermute_b32 v71, v157, v69
	s_waitcnt lgkmcnt(0)
	v_add_f32_e32 v69, v69, v71
	ds_bpermute_b32 v71, v159, v69
	s_waitcnt lgkmcnt(0)
	v_add_f32_e32 v69, v69, v71
	v_fmamk_f32 v69, v69, 0x3a800000, v177
	v_cmp_gt_f32_e32 vcc, s53, v69
	v_mul_f32_e32 v71, 0x4f800000, v69
	s_nop 0
	v_cndmask_b32_e32 v69, v69, v71, vcc
	v_sqrt_f32_e32 v71, v69
	s_nop 0
	v_add_u32_e32 v76, -1, v71
	v_fma_f32 v77, -v76, v71, v69
	v_cmp_ge_f32_e64 s[4:5], 0, v77
	v_add_u32_e32 v77, 1, v71
	s_nop 0
	v_cndmask_b32_e64 v76, v71, v76, s[4:5]
	v_fma_f32 v71, -v77, v71, v69
	v_cmp_lt_f32_e64 s[4:5], 0, v71
	s_nop 1
	v_cndmask_b32_e64 v71, v76, v77, s[4:5]
	v_mul_f32_e32 v76, 0x37800000, v71
	v_cndmask_b32_e32 v71, v71, v76, vcc
	v_cmp_class_f32_e32 vcc, v69, v234
	s_nop 1
	v_cndmask_b32_e32 v69, v71, v69, vcc
	v_div_scale_f32 v71, s[2:3], v69, v69, 1.0
	v_rcp_f32_e32 v76, v71
	s_nop 0
	v_fma_f32 v77, -v71, v76, 1.0
	v_fmac_f32_e32 v76, v77, v76
	v_div_scale_f32 v77, vcc, 1.0, v69, 1.0
	v_mul_f32_e32 v78, v77, v76
	v_fma_f32 v79, -v71, v78, v77
	v_fmac_f32_e32 v78, v79, v76
	v_fma_f32 v71, -v71, v78, v77
	v_div_fmas_f32 v71, v71, v76, v78
	v_div_fixup_f32 v152, v71, v69, 1.0
	ds_bpermute_b32 v69, v97, v154
	v_pk_mul_f32 v[62:63], v[152:153], v[62:63] op_sel_hi:[0,1]
	v_pk_mul_f32 v[60:61], v[152:153], v[60:61] op_sel_hi:[0,1]
	s_waitcnt lgkmcnt(0)
	v_add_f32_e32 v69, v154, v69
	ds_bpermute_b32 v71, v147, v69
	s_waitcnt lgkmcnt(0)
	v_add_f32_e32 v69, v69, v71
	ds_bpermute_b32 v71, v153, v69
	s_waitcnt lgkmcnt(0)
	v_add_f32_e32 v69, v69, v71
	ds_bpermute_b32 v71, v155, v69
	s_waitcnt lgkmcnt(0)
	v_add_f32_e32 v69, v69, v71
	ds_bpermute_b32 v71, v157, v69
	s_waitcnt lgkmcnt(0)
	v_add_f32_e32 v69, v69, v71
	ds_bpermute_b32 v71, v159, v69
	s_waitcnt lgkmcnt(0)
	v_add_f32_e32 v69, v69, v71
	v_fmamk_f32 v69, v69, 0x3a800000, v177
	v_cmp_gt_f32_e32 vcc, s53, v69
	v_mul_f32_e32 v71, 0x4f800000, v69
	s_nop 0
	v_cndmask_b32_e32 v69, v69, v71, vcc
	v_sqrt_f32_e32 v71, v69
	s_nop 0
	v_add_u32_e32 v76, -1, v71
	v_fma_f32 v77, -v76, v71, v69
	v_cmp_ge_f32_e64 s[4:5], 0, v77
	v_add_u32_e32 v77, 1, v71
	s_nop 0
	v_cndmask_b32_e64 v76, v71, v76, s[4:5]
	v_fma_f32 v71, -v77, v71, v69
	v_cmp_lt_f32_e64 s[4:5], 0, v71
	s_nop 1
	v_cndmask_b32_e64 v71, v76, v77, s[4:5]
	v_mul_f32_e32 v76, 0x37800000, v71
	v_cndmask_b32_e32 v71, v71, v76, vcc
	v_cmp_class_f32_e32 vcc, v69, v234
	s_nop 1
	v_cndmask_b32_e32 v69, v71, v69, vcc
	v_div_scale_f32 v71, s[2:3], v69, v69, 1.0
	v_rcp_f32_e32 v76, v71
	s_nop 0
	v_fma_f32 v77, -v71, v76, 1.0
	v_fmac_f32_e32 v76, v77, v76
	v_div_scale_f32 v77, vcc, 1.0, v69, 1.0
	v_mul_f32_e32 v78, v77, v76
	v_fma_f32 v79, -v71, v78, v77
	v_fmac_f32_e32 v78, v79, v76
	v_fma_f32 v71, -v71, v78, v77
	v_div_fmas_f32 v71, v71, v76, v78
	v_div_fixup_f32 v154, v71, v69, 1.0
	ds_bpermute_b32 v69, v97, v70
	s_waitcnt lgkmcnt(0)
	v_add_f32_e32 v69, v70, v69
	ds_bpermute_b32 v70, v147, v69
	s_waitcnt lgkmcnt(0)
	v_add_f32_e32 v69, v69, v70
	ds_bpermute_b32 v70, v153, v69
	s_waitcnt lgkmcnt(0)
	v_add_f32_e32 v69, v69, v70
	ds_bpermute_b32 v70, v155, v69
	s_waitcnt lgkmcnt(0)
	v_add_f32_e32 v69, v69, v70
	ds_bpermute_b32 v70, v157, v69
	s_waitcnt lgkmcnt(0)
	v_add_f32_e32 v69, v69, v70
	ds_bpermute_b32 v70, v159, v69
	s_waitcnt lgkmcnt(0)
	v_add_f32_e32 v69, v69, v70
	v_fmamk_f32 v69, v69, 0x3a800000, v177
	v_cmp_gt_f32_e32 vcc, s53, v69
	v_mul_f32_e32 v70, 0x4f800000, v69
	s_nop 0
	v_cndmask_b32_e32 v69, v69, v70, vcc
	v_sqrt_f32_e32 v70, v69
	s_nop 0
	v_add_u32_e32 v71, -1, v70
	v_fma_f32 v76, -v71, v70, v69
	v_cmp_ge_f32_e64 s[4:5], 0, v76
	v_add_u32_e32 v76, 1, v70
	s_nop 0
	v_cndmask_b32_e64 v71, v70, v71, s[4:5]
	v_fma_f32 v70, -v76, v70, v69
	v_cmp_lt_f32_e64 s[4:5], 0, v70
	s_nop 1
	v_cndmask_b32_e64 v70, v71, v76, s[4:5]
	v_mul_f32_e32 v71, 0x37800000, v70
	v_cndmask_b32_e32 v70, v70, v71, vcc
	v_cmp_class_f32_e32 vcc, v69, v234
	s_nop 1
	v_cndmask_b32_e32 v69, v70, v69, vcc
	v_div_scale_f32 v70, s[2:3], v69, v69, 1.0
	v_rcp_f32_e32 v71, v70
	s_nop 0
	v_fma_f32 v76, -v70, v71, 1.0
	v_fmac_f32_e32 v71, v76, v71
	v_div_scale_f32 v76, vcc, 1.0, v69, 1.0
	v_mul_f32_e32 v77, v76, v71
	v_fma_f32 v78, -v70, v77, v76
	v_fmac_f32_e32 v77, v78, v71
	v_fma_f32 v70, -v70, v77, v76
	v_div_fmas_f32 v70, v70, v71, v77
	v_div_fixup_f32 v156, v70, v69, 1.0
	ds_bpermute_b32 v69, v97, v68
	s_waitcnt lgkmcnt(0)
	v_add_f32_e32 v68, v68, v69
	ds_bpermute_b32 v69, v147, v68
	s_waitcnt lgkmcnt(0)
	v_add_f32_e32 v68, v68, v69
	ds_bpermute_b32 v69, v153, v68
	s_waitcnt lgkmcnt(0)
	v_add_f32_e32 v68, v68, v69
	ds_bpermute_b32 v69, v155, v68
	s_waitcnt lgkmcnt(0)
	v_add_f32_e32 v68, v68, v69
	ds_bpermute_b32 v69, v157, v68
	s_waitcnt lgkmcnt(0)
	v_add_f32_e32 v68, v68, v69
	ds_bpermute_b32 v69, v159, v68
	s_waitcnt lgkmcnt(0)
	v_add_f32_e32 v68, v68, v69
	v_fmamk_f32 v68, v68, 0x3a800000, v177
	v_cmp_gt_f32_e32 vcc, s53, v68
	v_mul_f32_e32 v69, 0x4f800000, v68
	s_nop 0
	v_cndmask_b32_e32 v68, v68, v69, vcc
	v_sqrt_f32_e32 v69, v68
	s_nop 0
	v_add_u32_e32 v70, -1, v69
	v_fma_f32 v71, -v70, v69, v68
	v_cmp_ge_f32_e64 s[4:5], 0, v71
	v_add_u32_e32 v71, 1, v69
	s_nop 0
	v_cndmask_b32_e64 v70, v69, v70, s[4:5]
	v_fma_f32 v69, -v71, v69, v68
	v_cmp_lt_f32_e64 s[4:5], 0, v69
	s_nop 1
	v_cndmask_b32_e64 v69, v70, v71, s[4:5]
	v_mul_f32_e32 v70, 0x37800000, v69
	v_cndmask_b32_e32 v69, v69, v70, vcc
	v_cmp_class_f32_e32 vcc, v68, v234
	s_nop 1
	v_cndmask_b32_e32 v68, v69, v68, vcc
	v_div_scale_f32 v69, s[2:3], v68, v68, 1.0
	v_rcp_f32_e32 v70, v69
	s_nop 0
	v_fma_f32 v71, -v69, v70, 1.0
	v_fmac_f32_e32 v70, v71, v70
	v_div_scale_f32 v71, vcc, 1.0, v68, 1.0
	v_mul_f32_e32 v76, v71, v70
	v_fma_f32 v77, -v69, v76, v71
	v_fmac_f32_e32 v76, v77, v70
	v_fma_f32 v69, -v69, v76, v71
	v_div_fmas_f32 v69, v69, v70, v76
	global_load_dwordx4 v[76:79], v[84:85], off
	v_add_co_u32_e32 v162, vcc, s79, v160
	v_div_fixup_f32 v158, v69, v68, 1.0
	s_nop 0
	v_addc_co_u32_e32 v163, vcc, 0, v161, vcc
	v_add_co_u32_e32 v164, vcc, s21, v160
	s_waitcnt vmcnt(0)
	v_pk_fma_f32 v[70:71], v[60:61], v[78:79], v[42:43]
	v_pk_fma_f32 v[68:69], v[62:63], v[76:77], v[40:41]
	v_pk_mul_f32 v[40:41], v[154:155], v[74:75] op_sel_hi:[0,1]
	v_pk_mul_f32 v[42:43], v[154:155], v[72:73] op_sel_hi:[0,1]
	v_pk_fma_f32 v[62:63], v[42:43], v[78:79], v[50:51]
	v_pk_fma_f32 v[60:61], v[40:41], v[76:77], v[48:49]
	v_addc_co_u32_e32 v165, vcc, 0, v161, vcc
	v_pk_mul_f32 v[40:41], v[156:157], v[144:145] op_sel_hi:[0,1]
	v_pk_mul_f32 v[42:43], v[156:157], v[142:143] op_sel_hi:[0,1]
	v_pk_fma_f32 v[74:75], v[78:79], v[42:43], v[54:55]
	v_pk_fma_f32 v[72:73], v[76:77], v[40:41], v[52:53]
	v_pk_mul_f32 v[40:41], v[158:159], v[150:151] op_sel_hi:[0,1]
	v_pk_mul_f32 v[42:43], v[158:159], v[148:149] op_sel_hi:[0,1]
	v_add_co_u32_e32 v142, vcc, s22, v160
	v_pk_fma_f32 v[54:55], v[78:79], v[42:43], v[66:67]
	v_pk_fma_f32 v[52:53], v[76:77], v[40:41], v[64:65]
	v_addc_co_u32_e32 v143, vcc, 0, v161, vcc
	global_store_dwordx4 v[160:161], v[68:71], off sc1
	global_store_dwordx4 v[164:165], v[60:63], off offset:-4096 sc1
	global_store_dwordx4 v[164:165], v[72:75], off sc1
	global_store_dwordx4 v[142:143], v[52:55], off sc1
	global_load_dwordx4 v[76:79], v[84:85], off offset:1024
	v_pk_mul_f32 v[40:41], v[152:153], v[104:105] op_sel_hi:[0,1]
	v_pk_mul_f32 v[42:43], v[152:153], v[102:103] op_sel_hi:[0,1]
	s_andn2_b64 vcc, exec, s[14:15]
	s_waitcnt vmcnt(0)
	v_pk_fma_f32 v[64:65], v[42:43], v[76:77], v[24:25]
	v_pk_fma_f32 v[66:67], v[40:41], v[78:79], v[26:27]
	v_pk_mul_f32 v[24:25], v[154:155], v[128:129] op_sel_hi:[0,1]
	v_pk_mul_f32 v[26:27], v[154:155], v[126:127] op_sel_hi:[0,1]
	v_pk_fma_f32 v[48:49], v[26:27], v[76:77], v[32:33]
	v_pk_fma_f32 v[50:51], v[24:25], v[78:79], v[34:35]
	v_pk_mul_f32 v[24:25], v[156:157], v[136:137] op_sel_hi:[0,1]
	v_pk_mul_f32 v[26:27], v[156:157], v[134:135] op_sel_hi:[0,1]
	v_pk_fma_f32 v[40:41], v[26:27], v[76:77], v[36:37]
	v_pk_fma_f32 v[42:43], v[24:25], v[78:79], v[38:39]
	v_pk_mul_f32 v[24:25], v[158:159], v[140:141] op_sel_hi:[0,1]
	v_pk_mul_f32 v[26:27], v[158:159], v[138:139] op_sel_hi:[0,1]
	v_pk_fma_f32 v[36:37], v[76:77], v[26:27], v[56:57]
	v_pk_fma_f32 v[38:39], v[78:79], v[24:25], v[58:59]
	global_store_dwordx4 v[160:161], v[64:67], off offset:1024 sc1
	global_store_dwordx4 v[162:163], v[48:51], off offset:1024 sc1
	global_store_dwordx4 v[164:165], v[40:43], off offset:1024 sc1
	global_store_dwordx4 v[142:143], v[36:39], off offset:1024 sc1
	global_load_dwordx4 v[56:59], v[84:85], off offset:2048
	v_pk_mul_f32 v[24:25], v[152:153], v[100:101] op_sel_hi:[0,1]
	v_pk_mul_f32 v[26:27], v[152:153], v[98:99] op_sel_hi:[0,1]
	s_waitcnt vmcnt(0)
	v_pk_fma_f32 v[32:33], v[26:27], v[56:57], v[12:13]
	v_pk_fma_f32 v[34:35], v[24:25], v[58:59], v[14:15]
	v_pk_mul_f32 v[12:13], v[154:155], v[116:117] op_sel_hi:[0,1]
	v_pk_mul_f32 v[14:15], v[154:155], v[114:115] op_sel_hi:[0,1]
	v_pk_fma_f32 v[24:25], v[14:15], v[56:57], v[16:17]
	v_pk_fma_f32 v[26:27], v[12:13], v[58:59], v[18:19]
	v_pk_mul_f32 v[12:13], v[156:157], v[124:125] op_sel_hi:[0,1]
	v_pk_mul_f32 v[14:15], v[156:157], v[122:123] op_sel_hi:[0,1]
	v_pk_fma_f32 v[20:21], v[14:15], v[56:57], v[20:21]
	v_pk_fma_f32 v[22:23], v[12:13], v[58:59], v[22:23]
	v_pk_mul_f32 v[12:13], v[158:159], v[132:133] op_sel_hi:[0,1]
	v_pk_mul_f32 v[14:15], v[158:159], v[130:131] op_sel_hi:[0,1]
	v_pk_fma_f32 v[16:17], v[14:15], v[56:57], v[44:45]
	v_pk_fma_f32 v[18:19], v[12:13], v[58:59], v[46:47]
	global_store_dwordx4 v[160:161], v[32:35], off offset:2048 sc1
	global_store_dwordx4 v[162:163], v[24:27], off offset:2048 sc1
	global_store_dwordx4 v[164:165], v[20:23], off offset:2048 sc1
	global_store_dwordx4 v[142:143], v[16:19], off offset:2048 sc1
	global_load_dwordx4 v[44:47], v[84:85], off offset:3072
	v_pk_mul_f32 v[14:15], v[152:153], v[94:95] op_sel_hi:[0,1]
	v_pk_mul_f32 v[12:13], v[152:153], v[92:93] op_sel_hi:[0,1]
	s_waitcnt vmcnt(0)
	v_pk_fma_f32 v[12:13], v[12:13], v[44:45], v[0:1]
	v_pk_fma_f32 v[14:15], v[14:15], v[46:47], v[2:3]
	v_pk_mul_f32 v[0:1], v[154:155], v[108:109] op_sel_hi:[0,1]
	v_pk_mul_f32 v[2:3], v[154:155], v[106:107] op_sel_hi:[0,1]
	v_pk_fma_f32 v[8:9], v[2:3], v[44:45], v[8:9]
	v_pk_fma_f32 v[10:11], v[0:1], v[46:47], v[10:11]
	v_pk_mul_f32 v[0:1], v[156:157], v[112:113] op_sel_hi:[0,1]
	v_pk_mul_f32 v[2:3], v[156:157], v[110:111] op_sel_hi:[0,1]
	v_pk_fma_f32 v[4:5], v[2:3], v[44:45], v[4:5]
	v_pk_fma_f32 v[6:7], v[0:1], v[46:47], v[6:7]
	v_pk_mul_f32 v[2:3], v[158:159], v[120:121] op_sel_hi:[0,1]
	v_pk_mul_f32 v[0:1], v[158:159], v[118:119] op_sel_hi:[0,1]
	v_pk_fma_f32 v[0:1], v[0:1], v[44:45], v[28:29]
	v_pk_fma_f32 v[2:3], v[2:3], v[46:47], v[30:31]
	global_store_dwordx4 v[160:161], v[12:15], off offset:3072 sc1
	global_store_dwordx4 v[162:163], v[8:11], off offset:3072 sc1
	global_store_dwordx4 v[164:165], v[4:7], off offset:3072 sc1
	global_store_dwordx4 v[142:143], v[0:3], off offset:3072 sc1
	s_cbranch_vccnz .LBB0_1437
	v_mul_f32_e32 v28, v53, v53
	v_mul_f32_e32 v29, v55, v55
	v_fmac_f32_e32 v28, v52, v52
	v_fmac_f32_e32 v29, v54, v54
	v_add_f32_e32 v28, v28, v29
	v_mul_f32_e32 v29, v37, v37
	v_mul_f32_e32 v30, v39, v39
	v_fmac_f32_e32 v29, v36, v36
	v_fmac_f32_e32 v30, v38, v38
	v_add_f32_e32 v29, v29, v30
	v_add_f32_e32 v28, v28, v29
	v_mul_f32_e32 v29, v17, v17
	v_mul_f32_e32 v30, v19, v19
	v_fmac_f32_e32 v29, v16, v16
	v_fmac_f32_e32 v30, v18, v18
	v_add_f32_e32 v29, v29, v30
	v_add_f32_e32 v28, v28, v29
	v_mul_f32_e32 v29, v1, v1
	v_mul_f32_e32 v30, v3, v3
	v_fmac_f32_e32 v29, v0, v0
	v_fmac_f32_e32 v30, v2, v2
	v_add_f32_e32 v29, v29, v30
	v_add_f32_e32 v28, v28, v29
	v_mul_f32_e32 v29, v73, v73
	v_mul_f32_e32 v30, v75, v75
	v_fmac_f32_e32 v29, v72, v72
	v_fmac_f32_e32 v30, v74, v74
	v_add_f32_e32 v29, v29, v30
	v_mul_f32_e32 v30, v41, v41
	v_mul_f32_e32 v31, v43, v43
	v_fmac_f32_e32 v30, v40, v40
	v_fmac_f32_e32 v31, v42, v42
	v_add_f32_e32 v30, v30, v31
	v_add_f32_e32 v29, v29, v30
	v_mul_f32_e32 v30, v21, v21
	v_mul_f32_e32 v31, v23, v23
	v_fmac_f32_e32 v30, v20, v20
	v_fmac_f32_e32 v31, v22, v22
	v_add_f32_e32 v30, v30, v31
	v_add_f32_e32 v29, v29, v30
	v_mul_f32_e32 v30, v5, v5
	v_mul_f32_e32 v31, v7, v7
	v_fmac_f32_e32 v30, v4, v4
	v_fmac_f32_e32 v31, v6, v6
	v_add_f32_e32 v30, v30, v31
	v_add_f32_e32 v29, v29, v30
	v_mul_f32_e32 v30, v61, v61
	v_mul_f32_e32 v31, v63, v63
	v_fmac_f32_e32 v30, v60, v60
	v_fmac_f32_e32 v31, v62, v62
	v_add_f32_e32 v30, v30, v31
	v_mul_f32_e32 v31, v49, v49
	v_mul_f32_e32 v44, v51, v51
	v_fmac_f32_e32 v31, v48, v48
	v_fmac_f32_e32 v44, v50, v50
	v_add_f32_e32 v31, v31, v44
	v_add_f32_e32 v30, v30, v31
	v_mul_f32_e32 v31, v25, v25
	v_mul_f32_e32 v44, v27, v27
	v_fmac_f32_e32 v31, v24, v24
	v_fmac_f32_e32 v44, v26, v26
	v_add_f32_e32 v31, v31, v44
	v_add_f32_e32 v30, v30, v31
	v_mul_f32_e32 v31, v9, v9
	v_mul_f32_e32 v44, v11, v11
	v_fmac_f32_e32 v31, v8, v8
	v_fmac_f32_e32 v44, v10, v10
	v_add_f32_e32 v31, v31, v44
	v_add_f32_e32 v30, v30, v31
	v_mul_f32_e32 v31, v69, v69
	v_mul_f32_e32 v44, v71, v71
	v_fmac_f32_e32 v31, v68, v68
	v_fmac_f32_e32 v44, v70, v70
	v_add_f32_e32 v31, v31, v44
	v_mul_f32_e32 v44, v65, v65
	v_mul_f32_e32 v45, v67, v67
	v_fmac_f32_e32 v44, v64, v64
	v_fmac_f32_e32 v45, v66, v66
	v_add_f32_e32 v44, v44, v45
	v_add_f32_e32 v31, v31, v44
	v_mul_f32_e32 v44, v33, v33
	v_mul_f32_e32 v45, v35, v35
	v_fmac_f32_e32 v44, v32, v32
	v_fmac_f32_e32 v45, v34, v34
	v_add_f32_e32 v44, v44, v45
	v_add_f32_e32 v31, v31, v44
	v_mul_f32_e32 v44, v13, v13
	v_mul_f32_e32 v45, v15, v15
	v_fmac_f32_e32 v44, v12, v12
	v_fmac_f32_e32 v45, v14, v14
	v_add_f32_e32 v44, v44, v45
	v_add_f32_e32 v31, v31, v44
	ds_bpermute_b32 v44, v97, v31
	s_lshl_b64 s[18:19], s[16:17], 10
	s_waitcnt lgkmcnt(0)
	v_add_f32_e32 v31, v31, v44
	ds_bpermute_b32 v44, v147, v31
	s_waitcnt lgkmcnt(0)
	v_add_f32_e32 v31, v31, v44
	ds_bpermute_b32 v44, v153, v31
	s_waitcnt lgkmcnt(0)
	v_add_f32_e32 v31, v31, v44
	ds_bpermute_b32 v44, v155, v31
	s_waitcnt lgkmcnt(0)
	v_add_f32_e32 v31, v31, v44
	ds_bpermute_b32 v44, v157, v31
	s_waitcnt lgkmcnt(0)
	v_add_f32_e32 v31, v31, v44
	ds_bpermute_b32 v44, v159, v31
	s_waitcnt lgkmcnt(0)
	v_add_f32_e32 v31, v31, v44
	v_fmamk_f32 v31, v31, 0x3a800000, v177
	v_cmp_gt_f32_e32 vcc, s53, v31
	v_mul_f32_e32 v44, 0x4f800000, v31
	s_nop 0
	v_cndmask_b32_e32 v31, v31, v44, vcc
	v_sqrt_f32_e32 v44, v31
	s_nop 0
	v_add_u32_e32 v45, -1, v44
	v_fma_f32 v46, -v45, v44, v31
	v_cmp_ge_f32_e64 s[4:5], 0, v46
	v_add_u32_e32 v46, 1, v44
	s_nop 0
	v_cndmask_b32_e64 v45, v44, v45, s[4:5]
	v_fma_f32 v44, -v46, v44, v31
	v_cmp_lt_f32_e64 s[4:5], 0, v44
	s_nop 1
	v_cndmask_b32_e64 v44, v45, v46, s[4:5]
	v_mul_f32_e32 v45, 0x37800000, v44
	v_cndmask_b32_e32 v44, v44, v45, vcc
	v_cmp_class_f32_e32 vcc, v31, v234
	s_nop 1
	v_cndmask_b32_e32 v31, v44, v31, vcc
	v_div_scale_f32 v44, s[2:3], v31, v31, 1.0
	v_rcp_f32_e32 v45, v44
	s_nop 0
	v_fma_f32 v46, -v44, v45, 1.0
	v_fmac_f32_e32 v45, v46, v45
	v_div_scale_f32 v46, vcc, 1.0, v31, 1.0
	v_mul_f32_e32 v47, v46, v45
	v_fma_f32 v56, -v44, v47, v46
	v_fmac_f32_e32 v47, v56, v45
	v_fma_f32 v44, -v44, v47, v46
	v_div_fmas_f32 v44, v44, v45, v47
	v_div_fixup_f32 v56, v44, v31, 1.0
	ds_bpermute_b32 v31, v97, v30
	v_mul_f32_e32 v32, v32, v56
	v_mul_f32_e32 v33, v33, v56
	v_mul_f32_e32 v12, v12, v56
	v_mul_f32_e32 v13, v13, v56
	s_waitcnt lgkmcnt(0)
	v_add_f32_e32 v30, v30, v31
	ds_bpermute_b32 v31, v147, v30
	s_waitcnt lgkmcnt(0)
	v_add_f32_e32 v30, v30, v31
	ds_bpermute_b32 v31, v153, v30
	s_waitcnt lgkmcnt(0)
	v_add_f32_e32 v30, v30, v31
	ds_bpermute_b32 v31, v155, v30
	s_waitcnt lgkmcnt(0)
	v_add_f32_e32 v30, v30, v31
	ds_bpermute_b32 v31, v157, v30
	s_waitcnt lgkmcnt(0)
	v_add_f32_e32 v30, v30, v31
	ds_bpermute_b32 v31, v159, v30
	s_waitcnt lgkmcnt(0)
	v_add_f32_e32 v30, v30, v31
	v_fmamk_f32 v30, v30, 0x3a800000, v177
	v_cmp_gt_f32_e32 vcc, s53, v30
	v_mul_f32_e32 v31, 0x4f800000, v30
	s_nop 0
	v_cndmask_b32_e32 v30, v30, v31, vcc
	v_sqrt_f32_e32 v31, v30
	s_nop 0
	v_add_u32_e32 v44, -1, v31
	v_fma_f32 v45, -v44, v31, v30
	v_cmp_ge_f32_e64 s[4:5], 0, v45
	v_add_u32_e32 v45, 1, v31
	s_nop 0
	v_cndmask_b32_e64 v44, v31, v44, s[4:5]
	v_fma_f32 v31, -v45, v31, v30
	v_cmp_lt_f32_e64 s[4:5], 0, v31
	s_nop 1
	v_cndmask_b32_e64 v31, v44, v45, s[4:5]
	v_mul_f32_e32 v44, 0x37800000, v31
	v_cndmask_b32_e32 v31, v31, v44, vcc
	v_cmp_class_f32_e32 vcc, v30, v234
	s_nop 1
	v_cndmask_b32_e32 v30, v31, v30, vcc
	v_div_scale_f32 v31, s[2:3], v30, v30, 1.0
	v_rcp_f32_e32 v44, v31
	s_nop 0
	v_fma_f32 v45, -v31, v44, 1.0
	v_fmac_f32_e32 v44, v45, v44
	v_div_scale_f32 v45, vcc, 1.0, v30, 1.0
	v_mul_f32_e32 v46, v45, v44
	v_fma_f32 v47, -v31, v46, v45
	v_fmac_f32_e32 v46, v47, v44
	v_fma_f32 v31, -v31, v46, v45
	v_div_fmas_f32 v31, v31, v44, v46
	v_div_fixup_f32 v57, v31, v30, 1.0
	ds_bpermute_b32 v30, v97, v29
	v_mul_f32_e32 v47, v69, v56
	v_mul_f32_e32 v48, v48, v57
	v_mul_f32_e32 v49, v49, v57
	v_mul_f32_e32 v24, v24, v57
	s_waitcnt lgkmcnt(0)
	v_add_f32_e32 v29, v29, v30
	ds_bpermute_b32 v30, v147, v29
	v_mul_f32_e32 v25, v25, v57
	v_mul_f32_e32 v8, v8, v57
	v_mul_f32_e32 v9, v9, v57
	s_waitcnt lgkmcnt(0)
	v_add_f32_e32 v29, v29, v30
	ds_bpermute_b32 v30, v153, v29
	s_waitcnt lgkmcnt(0)
	v_add_f32_e32 v29, v29, v30
	ds_bpermute_b32 v30, v155, v29
	s_waitcnt lgkmcnt(0)
	v_add_f32_e32 v29, v29, v30
	ds_bpermute_b32 v30, v157, v29
	s_waitcnt lgkmcnt(0)
	v_add_f32_e32 v29, v29, v30
	ds_bpermute_b32 v30, v159, v29
	s_waitcnt lgkmcnt(0)
	v_add_f32_e32 v29, v29, v30
	v_fmamk_f32 v29, v29, 0x3a800000, v177
	v_cmp_gt_f32_e32 vcc, s53, v29
	v_mul_f32_e32 v30, 0x4f800000, v29
	s_nop 0
	v_cndmask_b32_e32 v29, v29, v30, vcc
	v_sqrt_f32_e32 v30, v29
	s_nop 0
	v_add_u32_e32 v31, -1, v30
	v_fma_f32 v44, -v31, v30, v29
	v_cmp_ge_f32_e64 s[4:5], 0, v44
	v_add_u32_e32 v44, 1, v30
	s_nop 0
	v_cndmask_b32_e64 v31, v30, v31, s[4:5]
	v_fma_f32 v30, -v44, v30, v29
	v_cmp_lt_f32_e64 s[4:5], 0, v30
	s_nop 1
	v_cndmask_b32_e64 v30, v31, v44, s[4:5]
	v_mul_f32_e32 v31, 0x37800000, v30
	v_cndmask_b32_e32 v30, v30, v31, vcc
	v_cmp_class_f32_e32 vcc, v29, v234
	s_nop 1
	v_cndmask_b32_e32 v29, v30, v29, vcc
	v_div_scale_f32 v30, s[2:3], v29, v29, 1.0
	v_rcp_f32_e32 v31, v30
	s_nop 0
	v_fma_f32 v44, -v30, v31, 1.0
	v_fmac_f32_e32 v31, v44, v31
	v_div_scale_f32 v44, vcc, 1.0, v29, 1.0
	v_mul_f32_e32 v45, v44, v31
	v_fma_f32 v46, -v30, v45, v44
	v_fmac_f32_e32 v45, v46, v31
	v_fma_f32 v30, -v30, v45, v44
	v_div_fmas_f32 v30, v30, v31, v45
	v_div_fixup_f32 v58, v30, v29, 1.0
	ds_bpermute_b32 v29, v97, v28
	v_mul_f32_e32 v46, v68, v56
	v_mul_f32_e32 v40, v40, v58
	v_mul_f32_e32 v41, v41, v58
	v_mul_f32_e32 v20, v20, v58
	s_waitcnt lgkmcnt(0)
	v_add_f32_e32 v28, v28, v29
	ds_bpermute_b32 v29, v147, v28
	v_mul_f32_e32 v21, v21, v58
	v_mul_f32_e32 v4, v4, v58
	v_mul_f32_e32 v5, v5, v58
	s_waitcnt lgkmcnt(0)
	v_add_f32_e32 v28, v28, v29
	ds_bpermute_b32 v29, v153, v28
	s_waitcnt lgkmcnt(0)
	v_add_f32_e32 v28, v28, v29
	ds_bpermute_b32 v29, v155, v28
	s_waitcnt lgkmcnt(0)
	v_add_f32_e32 v28, v28, v29
	ds_bpermute_b32 v29, v157, v28
	s_waitcnt lgkmcnt(0)
	v_add_f32_e32 v28, v28, v29
	ds_bpermute_b32 v29, v159, v28
	s_waitcnt lgkmcnt(0)
	v_add_f32_e32 v28, v28, v29
	v_fmamk_f32 v28, v28, 0x3a800000, v177
	v_cmp_gt_f32_e32 vcc, s53, v28
	v_mul_f32_e32 v29, 0x4f800000, v28
	s_nop 0
	v_cndmask_b32_e32 v28, v28, v29, vcc
	v_sqrt_f32_e32 v29, v28
	s_nop 0
	v_add_u32_e32 v30, -1, v29
	v_fma_f32 v31, -v30, v29, v28
	v_cmp_ge_f32_e64 s[4:5], 0, v31
	v_add_u32_e32 v31, 1, v29
	s_nop 0
	v_cndmask_b32_e64 v30, v29, v30, s[4:5]
	v_fma_f32 v29, -v31, v29, v28
	v_cmp_lt_f32_e64 s[4:5], 0, v29
	s_nop 1
	v_cndmask_b32_e64 v29, v30, v31, s[4:5]
	v_mul_f32_e32 v30, 0x37800000, v29
	v_cndmask_b32_e32 v29, v29, v30, vcc
	v_cmp_class_f32_e32 vcc, v28, v234
	s_nop 1
	v_cndmask_b32_e32 v28, v29, v28, vcc
	v_div_scale_f32 v29, s[2:3], v28, v28, 1.0
	v_rcp_f32_e32 v30, v29
	s_nop 0
	v_fma_f32 v31, -v29, v30, 1.0
	v_fmac_f32_e32 v30, v31, v30
	v_div_scale_f32 v31, vcc, 1.0, v28, 1.0
	v_mul_f32_e32 v44, v31, v30
	v_fma_f32 v45, -v29, v44, v31
	v_fmac_f32_e32 v44, v45, v30
	v_fma_f32 v29, -v29, v44, v31
	v_div_fmas_f32 v29, v29, v30, v44
	v_div_fixup_f32 v59, v29, v28, 1.0
	global_load_dwordx4 v[28:31], v[88:89], off
	v_lshl_add_u64 v[44:45], s[18:19], 1, v[90:91]
	v_mul_f32_e32 v52, v52, v59
	v_mul_f32_e32 v36, v36, v59
	v_mul_f32_e32 v16, v16, v59
	v_mul_f32_e32 v17, v17, v59
	v_mul_f32_e32 v0, v0, v59
	v_mul_f32_e32 v1, v1, v59
	s_waitcnt vmcnt(0)
	v_mul_f32_e32 v46, v46, v28
	v_mul_f32_e32 v47, v47, v29
	v_bfe_u32 v68, v46, 16, 1
	v_add3_u32 v46, v46, v68, s36
	v_bfe_u32 v68, v47, 16, 1
	v_lshrrev_b32_e32 v46, 16, v46
	v_add3_u32 v47, v47, v68, s36
	v_and_or_b32 v46, v47, s68, v46
	v_mul_f32_e32 v47, v70, v56
	v_mul_f32_e32 v47, v47, v30
	v_mul_f32_e32 v68, v71, v56
	v_mul_f32_e32 v68, v68, v31
	v_bfe_u32 v69, v47, 16, 1
	v_add3_u32 v47, v47, v69, s36
	v_bfe_u32 v69, v68, 16, 1
	v_lshrrev_b32_e32 v47, 16, v47
	v_add3_u32 v68, v68, v69, s36
	v_and_or_b32 v47, v68, s68, v47
	global_store_dwordx2 v[44:45], v[46:47], off sc1
	v_mul_f32_e32 v46, v60, v57
	v_mul_f32_e32 v46, v46, v28
	v_mul_f32_e32 v47, v61, v57
	v_mul_f32_e32 v47, v47, v29
	v_bfe_u32 v60, v46, 16, 1
	v_add3_u32 v46, v46, v60, s36
	v_bfe_u32 v60, v47, 16, 1
	v_lshrrev_b32_e32 v46, 16, v46
	v_add3_u32 v47, v47, v60, s36
	v_and_or_b32 v46, v47, s68, v46
	v_mul_f32_e32 v47, v62, v57
	v_mul_f32_e32 v47, v47, v30
	v_mul_f32_e32 v60, v63, v57
	v_mul_f32_e32 v60, v60, v31
	v_bfe_u32 v61, v47, 16, 1
	v_add3_u32 v47, v47, v61, s36
	v_bfe_u32 v61, v60, 16, 1
	v_lshrrev_b32_e32 v47, 16, v47
	v_add3_u32 v60, v60, v61, s36
	v_and_or_b32 v47, v60, s68, v47
	global_store_dwordx2 v[44:45], v[46:47], off offset:2048 sc1
	v_mul_f32_e32 v46, v72, v58
	v_mul_f32_e32 v46, v46, v28
	v_mul_f32_e32 v47, v73, v58
	v_mul_f32_e32 v47, v47, v29
	v_bfe_u32 v60, v46, 16, 1
	v_mul_f32_e32 v28, v28, v52
	v_mul_f32_e32 v52, v53, v59
	v_add3_u32 v46, v46, v60, s36
	v_bfe_u32 v60, v47, 16, 1
	v_mul_f32_e32 v29, v29, v52
	v_bfe_u32 v52, v28, 16, 1
	v_lshrrev_b32_e32 v46, 16, v46
	v_add3_u32 v47, v47, v60, s36
	v_add3_u32 v28, v28, v52, s36
	v_bfe_u32 v52, v29, 16, 1
	v_and_or_b32 v60, v47, s68, v46
	v_mul_f32_e32 v46, v74, v58
	v_lshrrev_b32_e32 v28, 16, v28
	v_add3_u32 v29, v29, v52, s36
	v_mul_f32_e32 v46, v46, v30
	v_mul_f32_e32 v47, v75, v58
	v_and_or_b32 v28, v29, s68, v28
	v_mul_f32_e32 v29, v54, v59
	v_mul_f32_e32 v47, v47, v31
	v_bfe_u32 v61, v46, 16, 1
	v_mul_f32_e32 v29, v30, v29
	v_mul_f32_e32 v30, v55, v59
	v_add3_u32 v46, v46, v61, s36
	v_bfe_u32 v61, v47, 16, 1
	v_mul_f32_e32 v30, v31, v30
	v_bfe_u32 v31, v29, 16, 1
	v_lshrrev_b32_e32 v46, 16, v46
	v_add3_u32 v47, v47, v61, s36
	v_add3_u32 v29, v29, v31, s36
	v_bfe_u32 v31, v30, 16, 1
	v_and_or_b32 v61, v47, s68, v46
	v_add_co_u32_e32 v46, vcc, s79, v44
	v_lshrrev_b32_e32 v29, 16, v29
	v_add3_u32 v30, v30, v31, s36
	v_addc_co_u32_e32 v47, vcc, 0, v45, vcc
	v_and_or_b32 v29, v30, s68, v29
	global_store_dwordx2 v[46:47], v[60:61], off sc1
	global_store_dwordx2 v[46:47], v[28:29], off offset:2048 sc1
	global_load_dwordx4 v[28:31], v[88:89], off offset:1024
	v_mul_f32_e32 v52, v64, v56
	v_mul_f32_e32 v53, v65, v56
	s_waitcnt vmcnt(0)
	v_mul_f32_e32 v52, v52, v28
	v_mul_f32_e32 v53, v53, v29
	v_bfe_u32 v54, v52, 16, 1
	v_add3_u32 v52, v52, v54, s36
	v_bfe_u32 v54, v53, 16, 1
	v_lshrrev_b32_e32 v52, 16, v52
	v_add3_u32 v53, v53, v54, s36
	v_and_or_b32 v52, v53, s68, v52
	v_mul_f32_e32 v53, v66, v56
	v_mul_f32_e32 v53, v53, v30
	v_mul_f32_e32 v54, v67, v56
	v_mul_f32_e32 v54, v54, v31
	v_bfe_u32 v55, v53, 16, 1
	v_add3_u32 v53, v53, v55, s36
	v_bfe_u32 v55, v54, 16, 1
	v_lshrrev_b32_e32 v53, 16, v53
	v_add3_u32 v54, v54, v55, s36
	v_and_or_b32 v53, v54, s68, v53
	v_mul_f32_e32 v48, v48, v28
	global_store_dwordx2 v[44:45], v[52:53], off offset:512 sc1
	v_mul_f32_e32 v49, v49, v29
	v_bfe_u32 v52, v48, 16, 1
	v_add3_u32 v48, v48, v52, s36
	v_bfe_u32 v52, v49, 16, 1
	v_lshrrev_b32_e32 v48, 16, v48
	v_add3_u32 v49, v49, v52, s36
	v_and_or_b32 v48, v49, s68, v48
	v_mul_f32_e32 v49, v50, v57
	v_mul_f32_e32 v49, v49, v30
	v_mul_f32_e32 v50, v51, v57
	v_mul_f32_e32 v50, v50, v31
	v_bfe_u32 v51, v49, 16, 1
	v_add3_u32 v49, v49, v51, s36
	v_bfe_u32 v51, v50, 16, 1
	v_lshrrev_b32_e32 v49, 16, v49
	v_add3_u32 v50, v50, v51, s36
	v_and_or_b32 v49, v50, s68, v49
	v_mul_f32_e32 v40, v40, v28
	v_mul_f32_e32 v28, v28, v36
	v_mul_f32_e32 v36, v37, v59
	global_store_dwordx2 v[44:45], v[48:49], off offset:2560 sc1
	v_mul_f32_e32 v41, v41, v29
	v_bfe_u32 v48, v40, 16, 1
	v_mul_f32_e32 v29, v29, v36
	v_bfe_u32 v36, v28, 16, 1
	v_add3_u32 v40, v40, v48, s36
	v_bfe_u32 v48, v41, 16, 1
	v_add3_u32 v28, v28, v36, s36
	v_bfe_u32 v36, v29, 16, 1
	v_lshrrev_b32_e32 v40, 16, v40
	v_add3_u32 v41, v41, v48, s36
	v_lshrrev_b32_e32 v28, 16, v28
	v_add3_u32 v29, v29, v36, s36
	v_and_or_b32 v40, v41, s68, v40
	v_mul_f32_e32 v41, v42, v58
	v_and_or_b32 v28, v29, s68, v28
	v_mul_f32_e32 v29, v38, v59
	v_mul_f32_e32 v41, v41, v30
	v_mul_f32_e32 v42, v43, v58
	v_mul_f32_e32 v29, v30, v29
	v_mul_f32_e32 v30, v39, v59
	v_mul_f32_e32 v42, v42, v31
	v_bfe_u32 v43, v41, 16, 1
	v_mul_f32_e32 v30, v31, v30
	v_bfe_u32 v31, v29, 16, 1
	v_add3_u32 v41, v41, v43, s36
	v_bfe_u32 v43, v42, 16, 1
	v_add3_u32 v29, v29, v31, s36
	v_bfe_u32 v31, v30, 16, 1
	v_lshrrev_b32_e32 v41, 16, v41
	v_add3_u32 v42, v42, v43, s36
	v_lshrrev_b32_e32 v29, 16, v29
	v_add3_u32 v30, v30, v31, s36
	v_and_or_b32 v41, v42, s68, v41
	v_and_or_b32 v29, v30, s68, v29
	global_store_dwordx2 v[46:47], v[40:41], off offset:512 sc1
	global_store_dwordx2 v[46:47], v[28:29], off offset:2560 sc1
	global_load_dwordx4 v[28:31], v[88:89], off offset:2048
	s_waitcnt vmcnt(0)
	v_mul_f32_e32 v32, v32, v28
	v_mul_f32_e32 v33, v33, v29
	v_bfe_u32 v36, v32, 16, 1
	v_add3_u32 v32, v32, v36, s36
	v_bfe_u32 v36, v33, 16, 1
	v_lshrrev_b32_e32 v32, 16, v32
	v_add3_u32 v33, v33, v36, s36
	v_and_or_b32 v32, v33, s68, v32
	v_mul_f32_e32 v33, v34, v56
	v_mul_f32_e32 v33, v33, v30
	v_mul_f32_e32 v34, v35, v56
	v_mul_f32_e32 v34, v34, v31
	v_bfe_u32 v35, v33, 16, 1
	v_add3_u32 v33, v33, v35, s36
	v_bfe_u32 v35, v34, 16, 1
	v_lshrrev_b32_e32 v33, 16, v33
	v_add3_u32 v34, v34, v35, s36
	v_and_or_b32 v33, v34, s68, v33
	v_mul_f32_e32 v24, v24, v28
	global_store_dwordx2 v[44:45], v[32:33], off offset:1024 sc1
	v_mul_f32_e32 v25, v25, v29
	v_bfe_u32 v32, v24, 16, 1
	v_add3_u32 v24, v24, v32, s36
	v_bfe_u32 v32, v25, 16, 1
	v_lshrrev_b32_e32 v24, 16, v24
	v_add3_u32 v25, v25, v32, s36
	v_and_or_b32 v24, v25, s68, v24
	v_mul_f32_e32 v25, v26, v57
	v_mul_f32_e32 v25, v25, v30
	v_mul_f32_e32 v26, v27, v57
	v_mul_f32_e32 v26, v26, v31
	v_bfe_u32 v27, v25, 16, 1
	v_add3_u32 v25, v25, v27, s36
	v_bfe_u32 v27, v26, 16, 1
	v_lshrrev_b32_e32 v25, 16, v25
	v_add3_u32 v26, v26, v27, s36
	v_and_or_b32 v25, v26, s68, v25
	v_mul_f32_e32 v20, v20, v28
	global_store_dwordx2 v[44:45], v[24:25], off offset:3072 sc1
	v_mul_f32_e32 v21, v21, v29
	v_bfe_u32 v24, v20, 16, 1
	v_add3_u32 v20, v20, v24, s36
	v_bfe_u32 v24, v21, 16, 1
	v_lshrrev_b32_e32 v20, 16, v20
	v_add3_u32 v21, v21, v24, s36
	v_and_or_b32 v20, v21, s68, v20
	v_mul_f32_e32 v21, v22, v58
	v_mul_f32_e32 v21, v21, v30
	v_mul_f32_e32 v22, v23, v58
	v_mul_f32_e32 v22, v22, v31
	v_bfe_u32 v23, v21, 16, 1
	v_add3_u32 v21, v21, v23, s36
	v_bfe_u32 v23, v22, 16, 1
	v_lshrrev_b32_e32 v21, 16, v21
	v_add3_u32 v22, v22, v23, s36
	v_and_or_b32 v21, v22, s68, v21
	v_mul_f32_e32 v16, v16, v28
	global_store_dwordx2 v[46:47], v[20:21], off offset:1024 sc1
	v_mul_f32_e32 v17, v17, v29
	v_bfe_u32 v20, v16, 16, 1
	v_add3_u32 v16, v16, v20, s36
	v_bfe_u32 v20, v17, 16, 1
	v_lshrrev_b32_e32 v16, 16, v16
	v_add3_u32 v17, v17, v20, s36
	v_and_or_b32 v16, v17, s68, v16
	v_mul_f32_e32 v17, v18, v59
	v_mul_f32_e32 v17, v17, v30
	v_mul_f32_e32 v18, v19, v59
	v_mul_f32_e32 v18, v18, v31
	v_bfe_u32 v19, v17, 16, 1
	v_add3_u32 v17, v17, v19, s36
	v_bfe_u32 v19, v18, 16, 1
	v_lshrrev_b32_e32 v17, 16, v17
	v_add3_u32 v18, v18, v19, s36
	v_and_or_b32 v17, v18, s68, v17
	global_store_dwordx2 v[46:47], v[16:17], off offset:3072 sc1
	global_load_dwordx4 v[16:19], v[88:89], off offset:3072
	s_waitcnt vmcnt(0)
	v_mul_f32_e32 v12, v12, v16
	v_mul_f32_e32 v13, v13, v17
	v_bfe_u32 v20, v12, 16, 1
	v_add3_u32 v12, v12, v20, s36
	v_bfe_u32 v20, v13, 16, 1
	v_lshrrev_b32_e32 v12, 16, v12
	v_add3_u32 v13, v13, v20, s36
	v_and_or_b32 v12, v13, s68, v12
	v_mul_f32_e32 v13, v14, v56
	v_mul_f32_e32 v13, v13, v18
	v_mul_f32_e32 v14, v15, v56
	v_mul_f32_e32 v14, v14, v19
	v_bfe_u32 v15, v13, 16, 1
	v_add3_u32 v13, v13, v15, s36
	v_bfe_u32 v15, v14, 16, 1
	v_lshrrev_b32_e32 v13, 16, v13
	v_add3_u32 v14, v14, v15, s36
	v_and_or_b32 v13, v14, s68, v13
	v_mul_f32_e32 v8, v8, v16
	global_store_dwordx2 v[44:45], v[12:13], off offset:1536 sc1
	v_mul_f32_e32 v9, v9, v17
	v_bfe_u32 v12, v8, 16, 1
	v_add3_u32 v8, v8, v12, s36
	v_bfe_u32 v12, v9, 16, 1
	v_lshrrev_b32_e32 v8, 16, v8
	v_add3_u32 v9, v9, v12, s36
	v_and_or_b32 v8, v9, s68, v8
	v_mul_f32_e32 v9, v10, v57
	v_mul_f32_e32 v9, v9, v18
	v_mul_f32_e32 v10, v11, v57
	v_mul_f32_e32 v10, v10, v19
	v_bfe_u32 v11, v9, 16, 1
	v_add3_u32 v9, v9, v11, s36
	v_bfe_u32 v11, v10, 16, 1
	v_lshrrev_b32_e32 v9, 16, v9
	v_add3_u32 v10, v10, v11, s36
	v_and_or_b32 v9, v10, s68, v9
	v_mul_f32_e32 v4, v4, v16
	global_store_dwordx2 v[44:45], v[8:9], off offset:3584 sc1
	v_mul_f32_e32 v5, v5, v17
	v_bfe_u32 v8, v4, 16, 1
	v_add3_u32 v4, v4, v8, s36
	v_bfe_u32 v8, v5, 16, 1
	v_lshrrev_b32_e32 v4, 16, v4
	v_add3_u32 v5, v5, v8, s36
	v_and_or_b32 v4, v5, s68, v4
	v_mul_f32_e32 v5, v6, v58
	v_mul_f32_e32 v5, v5, v18
	v_mul_f32_e32 v6, v7, v58
	v_mul_f32_e32 v6, v6, v19
	v_bfe_u32 v7, v5, 16, 1
	v_add3_u32 v5, v5, v7, s36
	v_bfe_u32 v7, v6, 16, 1
	v_lshrrev_b32_e32 v5, 16, v5
	v_add3_u32 v6, v6, v7, s36
	v_and_or_b32 v5, v6, s68, v5
	v_mul_f32_e32 v0, v0, v16
	global_store_dwordx2 v[46:47], v[4:5], off offset:1536 sc1
	v_mul_f32_e32 v1, v1, v17
	v_bfe_u32 v4, v0, 16, 1
	v_add3_u32 v0, v0, v4, s36
	v_bfe_u32 v4, v1, 16, 1
	v_lshrrev_b32_e32 v0, 16, v0
	v_add3_u32 v1, v1, v4, s36
	v_and_or_b32 v0, v1, s68, v0
	v_mul_f32_e32 v1, v2, v59
	v_mul_f32_e32 v1, v1, v18
	v_mul_f32_e32 v2, v3, v59
	v_mul_f32_e32 v2, v2, v19
	v_bfe_u32 v3, v1, 16, 1
	v_add3_u32 v1, v1, v3, s36
	v_bfe_u32 v3, v2, 16, 1
	v_lshrrev_b32_e32 v1, 16, v1
	v_add3_u32 v2, v2, v3, s36
	v_and_or_b32 v1, v2, s68, v1
	global_store_dwordx2 v[46:47], v[0:1], off offset:3584 sc1
	s_branch .LBB0_1437

.LBB0_1848:
	s_ashr_i32 s19, s18, 31
	s_lshl_b64 s[2:3], s[18:19], 11
	s_lshl_b64 s[20:21], s[18:19], 12
	v_lshl_add_u64 v[4:5], v[82:83], 0, s[2:3]
	v_lshl_add_u64 v[28:29], v[84:85], 0, s[20:21]
	global_load_dwordx2 v[64:65], v[4:5], off
	global_load_dwordx4 v[40:43], v[28:29], off
	global_load_dwordx2 v[94:95], v[4:5], off offset:512
	global_load_dwordx4 v[20:23], v[28:29], off offset:1024
	global_load_dwordx2 v[78:79], v[4:5], off offset:1024
	global_load_dwordx4 v[12:15], v[28:29], off offset:2048
	global_load_dwordx2 v[76:77], v[4:5], off offset:1536
	global_load_dwordx4 v[0:3], v[28:29], off offset:3072
	global_load_dwordx2 v[74:75], v[4:5], off offset:2048
	v_add_co_u32_e32 v6, vcc, s79, v28
	s_movk_i32 s23, 0x2000
	s_nop 0
	v_addc_co_u32_e32 v7, vcc, 0, v29, vcc
	v_add_co_u32_e32 v30, vcc, s23, v28
	s_movk_i32 s24, 0x3000
	s_nop 0
	v_addc_co_u32_e32 v31, vcc, 0, v29, vcc
	global_load_dwordx4 v[48:51], v[30:31], off offset:-4096
	global_load_dwordx2 v[108:109], v[4:5], off offset:2560
	global_load_dwordx4 v[32:35], v[6:7], off offset:1024
	global_load_dwordx2 v[118:119], v[4:5], off offset:3072
	global_load_dwordx4 v[16:19], v[6:7], off offset:2048
	global_load_dwordx2 v[110:111], v[4:5], off offset:3584
	global_load_dwordx4 v[8:11], v[6:7], off offset:3072
	v_add_co_u32_e32 v66, vcc, s79, v4
	v_lshl_add_u64 v[162:163], v[92:93], 0, s[20:21]
	s_nop 0
	v_addc_co_u32_e32 v67, vcc, 0, v5, vcc
	global_load_dwordx2 v[114:115], v[66:67], off
	global_load_dwordx4 v[52:55], v[30:31], off
	global_load_dwordx2 v[112:113], v[66:67], off offset:512
	global_load_dwordx4 v[36:39], v[30:31], off offset:1024
	global_load_dwordx2 v[72:73], v[66:67], off offset:1024
	global_load_dwordx4 v[24:27], v[30:31], off offset:2048
	global_load_dwordx2 v[70:71], v[66:67], off offset:1536
	global_load_dwordx4 v[4:7], v[30:31], off offset:3072
	global_load_dwordx2 v[68:69], v[66:67], off offset:2048
	v_add_co_u32_e32 v28, vcc, s24, v28
	s_nop 1
	v_addc_co_u32_e32 v29, vcc, 0, v29, vcc
	global_load_dwordx4 v[60:63], v[28:29], off
	global_load_dwordx2 v[132:133], v[66:67], off offset:2560
	global_load_dwordx4 v[56:59], v[28:29], off offset:1024
	global_load_dwordx2 v[120:121], v[66:67], off offset:3072
	global_load_dwordx4 v[44:47], v[28:29], off offset:2048
	global_load_dwordx2 v[122:123], v[66:67], off offset:3584
	s_nop 0
	global_load_dwordx4 v[28:31], v[28:29], off offset:3072
	s_waitcnt vmcnt(7)
	v_and_b32_e32 v105, 0xffff0000, v94
	v_lshlrev_b32_e32 v66, 16, v64
	v_and_b32_e32 v67, 0xffff0000, v64
	v_lshlrev_b32_e32 v64, 16, v65
	v_and_b32_e32 v65, 0xffff0000, v65
	v_and_b32_e32 v107, 0xffff0000, v95
	v_mul_f32_e32 v98, v67, v67
	v_mul_f32_e32 v99, v65, v65
	v_lshlrev_b32_e32 v104, 16, v94
	v_lshlrev_b32_e32 v106, 16, v95
	v_mul_f32_e32 v94, v105, v105
	v_mul_f32_e32 v95, v107, v107
	v_and_b32_e32 v101, 0xffff0000, v78
	v_and_b32_e32 v103, 0xffff0000, v79
	v_fmac_f32_e32 v98, v66, v66
	v_fmac_f32_e32 v99, v64, v64
	v_fmac_f32_e32 v94, v104, v104
	v_fmac_f32_e32 v95, v106, v106
	v_lshlrev_b32_e32 v100, 16, v78
	v_lshlrev_b32_e32 v102, 16, v79
	v_mul_f32_e32 v78, v101, v101
	v_mul_f32_e32 v79, v103, v103
	v_add_f32_e32 v98, v98, v99
	v_add_f32_e32 v94, v94, v95
	v_fmac_f32_e32 v78, v100, v100
	v_fmac_f32_e32 v79, v102, v102
	v_add_f32_e32 v94, v98, v94
	v_add_f32_e32 v78, v78, v79
	v_and_b32_e32 v95, 0xffff0000, v76
	v_and_b32_e32 v99, 0xffff0000, v77
	v_add_f32_e32 v78, v94, v78
	v_lshlrev_b32_e32 v94, 16, v76
	v_lshlrev_b32_e32 v98, 16, v77
	v_mul_f32_e32 v76, v95, v95
	v_mul_f32_e32 v77, v99, v99
	v_fmac_f32_e32 v76, v94, v94
	v_fmac_f32_e32 v77, v98, v98
	v_add_f32_e32 v76, v76, v77
	v_and_b32_e32 v79, 0xffff0000, v74
	v_and_b32_e32 v77, 0xffff0000, v75
	v_add_f32_e32 v154, v78, v76
	v_lshlrev_b32_e32 v78, 16, v74
	v_lshlrev_b32_e32 v76, 16, v75
	v_mul_f32_e32 v74, v79, v79
	v_mul_f32_e32 v75, v77, v77
	v_fmac_f32_e32 v74, v78, v78
	v_fmac_f32_e32 v75, v76, v76
	v_and_b32_e32 v129, 0xffff0000, v108
	v_and_b32_e32 v131, 0xffff0000, v109
	v_add_f32_e32 v74, v74, v75
	v_lshlrev_b32_e32 v128, 16, v108
	v_lshlrev_b32_e32 v130, 16, v109
	v_mul_f32_e32 v75, v129, v129
	v_mul_f32_e32 v108, v131, v131
	v_fmac_f32_e32 v75, v128, v128
	v_fmac_f32_e32 v108, v130, v130
	v_add_f32_e32 v75, v75, v108
	v_lshlrev_b32_e32 v116, 16, v118
	v_and_b32_e32 v117, 0xffff0000, v118
	v_lshlrev_b32_e32 v118, 16, v119
	v_and_b32_e32 v119, 0xffff0000, v119
	v_add_f32_e32 v74, v74, v75
	v_mul_f32_e32 v75, v117, v117
	v_mul_f32_e32 v108, v119, v119
	v_fmac_f32_e32 v75, v116, v116
	v_fmac_f32_e32 v108, v118, v118
	v_add_f32_e32 v75, v75, v108
	v_lshlrev_b32_e32 v108, 16, v110
	v_and_b32_e32 v109, 0xffff0000, v110
	v_lshlrev_b32_e32 v110, 16, v111
	v_and_b32_e32 v111, 0xffff0000, v111
	v_add_f32_e32 v74, v74, v75
	v_mul_f32_e32 v75, v109, v109
	v_mul_f32_e32 v124, v111, v111
	v_fmac_f32_e32 v75, v108, v108
	v_fmac_f32_e32 v124, v110, v110
	v_add_f32_e32 v75, v75, v124
	v_and_b32_e32 v149, 0xffff0000, v114
	v_and_b32_e32 v145, 0xffff0000, v115
	v_and_b32_e32 v137, 0xffff0000, v112
	v_and_b32_e32 v139, 0xffff0000, v113
	v_add_f32_e32 v74, v74, v75
	v_lshlrev_b32_e32 v148, 16, v114
	v_lshlrev_b32_e32 v144, 16, v115
	v_mul_f32_e32 v75, v149, v149
	v_mul_f32_e32 v114, v145, v145
	v_lshlrev_b32_e32 v136, 16, v112
	v_lshlrev_b32_e32 v138, 16, v113
	v_mul_f32_e32 v112, v137, v137
	v_mul_f32_e32 v113, v139, v139
	v_fmac_f32_e32 v75, v148, v148
	v_fmac_f32_e32 v114, v144, v144
	v_fmac_f32_e32 v112, v136, v136
	v_fmac_f32_e32 v113, v138, v138
	v_add_f32_e32 v75, v75, v114
	v_add_f32_e32 v112, v112, v113
	v_and_b32_e32 v113, 0xffff0000, v70
	v_and_b32_e32 v115, 0xffff0000, v71
	v_and_b32_e32 v153, 0xffff0000, v68
	v_and_b32_e32 v151, 0xffff0000, v69
	v_add_f32_e32 v75, v75, v112
	v_lshlrev_b32_e32 v112, 16, v70
	v_lshlrev_b32_e32 v114, 16, v71
	v_mul_f32_e32 v70, v113, v113
	v_mul_f32_e32 v71, v115, v115
	v_lshlrev_b32_e32 v152, 16, v68
	v_lshlrev_b32_e32 v150, 16, v69
	v_mul_f32_e32 v68, v153, v153
	v_mul_f32_e32 v69, v151, v151
	v_fmac_f32_e32 v70, v112, v112
	v_fmac_f32_e32 v71, v114, v114
	v_fmac_f32_e32 v68, v152, v152
	v_fmac_f32_e32 v69, v150, v150
	s_waitcnt vmcnt(5)
	v_and_b32_e32 v141, 0xffff0000, v132
	v_and_b32_e32 v143, 0xffff0000, v133
	v_add_f32_e32 v70, v70, v71
	v_add_f32_e32 v68, v68, v69
	v_lshlrev_b32_e32 v140, 16, v132
	v_lshlrev_b32_e32 v142, 16, v133
	v_mul_f32_e32 v69, v141, v141
	v_mul_f32_e32 v71, v143, v143
	v_fmac_f32_e32 v69, v140, v140
	v_fmac_f32_e32 v71, v142, v142
	v_add_f32_e32 v69, v69, v71
	s_waitcnt vmcnt(3)
	v_and_b32_e32 v133, 0xffff0000, v120
	v_and_b32_e32 v135, 0xffff0000, v121
	v_add_f32_e32 v68, v68, v69
	v_lshlrev_b32_e32 v132, 16, v120
	v_lshlrev_b32_e32 v134, 16, v121
	v_mul_f32_e32 v69, v133, v133
	v_mul_f32_e32 v71, v135, v135
	v_fmac_f32_e32 v69, v132, v132
	v_fmac_f32_e32 v71, v134, v134
	v_add_f32_e32 v69, v69, v71
	s_waitcnt vmcnt(1)
	v_lshlrev_b32_e32 v120, 16, v122
	v_and_b32_e32 v121, 0xffff0000, v122
	v_lshlrev_b32_e32 v122, 16, v123
	v_and_b32_e32 v123, 0xffff0000, v123
	v_add_f32_e32 v68, v68, v69
	v_mul_f32_e32 v69, v121, v121
	v_mul_f32_e32 v71, v123, v123
	v_fmac_f32_e32 v69, v120, v120
	v_fmac_f32_e32 v71, v122, v122
	v_add_f32_e32 v69, v69, v71
	v_add_f32_e32 v68, v68, v69
	ds_bpermute_b32 v69, v97, v154
	v_and_b32_e32 v125, 0xffff0000, v72
	v_and_b32_e32 v127, 0xffff0000, v73
	v_lshlrev_b32_e32 v124, 16, v72
	v_lshlrev_b32_e32 v126, 16, v73
	s_waitcnt lgkmcnt(0)
	v_add_f32_e32 v69, v154, v69
	ds_bpermute_b32 v71, v147, v69
	v_mul_f32_e32 v72, v125, v125
	v_mul_f32_e32 v73, v127, v127
	v_fmac_f32_e32 v72, v124, v124
	v_fmac_f32_e32 v73, v126, v126
	s_waitcnt lgkmcnt(0)
	v_add_f32_e32 v69, v69, v71
	ds_bpermute_b32 v71, v155, v69
	v_add_f32_e32 v72, v72, v73
	v_add_f32_e32 v72, v75, v72
	v_add_f32_e32 v70, v72, v70
	s_waitcnt lgkmcnt(0)
	v_add_f32_e32 v69, v69, v71
	ds_bpermute_b32 v71, v157, v69
	s_waitcnt lgkmcnt(0)
	v_add_f32_e32 v69, v69, v71
	ds_bpermute_b32 v71, v159, v69
	s_waitcnt lgkmcnt(0)
	v_add_f32_e32 v69, v69, v71
	ds_bpermute_b32 v71, v161, v69
	s_waitcnt lgkmcnt(0)
	v_add_f32_e32 v69, v69, v71
	v_fmamk_f32 v69, v69, 0x3a800000, v177
	v_cmp_gt_f32_e32 vcc, s53, v69
	v_mul_f32_e32 v71, 0x4f800000, v69
	s_nop 0
	v_cndmask_b32_e32 v69, v69, v71, vcc
	v_sqrt_f32_e32 v71, v69
	s_nop 0
	v_add_u32_e32 v72, -1, v71
	v_fma_f32 v73, -v72, v71, v69
	v_cmp_ge_f32_e64 s[4:5], 0, v73
	v_add_u32_e32 v73, 1, v71
	s_nop 0
	v_cndmask_b32_e64 v72, v71, v72, s[4:5]
	v_fma_f32 v71, -v73, v71, v69
	v_cmp_lt_f32_e64 s[4:5], 0, v71
	s_nop 1
	v_cndmask_b32_e64 v71, v72, v73, s[4:5]
	v_mul_f32_e32 v72, 0x37800000, v71
	v_cndmask_b32_e32 v71, v71, v72, vcc
	v_cmp_class_f32_e32 vcc, v69, v234
	s_nop 1
	v_cndmask_b32_e32 v69, v71, v69, vcc
	v_div_scale_f32 v71, s[2:3], v69, v69, 1.0
	v_rcp_f32_e32 v72, v71
	s_nop 0
	v_fma_f32 v73, -v71, v72, 1.0
	v_fmac_f32_e32 v72, v73, v72
	v_div_scale_f32 v73, vcc, 1.0, v69, 1.0
	v_mul_f32_e32 v75, v73, v72
	v_fma_f32 v154, -v71, v75, v73
	v_fmac_f32_e32 v75, v154, v72
	v_fma_f32 v71, -v71, v75, v73
	v_div_fmas_f32 v71, v71, v72, v75
	v_div_fixup_f32 v154, v71, v69, 1.0
	ds_bpermute_b32 v69, v97, v74
	v_pk_mul_f32 v[66:67], v[154:155], v[66:67] op_sel_hi:[0,1]
	v_pk_mul_f32 v[64:65], v[154:155], v[64:65] op_sel_hi:[0,1]
	s_waitcnt lgkmcnt(0)
	v_add_f32_e32 v69, v74, v69
	ds_bpermute_b32 v71, v147, v69
	s_waitcnt lgkmcnt(0)
	v_add_f32_e32 v69, v69, v71
	ds_bpermute_b32 v71, v155, v69
	s_waitcnt lgkmcnt(0)
	v_add_f32_e32 v69, v69, v71
	ds_bpermute_b32 v71, v157, v69
	s_waitcnt lgkmcnt(0)
	v_add_f32_e32 v69, v69, v71
	ds_bpermute_b32 v71, v159, v69
	s_waitcnt lgkmcnt(0)
	v_add_f32_e32 v69, v69, v71
	ds_bpermute_b32 v71, v161, v69
	s_waitcnt lgkmcnt(0)
	v_add_f32_e32 v69, v69, v71
	v_fmamk_f32 v69, v69, 0x3a800000, v177
	v_cmp_gt_f32_e32 vcc, s53, v69
	v_mul_f32_e32 v71, 0x4f800000, v69
	s_nop 0
	v_cndmask_b32_e32 v69, v69, v71, vcc
	v_sqrt_f32_e32 v71, v69
	s_nop 0
	v_add_u32_e32 v72, -1, v71
	v_fma_f32 v73, -v72, v71, v69
	v_cmp_ge_f32_e64 s[4:5], 0, v73
	v_add_u32_e32 v73, 1, v71
	s_nop 0
	v_cndmask_b32_e64 v72, v71, v72, s[4:5]
	v_fma_f32 v71, -v73, v71, v69
	v_cmp_lt_f32_e64 s[4:5], 0, v71
	s_nop 1
	v_cndmask_b32_e64 v71, v72, v73, s[4:5]
	v_mul_f32_e32 v72, 0x37800000, v71
	v_cndmask_b32_e32 v71, v71, v72, vcc
	v_cmp_class_f32_e32 vcc, v69, v234
	s_nop 1
	v_cndmask_b32_e32 v69, v71, v69, vcc
	v_div_scale_f32 v71, s[2:3], v69, v69, 1.0
	v_rcp_f32_e32 v72, v71
	s_nop 0
	v_fma_f32 v73, -v71, v72, 1.0
	v_fmac_f32_e32 v72, v73, v72
	v_div_scale_f32 v73, vcc, 1.0, v69, 1.0
	v_mul_f32_e32 v74, v73, v72
	v_fma_f32 v75, -v71, v74, v73
	v_fmac_f32_e32 v74, v75, v72
	v_fma_f32 v71, -v71, v74, v73
	v_div_fmas_f32 v71, v71, v72, v74
	v_div_fixup_f32 v156, v71, v69, 1.0
	ds_bpermute_b32 v69, v97, v70
	s_waitcnt lgkmcnt(0)
	v_add_f32_e32 v69, v70, v69
	ds_bpermute_b32 v70, v147, v69
	s_waitcnt lgkmcnt(0)
	v_add_f32_e32 v69, v69, v70
	ds_bpermute_b32 v70, v155, v69
	s_waitcnt lgkmcnt(0)
	v_add_f32_e32 v69, v69, v70
	ds_bpermute_b32 v70, v157, v69
	s_waitcnt lgkmcnt(0)
	v_add_f32_e32 v69, v69, v70
	ds_bpermute_b32 v70, v159, v69
	s_waitcnt lgkmcnt(0)
	v_add_f32_e32 v69, v69, v70
	ds_bpermute_b32 v70, v161, v69
	s_waitcnt lgkmcnt(0)
	v_add_f32_e32 v69, v69, v70
	v_fmamk_f32 v69, v69, 0x3a800000, v177
	v_cmp_gt_f32_e32 vcc, s53, v69
	v_mul_f32_e32 v70, 0x4f800000, v69
	s_nop 0
	v_cndmask_b32_e32 v69, v69, v70, vcc
	v_sqrt_f32_e32 v70, v69
	s_nop 0
	v_add_u32_e32 v71, -1, v70
	v_fma_f32 v72, -v71, v70, v69
	v_cmp_ge_f32_e64 s[4:5], 0, v72
	v_add_u32_e32 v72, 1, v70
	s_nop 0
	v_cndmask_b32_e64 v71, v70, v71, s[4:5]
	v_fma_f32 v70, -v72, v70, v69
	v_cmp_lt_f32_e64 s[4:5], 0, v70
	s_nop 1
	v_cndmask_b32_e64 v70, v71, v72, s[4:5]
	v_mul_f32_e32 v71, 0x37800000, v70
	v_cndmask_b32_e32 v70, v70, v71, vcc
	v_cmp_class_f32_e32 vcc, v69, v234
	s_nop 1
	v_cndmask_b32_e32 v69, v70, v69, vcc
	v_div_scale_f32 v70, s[2:3], v69, v69, 1.0
	v_rcp_f32_e32 v71, v70
	s_nop 0
	v_fma_f32 v72, -v70, v71, 1.0
	v_fmac_f32_e32 v71, v72, v71
	v_div_scale_f32 v72, vcc, 1.0, v69, 1.0
	v_mul_f32_e32 v73, v72, v71
	v_fma_f32 v74, -v70, v73, v72
	v_fmac_f32_e32 v73, v74, v71
	v_fma_f32 v70, -v70, v73, v72
	v_div_fmas_f32 v70, v70, v71, v73
	v_div_fixup_f32 v158, v70, v69, 1.0
	ds_bpermute_b32 v69, v97, v68
	s_waitcnt lgkmcnt(0)
	v_add_f32_e32 v68, v68, v69
	ds_bpermute_b32 v69, v147, v68
	s_waitcnt lgkmcnt(0)
	v_add_f32_e32 v68, v68, v69
	ds_bpermute_b32 v69, v155, v68
	s_waitcnt lgkmcnt(0)
	v_add_f32_e32 v68, v68, v69
	ds_bpermute_b32 v69, v157, v68
	s_waitcnt lgkmcnt(0)
	v_add_f32_e32 v68, v68, v69
	ds_bpermute_b32 v69, v159, v68
	s_waitcnt lgkmcnt(0)
	v_add_f32_e32 v68, v68, v69
	ds_bpermute_b32 v69, v161, v68
	s_waitcnt lgkmcnt(0)
	v_add_f32_e32 v68, v68, v69
	v_fmamk_f32 v68, v68, 0x3a800000, v177
	v_cmp_gt_f32_e32 vcc, s53, v68
	v_mul_f32_e32 v69, 0x4f800000, v68
	s_nop 0
	v_cndmask_b32_e32 v68, v68, v69, vcc
	v_sqrt_f32_e32 v69, v68
	s_nop 0
	v_add_u32_e32 v70, -1, v69
	v_fma_f32 v71, -v70, v69, v68
	v_cmp_ge_f32_e64 s[4:5], 0, v71
	v_add_u32_e32 v71, 1, v69
	s_nop 0
	v_cndmask_b32_e64 v70, v69, v70, s[4:5]
	v_fma_f32 v69, -v71, v69, v68
	v_cmp_lt_f32_e64 s[4:5], 0, v69
	s_nop 1
	v_cndmask_b32_e64 v69, v70, v71, s[4:5]
	v_mul_f32_e32 v70, 0x37800000, v69
	v_cndmask_b32_e32 v69, v69, v70, vcc
	v_cmp_class_f32_e32 vcc, v68, v234
	s_nop 1
	v_cndmask_b32_e32 v68, v69, v68, vcc
	v_div_scale_f32 v69, s[2:3], v68, v68, 1.0
	v_rcp_f32_e32 v70, v69
	s_nop 0
	v_fma_f32 v71, -v69, v70, 1.0
	v_fmac_f32_e32 v70, v71, v70
	v_div_scale_f32 v71, vcc, 1.0, v68, 1.0
	v_mul_f32_e32 v72, v71, v70
	v_fma_f32 v73, -v69, v72, v71
	v_fmac_f32_e32 v72, v73, v70
	v_fma_f32 v69, -v69, v72, v71
	v_div_fmas_f32 v69, v69, v70, v72
	v_div_fixup_f32 v160, v69, v68, 1.0
	global_load_dwordx4 v[68:71], v[86:87], off
	v_add_co_u32_e32 v164, vcc, s79, v162
	s_waitcnt vmcnt(0)
	v_pk_fma_f32 v[74:75], v[64:65], v[70:71], v[42:43]
	v_addc_co_u32_e32 v165, vcc, 0, v163, vcc
	v_pk_fma_f32 v[72:73], v[66:67], v[68:69], v[40:41]
	v_pk_mul_f32 v[40:41], v[156:157], v[78:79] op_sel_hi:[0,1]
	v_pk_mul_f32 v[42:43], v[156:157], v[76:77] op_sel_hi:[0,1]
	v_add_co_u32_e32 v166, vcc, s23, v162
	v_pk_fma_f32 v[66:67], v[42:43], v[70:71], v[50:51]
	v_pk_fma_f32 v[64:65], v[40:41], v[68:69], v[48:49]
	v_addc_co_u32_e32 v167, vcc, 0, v163, vcc
	v_pk_mul_f32 v[40:41], v[158:159], v[148:149] op_sel_hi:[0,1]
	v_pk_mul_f32 v[42:43], v[158:159], v[144:145] op_sel_hi:[0,1]
	v_pk_fma_f32 v[78:79], v[70:71], v[42:43], v[54:55]
	v_pk_fma_f32 v[76:77], v[68:69], v[40:41], v[52:53]
	v_pk_mul_f32 v[40:41], v[160:161], v[152:153] op_sel_hi:[0,1]
	v_pk_mul_f32 v[42:43], v[160:161], v[150:151] op_sel_hi:[0,1]
	v_add_co_u32_e32 v144, vcc, s24, v162
	v_pk_fma_f32 v[62:63], v[70:71], v[42:43], v[62:63]
	v_pk_fma_f32 v[60:61], v[68:69], v[40:41], v[60:61]
	v_addc_co_u32_e32 v145, vcc, 0, v163, vcc
	global_store_dwordx4 v[162:163], v[72:75], off sc1
	global_store_dwordx4 v[166:167], v[64:67], off offset:-4096 sc1
	global_store_dwordx4 v[166:167], v[76:79], off sc1
	global_store_dwordx4 v[144:145], v[60:63], off sc1
	global_load_dwordx4 v[40:43], v[86:87], off offset:1024
	v_pk_mul_f32 v[48:49], v[154:155], v[106:107] op_sel_hi:[0,1]
	v_pk_mul_f32 v[50:51], v[154:155], v[104:105] op_sel_hi:[0,1]
	s_andn2_b64 vcc, exec, s[16:17]
	s_waitcnt vmcnt(0)
	v_pk_fma_f32 v[68:69], v[50:51], v[40:41], v[20:21]
	v_pk_fma_f32 v[70:71], v[48:49], v[42:43], v[22:23]
	v_pk_mul_f32 v[20:21], v[156:157], v[130:131] op_sel_hi:[0,1]
	v_pk_mul_f32 v[22:23], v[156:157], v[128:129] op_sel_hi:[0,1]
	v_pk_fma_f32 v[52:53], v[22:23], v[40:41], v[32:33]
	v_pk_fma_f32 v[54:55], v[20:21], v[42:43], v[34:35]
	v_pk_mul_f32 v[20:21], v[158:159], v[138:139] op_sel_hi:[0,1]
	v_pk_mul_f32 v[22:23], v[158:159], v[136:137] op_sel_hi:[0,1]
	v_pk_fma_f32 v[48:49], v[22:23], v[40:41], v[36:37]
	v_pk_fma_f32 v[50:51], v[20:21], v[42:43], v[38:39]
	v_pk_mul_f32 v[20:21], v[160:161], v[142:143] op_sel_hi:[0,1]
	v_pk_mul_f32 v[22:23], v[160:161], v[140:141] op_sel_hi:[0,1]
	v_pk_fma_f32 v[40:41], v[40:41], v[22:23], v[56:57]
	v_pk_fma_f32 v[42:43], v[42:43], v[20:21], v[58:59]
	global_store_dwordx4 v[162:163], v[68:71], off offset:1024 sc1
	global_store_dwordx4 v[164:165], v[52:55], off offset:1024 sc1
	global_store_dwordx4 v[166:167], v[48:51], off offset:1024 sc1
	global_store_dwordx4 v[144:145], v[40:43], off offset:1024 sc1
	global_load_dwordx4 v[56:59], v[86:87], off offset:2048
	v_pk_mul_f32 v[20:21], v[154:155], v[102:103] op_sel_hi:[0,1]
	v_pk_mul_f32 v[22:23], v[154:155], v[100:101] op_sel_hi:[0,1]
	s_waitcnt vmcnt(0)
	v_pk_fma_f32 v[36:37], v[22:23], v[56:57], v[12:13]
	v_pk_fma_f32 v[38:39], v[20:21], v[58:59], v[14:15]
	v_pk_mul_f32 v[12:13], v[156:157], v[118:119] op_sel_hi:[0,1]
	v_pk_mul_f32 v[14:15], v[156:157], v[116:117] op_sel_hi:[0,1]
	v_pk_fma_f32 v[32:33], v[14:15], v[56:57], v[16:17]
	v_pk_fma_f32 v[34:35], v[12:13], v[58:59], v[18:19]
	v_pk_mul_f32 v[12:13], v[158:159], v[126:127] op_sel_hi:[0,1]
	v_pk_mul_f32 v[14:15], v[158:159], v[124:125] op_sel_hi:[0,1]
	v_pk_fma_f32 v[20:21], v[14:15], v[56:57], v[24:25]
	v_pk_fma_f32 v[22:23], v[12:13], v[58:59], v[26:27]
	v_pk_mul_f32 v[12:13], v[160:161], v[134:135] op_sel_hi:[0,1]
	v_pk_mul_f32 v[14:15], v[160:161], v[132:133] op_sel_hi:[0,1]
	v_pk_fma_f32 v[16:17], v[14:15], v[56:57], v[44:45]
	v_pk_fma_f32 v[18:19], v[12:13], v[58:59], v[46:47]
	global_store_dwordx4 v[162:163], v[36:39], off offset:2048 sc1
	global_store_dwordx4 v[164:165], v[32:35], off offset:2048 sc1
	global_store_dwordx4 v[166:167], v[20:23], off offset:2048 sc1
	global_store_dwordx4 v[144:145], v[16:19], off offset:2048 sc1
	global_load_dwordx4 v[24:27], v[86:87], off offset:3072
	v_pk_mul_f32 v[14:15], v[154:155], v[98:99] op_sel_hi:[0,1]
	v_pk_mul_f32 v[12:13], v[154:155], v[94:95] op_sel_hi:[0,1]
	s_waitcnt vmcnt(0)
	v_pk_fma_f32 v[12:13], v[12:13], v[24:25], v[0:1]
	v_pk_fma_f32 v[14:15], v[14:15], v[26:27], v[2:3]
	v_pk_mul_f32 v[0:1], v[156:157], v[110:111] op_sel_hi:[0,1]
	v_pk_mul_f32 v[2:3], v[156:157], v[108:109] op_sel_hi:[0,1]
	v_pk_fma_f32 v[8:9], v[2:3], v[24:25], v[8:9]
	v_pk_fma_f32 v[10:11], v[0:1], v[26:27], v[10:11]
	v_pk_mul_f32 v[0:1], v[158:159], v[114:115] op_sel_hi:[0,1]
	v_pk_mul_f32 v[2:3], v[158:159], v[112:113] op_sel_hi:[0,1]
	v_pk_fma_f32 v[4:5], v[2:3], v[24:25], v[4:5]
	v_pk_fma_f32 v[6:7], v[0:1], v[26:27], v[6:7]
	v_pk_mul_f32 v[2:3], v[160:161], v[122:123] op_sel_hi:[0,1]
	v_pk_mul_f32 v[0:1], v[160:161], v[120:121] op_sel_hi:[0,1]
	v_pk_fma_f32 v[0:1], v[0:1], v[24:25], v[28:29]
	v_pk_fma_f32 v[2:3], v[2:3], v[26:27], v[30:31]
	global_store_dwordx4 v[162:163], v[12:15], off offset:3072 sc1
	global_store_dwordx4 v[164:165], v[8:11], off offset:3072 sc1
	global_store_dwordx4 v[166:167], v[4:7], off offset:3072 sc1
	global_store_dwordx4 v[144:145], v[0:3], off offset:3072 sc1
	s_cbranch_vccnz .LBB0_1847
	v_mul_f32_e32 v24, v61, v61
	v_mul_f32_e32 v25, v63, v63
	v_fmac_f32_e32 v24, v60, v60
	v_fmac_f32_e32 v25, v62, v62
	v_add_f32_e32 v24, v24, v25
	v_mul_f32_e32 v25, v41, v41
	v_mul_f32_e32 v26, v43, v43
	v_fmac_f32_e32 v25, v40, v40
	v_fmac_f32_e32 v26, v42, v42
	v_add_f32_e32 v25, v25, v26
	v_add_f32_e32 v24, v24, v25
	v_mul_f32_e32 v25, v17, v17
	v_mul_f32_e32 v26, v19, v19
	v_fmac_f32_e32 v25, v16, v16
	v_fmac_f32_e32 v26, v18, v18
	v_add_f32_e32 v25, v25, v26
	v_add_f32_e32 v24, v24, v25
	v_mul_f32_e32 v25, v1, v1
	v_mul_f32_e32 v26, v3, v3
	v_fmac_f32_e32 v25, v0, v0
	v_fmac_f32_e32 v26, v2, v2
	v_add_f32_e32 v25, v25, v26
	v_add_f32_e32 v24, v24, v25
	v_mul_f32_e32 v25, v77, v77
	v_mul_f32_e32 v26, v79, v79
	v_fmac_f32_e32 v25, v76, v76
	v_fmac_f32_e32 v26, v78, v78
	v_add_f32_e32 v25, v25, v26
	v_mul_f32_e32 v26, v49, v49
	v_mul_f32_e32 v27, v51, v51
	v_fmac_f32_e32 v26, v48, v48
	v_fmac_f32_e32 v27, v50, v50
	v_add_f32_e32 v26, v26, v27
	v_add_f32_e32 v25, v25, v26
	v_mul_f32_e32 v26, v21, v21
	v_mul_f32_e32 v27, v23, v23
	v_fmac_f32_e32 v26, v20, v20
	v_fmac_f32_e32 v27, v22, v22
	v_add_f32_e32 v26, v26, v27
	v_add_f32_e32 v25, v25, v26
	v_mul_f32_e32 v26, v5, v5
	v_mul_f32_e32 v27, v7, v7
	v_fmac_f32_e32 v26, v4, v4
	v_fmac_f32_e32 v27, v6, v6
	v_add_f32_e32 v26, v26, v27
	v_add_f32_e32 v25, v25, v26
	v_mul_f32_e32 v26, v65, v65
	v_mul_f32_e32 v27, v67, v67
	v_fmac_f32_e32 v26, v64, v64
	v_fmac_f32_e32 v27, v66, v66
	v_add_f32_e32 v26, v26, v27
	v_mul_f32_e32 v27, v53, v53
	v_mul_f32_e32 v28, v55, v55
	v_fmac_f32_e32 v27, v52, v52
	v_fmac_f32_e32 v28, v54, v54
	v_add_f32_e32 v27, v27, v28
	v_add_f32_e32 v26, v26, v27
	v_mul_f32_e32 v27, v33, v33
	v_mul_f32_e32 v28, v35, v35
	v_fmac_f32_e32 v27, v32, v32
	v_fmac_f32_e32 v28, v34, v34
	v_add_f32_e32 v27, v27, v28
	v_add_f32_e32 v26, v26, v27
	v_mul_f32_e32 v27, v9, v9
	v_mul_f32_e32 v28, v11, v11
	v_fmac_f32_e32 v27, v8, v8
	v_fmac_f32_e32 v28, v10, v10
	v_add_f32_e32 v27, v27, v28
	v_add_f32_e32 v26, v26, v27
	v_mul_f32_e32 v27, v73, v73
	v_mul_f32_e32 v28, v75, v75
	v_fmac_f32_e32 v27, v72, v72
	v_fmac_f32_e32 v28, v74, v74
	v_add_f32_e32 v27, v27, v28
	v_mul_f32_e32 v28, v69, v69
	v_mul_f32_e32 v29, v71, v71
	v_fmac_f32_e32 v28, v68, v68
	v_fmac_f32_e32 v29, v70, v70
	v_add_f32_e32 v28, v28, v29
	v_add_f32_e32 v27, v27, v28
	v_mul_f32_e32 v28, v37, v37
	v_mul_f32_e32 v29, v39, v39
	v_fmac_f32_e32 v28, v36, v36
	v_fmac_f32_e32 v29, v38, v38
	v_add_f32_e32 v28, v28, v29
	v_add_f32_e32 v27, v27, v28
	v_mul_f32_e32 v28, v13, v13
	v_mul_f32_e32 v29, v15, v15
	v_fmac_f32_e32 v28, v12, v12
	v_fmac_f32_e32 v29, v14, v14
	v_add_f32_e32 v28, v28, v29
	v_add_f32_e32 v27, v27, v28
	ds_bpermute_b32 v28, v97, v27
	s_lshl_b64 s[20:21], s[18:19], 10
	s_waitcnt lgkmcnt(0)
	v_add_f32_e32 v27, v27, v28
	ds_bpermute_b32 v28, v147, v27
	s_waitcnt lgkmcnt(0)
	v_add_f32_e32 v27, v27, v28
	ds_bpermute_b32 v28, v155, v27
	s_waitcnt lgkmcnt(0)
	v_add_f32_e32 v27, v27, v28
	ds_bpermute_b32 v28, v157, v27
	s_waitcnt lgkmcnt(0)
	v_add_f32_e32 v27, v27, v28
	ds_bpermute_b32 v28, v159, v27
	s_waitcnt lgkmcnt(0)
	v_add_f32_e32 v27, v27, v28
	ds_bpermute_b32 v28, v161, v27
	s_waitcnt lgkmcnt(0)
	v_add_f32_e32 v27, v27, v28
	v_fmamk_f32 v27, v27, 0x3a800000, v177
	v_cmp_gt_f32_e32 vcc, s53, v27
	v_mul_f32_e32 v28, 0x4f800000, v27
	s_nop 0
	v_cndmask_b32_e32 v27, v27, v28, vcc
	v_sqrt_f32_e32 v28, v27
	s_nop 0
	v_add_u32_e32 v29, -1, v28
	v_fma_f32 v30, -v29, v28, v27
	v_cmp_ge_f32_e64 s[4:5], 0, v30
	v_add_u32_e32 v30, 1, v28
	s_nop 0
	v_cndmask_b32_e64 v29, v28, v29, s[4:5]
	v_fma_f32 v28, -v30, v28, v27
	v_cmp_lt_f32_e64 s[4:5], 0, v28
	s_nop 1
	v_cndmask_b32_e64 v28, v29, v30, s[4:5]
	v_mul_f32_e32 v29, 0x37800000, v28
	v_cndmask_b32_e32 v28, v28, v29, vcc
	v_cmp_class_f32_e32 vcc, v27, v234
	s_nop 1
	v_cndmask_b32_e32 v27, v28, v27, vcc
	v_div_scale_f32 v28, s[2:3], v27, v27, 1.0
	v_rcp_f32_e32 v29, v28
	s_nop 0
	v_fma_f32 v30, -v28, v29, 1.0
	v_fmac_f32_e32 v29, v30, v29
	v_div_scale_f32 v30, vcc, 1.0, v27, 1.0
	v_mul_f32_e32 v31, v30, v29
	v_fma_f32 v44, -v28, v31, v30
	v_fmac_f32_e32 v31, v44, v29
	v_fma_f32 v28, -v28, v31, v30
	v_div_fmas_f32 v28, v28, v29, v31
	v_div_fixup_f32 v44, v28, v27, 1.0
	ds_bpermute_b32 v27, v97, v26
	v_mul_f32_e32 v36, v36, v44
	v_mul_f32_e32 v37, v37, v44
	v_mul_f32_e32 v12, v12, v44
	v_mul_f32_e32 v13, v13, v44
	s_waitcnt lgkmcnt(0)
	v_add_f32_e32 v26, v26, v27
	ds_bpermute_b32 v27, v147, v26
	s_waitcnt lgkmcnt(0)
	v_add_f32_e32 v26, v26, v27
	ds_bpermute_b32 v27, v155, v26
	s_waitcnt lgkmcnt(0)
	v_add_f32_e32 v26, v26, v27
	ds_bpermute_b32 v27, v157, v26
	s_waitcnt lgkmcnt(0)
	v_add_f32_e32 v26, v26, v27
	ds_bpermute_b32 v27, v159, v26
	s_waitcnt lgkmcnt(0)
	v_add_f32_e32 v26, v26, v27
	ds_bpermute_b32 v27, v161, v26
	s_waitcnt lgkmcnt(0)
	v_add_f32_e32 v26, v26, v27
	v_fmamk_f32 v26, v26, 0x3a800000, v177
	v_cmp_gt_f32_e32 vcc, s53, v26
	v_mul_f32_e32 v27, 0x4f800000, v26
	s_nop 0
	v_cndmask_b32_e32 v26, v26, v27, vcc
	v_sqrt_f32_e32 v27, v26
	s_nop 0
	v_add_u32_e32 v28, -1, v27
	v_fma_f32 v29, -v28, v27, v26
	v_cmp_ge_f32_e64 s[4:5], 0, v29
	v_add_u32_e32 v29, 1, v27
	s_nop 0
	v_cndmask_b32_e64 v28, v27, v28, s[4:5]
	v_fma_f32 v27, -v29, v27, v26
	v_cmp_lt_f32_e64 s[4:5], 0, v27
	s_nop 1
	v_cndmask_b32_e64 v27, v28, v29, s[4:5]
	v_mul_f32_e32 v28, 0x37800000, v27
	v_cndmask_b32_e32 v27, v27, v28, vcc
	v_cmp_class_f32_e32 vcc, v26, v234
	s_nop 1
	v_cndmask_b32_e32 v26, v27, v26, vcc
	v_div_scale_f32 v27, s[2:3], v26, v26, 1.0
	v_rcp_f32_e32 v28, v27
	s_nop 0
	v_fma_f32 v29, -v27, v28, 1.0
	v_fmac_f32_e32 v28, v29, v28
	v_div_scale_f32 v29, vcc, 1.0, v26, 1.0
	v_mul_f32_e32 v30, v29, v28
	v_fma_f32 v31, -v27, v30, v29
	v_fmac_f32_e32 v30, v31, v28
	v_fma_f32 v27, -v27, v30, v29
	v_div_fmas_f32 v27, v27, v28, v30
	v_div_fixup_f32 v45, v27, v26, 1.0
	ds_bpermute_b32 v26, v97, v25
	v_mul_f32_e32 v31, v73, v44
	v_mul_f32_e32 v52, v52, v45
	v_mul_f32_e32 v53, v53, v45
	v_mul_f32_e32 v32, v32, v45
	s_waitcnt lgkmcnt(0)
	v_add_f32_e32 v25, v25, v26
	ds_bpermute_b32 v26, v147, v25
	v_mul_f32_e32 v33, v33, v45
	v_mul_f32_e32 v8, v8, v45
	v_mul_f32_e32 v9, v9, v45
	s_waitcnt lgkmcnt(0)
	v_add_f32_e32 v25, v25, v26
	ds_bpermute_b32 v26, v155, v25
	s_waitcnt lgkmcnt(0)
	v_add_f32_e32 v25, v25, v26
	ds_bpermute_b32 v26, v157, v25
	s_waitcnt lgkmcnt(0)
	v_add_f32_e32 v25, v25, v26
	ds_bpermute_b32 v26, v159, v25
	s_waitcnt lgkmcnt(0)
	v_add_f32_e32 v25, v25, v26
	ds_bpermute_b32 v26, v161, v25
	s_waitcnt lgkmcnt(0)
	v_add_f32_e32 v25, v25, v26
	v_fmamk_f32 v25, v25, 0x3a800000, v177
	v_cmp_gt_f32_e32 vcc, s53, v25
	v_mul_f32_e32 v26, 0x4f800000, v25
	s_nop 0
	v_cndmask_b32_e32 v25, v25, v26, vcc
	v_sqrt_f32_e32 v26, v25
	s_nop 0
	v_add_u32_e32 v27, -1, v26
	v_fma_f32 v28, -v27, v26, v25
	v_cmp_ge_f32_e64 s[4:5], 0, v28
	v_add_u32_e32 v28, 1, v26
	s_nop 0
	v_cndmask_b32_e64 v27, v26, v27, s[4:5]
	v_fma_f32 v26, -v28, v26, v25
	v_cmp_lt_f32_e64 s[4:5], 0, v26
	s_nop 1
	v_cndmask_b32_e64 v26, v27, v28, s[4:5]
	v_mul_f32_e32 v27, 0x37800000, v26
	v_cndmask_b32_e32 v26, v26, v27, vcc
	v_cmp_class_f32_e32 vcc, v25, v234
	s_nop 1
	v_cndmask_b32_e32 v25, v26, v25, vcc
	v_div_scale_f32 v26, s[2:3], v25, v25, 1.0
	v_rcp_f32_e32 v27, v26
	s_nop 0
	v_fma_f32 v28, -v26, v27, 1.0
	v_fmac_f32_e32 v27, v28, v27
	v_div_scale_f32 v28, vcc, 1.0, v25, 1.0
	v_mul_f32_e32 v29, v28, v27
	v_fma_f32 v30, -v26, v29, v28
	v_fmac_f32_e32 v29, v30, v27
	v_fma_f32 v26, -v26, v29, v28
	v_div_fmas_f32 v26, v26, v27, v29
	v_div_fixup_f32 v46, v26, v25, 1.0
	ds_bpermute_b32 v25, v97, v24
	v_mul_f32_e32 v30, v72, v44
	v_mul_f32_e32 v48, v48, v46
	v_mul_f32_e32 v49, v49, v46
	v_mul_f32_e32 v20, v20, v46
	s_waitcnt lgkmcnt(0)
	v_add_f32_e32 v24, v24, v25
	ds_bpermute_b32 v25, v147, v24
	v_mul_f32_e32 v21, v21, v46
	v_mul_f32_e32 v4, v4, v46
	v_mul_f32_e32 v5, v5, v46
	s_waitcnt lgkmcnt(0)
	v_add_f32_e32 v24, v24, v25
	ds_bpermute_b32 v25, v155, v24
	s_waitcnt lgkmcnt(0)
	v_add_f32_e32 v24, v24, v25
	ds_bpermute_b32 v25, v157, v24
	s_waitcnt lgkmcnt(0)
	v_add_f32_e32 v24, v24, v25
	ds_bpermute_b32 v25, v159, v24
	s_waitcnt lgkmcnt(0)
	v_add_f32_e32 v24, v24, v25
	ds_bpermute_b32 v25, v161, v24
	s_waitcnt lgkmcnt(0)
	v_add_f32_e32 v24, v24, v25
	v_fmamk_f32 v24, v24, 0x3a800000, v177
	v_cmp_gt_f32_e32 vcc, s53, v24
	v_mul_f32_e32 v25, 0x4f800000, v24
	s_nop 0
	v_cndmask_b32_e32 v24, v24, v25, vcc
	v_sqrt_f32_e32 v25, v24
	s_nop 0
	v_add_u32_e32 v26, -1, v25
	v_fma_f32 v27, -v26, v25, v24
	v_cmp_ge_f32_e64 s[4:5], 0, v27
	v_add_u32_e32 v27, 1, v25
	s_nop 0
	v_cndmask_b32_e64 v26, v25, v26, s[4:5]
	v_fma_f32 v25, -v27, v25, v24
	v_cmp_lt_f32_e64 s[4:5], 0, v25
	s_nop 1
	v_cndmask_b32_e64 v25, v26, v27, s[4:5]
	v_mul_f32_e32 v26, 0x37800000, v25
	v_cndmask_b32_e32 v25, v25, v26, vcc
	v_cmp_class_f32_e32 vcc, v24, v234
	s_nop 1
	v_cndmask_b32_e32 v24, v25, v24, vcc
	v_div_scale_f32 v25, s[2:3], v24, v24, 1.0
	v_rcp_f32_e32 v26, v25
	s_nop 0
	v_fma_f32 v27, -v25, v26, 1.0
	v_fmac_f32_e32 v26, v27, v26
	v_div_scale_f32 v27, vcc, 1.0, v24, 1.0
	v_mul_f32_e32 v28, v27, v26
	v_fma_f32 v29, -v25, v28, v27
	v_fmac_f32_e32 v28, v29, v26
	v_fma_f32 v25, -v25, v28, v27
	v_div_fmas_f32 v25, v25, v26, v28
	v_div_fixup_f32 v47, v25, v24, 1.0
	global_load_dwordx4 v[24:27], v[88:89], off
	v_lshl_add_u64 v[28:29], s[20:21], 1, v[90:91]
	v_mul_f32_e32 v40, v40, v47
	v_mul_f32_e32 v16, v16, v47
	v_mul_f32_e32 v17, v17, v47
	v_mul_f32_e32 v0, v0, v47
	v_mul_f32_e32 v1, v1, v47
	s_waitcnt vmcnt(0)
	v_mul_f32_e32 v30, v30, v24
	v_mul_f32_e32 v31, v31, v25
	v_bfe_u32 v56, v30, 16, 1
	v_add3_u32 v30, v30, v56, s36
	v_bfe_u32 v56, v31, 16, 1
	v_lshrrev_b32_e32 v30, 16, v30
	v_add3_u32 v31, v31, v56, s36
	v_and_or_b32 v30, v31, s68, v30
	v_mul_f32_e32 v31, v74, v44
	v_mul_f32_e32 v31, v31, v26
	v_mul_f32_e32 v56, v75, v44
	v_mul_f32_e32 v56, v56, v27
	v_bfe_u32 v57, v31, 16, 1
	v_add3_u32 v31, v31, v57, s36
	v_bfe_u32 v57, v56, 16, 1
	v_lshrrev_b32_e32 v31, 16, v31
	v_add3_u32 v56, v56, v57, s36
	v_and_or_b32 v31, v56, s68, v31
	global_store_dwordx2 v[28:29], v[30:31], off sc1
	v_mul_f32_e32 v30, v64, v45
	v_mul_f32_e32 v30, v30, v24
	v_mul_f32_e32 v31, v65, v45
	v_mul_f32_e32 v31, v31, v25
	v_bfe_u32 v56, v30, 16, 1
	v_add3_u32 v30, v30, v56, s36
	v_bfe_u32 v56, v31, 16, 1
	v_lshrrev_b32_e32 v30, 16, v30
	v_add3_u32 v31, v31, v56, s36
	v_and_or_b32 v30, v31, s68, v30
	v_mul_f32_e32 v31, v66, v45
	v_mul_f32_e32 v31, v31, v26
	v_mul_f32_e32 v56, v67, v45
	v_mul_f32_e32 v56, v56, v27
	v_bfe_u32 v57, v31, 16, 1
	v_add3_u32 v31, v31, v57, s36
	v_bfe_u32 v57, v56, 16, 1
	v_lshrrev_b32_e32 v31, 16, v31
	v_add3_u32 v56, v56, v57, s36
	v_and_or_b32 v31, v56, s68, v31
	global_store_dwordx2 v[28:29], v[30:31], off offset:2048 sc1
	v_mul_f32_e32 v30, v76, v46
	v_mul_f32_e32 v30, v30, v24
	v_mul_f32_e32 v31, v77, v46
	v_mul_f32_e32 v31, v31, v25
	v_bfe_u32 v56, v30, 16, 1
	v_add3_u32 v30, v30, v56, s36
	v_bfe_u32 v56, v31, 16, 1
	v_lshrrev_b32_e32 v30, 16, v30
	v_add3_u32 v31, v31, v56, s36
	v_and_or_b32 v56, v31, s68, v30
	v_mul_f32_e32 v30, v78, v46
	v_mul_f32_e32 v30, v30, v26
	v_mul_f32_e32 v31, v79, v46
	v_mul_f32_e32 v31, v31, v27
	v_bfe_u32 v57, v30, 16, 1
	v_add3_u32 v30, v30, v57, s36
	v_bfe_u32 v57, v31, 16, 1
	v_lshrrev_b32_e32 v30, 16, v30
	v_add3_u32 v31, v31, v57, s36
	v_and_or_b32 v57, v31, s68, v30
	v_add_co_u32_e32 v30, vcc, s79, v28
	s_nop 1
	v_addc_co_u32_e32 v31, vcc, 0, v29, vcc
	global_store_dwordx2 v[30:31], v[56:57], off sc1
	v_mul_f32_e32 v56, v60, v47
	v_mul_f32_e32 v24, v24, v56
	v_mul_f32_e32 v56, v61, v47
	v_mul_f32_e32 v25, v25, v56
	v_bfe_u32 v56, v24, 16, 1
	v_add3_u32 v24, v24, v56, s36
	v_bfe_u32 v56, v25, 16, 1
	v_lshrrev_b32_e32 v24, 16, v24
	v_add3_u32 v25, v25, v56, s36
	v_and_or_b32 v24, v25, s68, v24
	v_mul_f32_e32 v25, v62, v47
	v_mul_f32_e32 v25, v26, v25
	v_mul_f32_e32 v26, v63, v47
	v_mul_f32_e32 v26, v27, v26
	v_bfe_u32 v27, v25, 16, 1
	v_add3_u32 v25, v25, v27, s36
	v_bfe_u32 v27, v26, 16, 1
	v_lshrrev_b32_e32 v25, 16, v25
	v_add3_u32 v26, v26, v27, s36
	v_and_or_b32 v25, v26, s68, v25
	global_store_dwordx2 v[30:31], v[24:25], off offset:2048 sc1
	global_load_dwordx4 v[24:27], v[88:89], off offset:1024
	v_mul_f32_e32 v56, v68, v44
	v_mul_f32_e32 v57, v69, v44
	s_waitcnt vmcnt(0)
	v_mul_f32_e32 v56, v56, v24
	v_mul_f32_e32 v57, v57, v25
	v_bfe_u32 v58, v56, 16, 1
	v_add3_u32 v56, v56, v58, s36
	v_bfe_u32 v58, v57, 16, 1
	v_lshrrev_b32_e32 v56, 16, v56
	v_add3_u32 v57, v57, v58, s36
	v_and_or_b32 v56, v57, s68, v56
	v_mul_f32_e32 v57, v70, v44
	v_mul_f32_e32 v57, v57, v26
	v_mul_f32_e32 v58, v71, v44
	v_mul_f32_e32 v58, v58, v27
	v_bfe_u32 v59, v57, 16, 1
	v_add3_u32 v57, v57, v59, s36
	v_bfe_u32 v59, v58, 16, 1
	v_lshrrev_b32_e32 v57, 16, v57
	v_add3_u32 v58, v58, v59, s36
	v_and_or_b32 v57, v58, s68, v57
	v_mul_f32_e32 v52, v52, v24
	global_store_dwordx2 v[28:29], v[56:57], off offset:512 sc1
	v_mul_f32_e32 v53, v53, v25
	v_bfe_u32 v56, v52, 16, 1
	v_add3_u32 v52, v52, v56, s36
	v_bfe_u32 v56, v53, 16, 1
	v_lshrrev_b32_e32 v52, 16, v52
	v_add3_u32 v53, v53, v56, s36
	v_and_or_b32 v52, v53, s68, v52
	v_mul_f32_e32 v53, v54, v45
	v_mul_f32_e32 v53, v53, v26
	v_mul_f32_e32 v54, v55, v45
	v_mul_f32_e32 v54, v54, v27
	v_bfe_u32 v55, v53, 16, 1
	v_add3_u32 v53, v53, v55, s36
	v_bfe_u32 v55, v54, 16, 1
	v_lshrrev_b32_e32 v53, 16, v53
	v_add3_u32 v54, v54, v55, s36
	v_and_or_b32 v53, v54, s68, v53
	v_mul_f32_e32 v48, v48, v24
	v_mul_f32_e32 v24, v24, v40
	v_mul_f32_e32 v40, v41, v47
	global_store_dwordx2 v[28:29], v[52:53], off offset:2560 sc1
	v_mul_f32_e32 v49, v49, v25
	v_bfe_u32 v52, v48, 16, 1
	v_mul_f32_e32 v25, v25, v40
	v_bfe_u32 v40, v24, 16, 1
	v_add3_u32 v48, v48, v52, s36
	v_bfe_u32 v52, v49, 16, 1
	v_add3_u32 v24, v24, v40, s36
	v_bfe_u32 v40, v25, 16, 1
	v_lshrrev_b32_e32 v48, 16, v48
	v_add3_u32 v49, v49, v52, s36
	v_lshrrev_b32_e32 v24, 16, v24
	v_add3_u32 v25, v25, v40, s36
	v_and_or_b32 v48, v49, s68, v48
	v_mul_f32_e32 v49, v50, v46
	v_and_or_b32 v24, v25, s68, v24
	v_mul_f32_e32 v25, v42, v47
	v_mul_f32_e32 v49, v49, v26
	v_mul_f32_e32 v50, v51, v46
	v_mul_f32_e32 v25, v26, v25
	v_mul_f32_e32 v26, v43, v47
	v_mul_f32_e32 v50, v50, v27
	v_bfe_u32 v51, v49, 16, 1
	v_mul_f32_e32 v26, v27, v26
	v_bfe_u32 v27, v25, 16, 1
	v_add3_u32 v49, v49, v51, s36
	v_bfe_u32 v51, v50, 16, 1
	v_add3_u32 v25, v25, v27, s36
	v_bfe_u32 v27, v26, 16, 1
	v_lshrrev_b32_e32 v49, 16, v49
	v_add3_u32 v50, v50, v51, s36
	v_lshrrev_b32_e32 v25, 16, v25
	v_add3_u32 v26, v26, v27, s36
	v_and_or_b32 v49, v50, s68, v49
	v_and_or_b32 v25, v26, s68, v25
	global_store_dwordx2 v[30:31], v[48:49], off offset:512 sc1
	global_store_dwordx2 v[30:31], v[24:25], off offset:2560 sc1
	global_load_dwordx4 v[24:27], v[88:89], off offset:2048
	s_waitcnt vmcnt(0)
	v_mul_f32_e32 v36, v36, v24
	v_mul_f32_e32 v37, v37, v25
	v_bfe_u32 v40, v36, 16, 1
	v_add3_u32 v36, v36, v40, s36
	v_bfe_u32 v40, v37, 16, 1
	v_lshrrev_b32_e32 v36, 16, v36
	v_add3_u32 v37, v37, v40, s36
	v_and_or_b32 v36, v37, s68, v36
	v_mul_f32_e32 v37, v38, v44
	v_mul_f32_e32 v37, v37, v26
	v_mul_f32_e32 v38, v39, v44
	v_mul_f32_e32 v38, v38, v27
	v_bfe_u32 v39, v37, 16, 1
	v_add3_u32 v37, v37, v39, s36
	v_bfe_u32 v39, v38, 16, 1
	v_lshrrev_b32_e32 v37, 16, v37
	v_add3_u32 v38, v38, v39, s36
	v_and_or_b32 v37, v38, s68, v37
	v_mul_f32_e32 v32, v32, v24
	global_store_dwordx2 v[28:29], v[36:37], off offset:1024 sc1
	v_mul_f32_e32 v33, v33, v25
	v_bfe_u32 v36, v32, 16, 1
	v_add3_u32 v32, v32, v36, s36
	v_bfe_u32 v36, v33, 16, 1
	v_lshrrev_b32_e32 v32, 16, v32
	v_add3_u32 v33, v33, v36, s36
	v_and_or_b32 v32, v33, s68, v32
	v_mul_f32_e32 v33, v34, v45
	v_mul_f32_e32 v33, v33, v26
	v_mul_f32_e32 v34, v35, v45
	v_mul_f32_e32 v34, v34, v27
	v_bfe_u32 v35, v33, 16, 1
	v_add3_u32 v33, v33, v35, s36
	v_bfe_u32 v35, v34, 16, 1
	v_lshrrev_b32_e32 v33, 16, v33
	v_add3_u32 v34, v34, v35, s36
	v_and_or_b32 v33, v34, s68, v33
	v_mul_f32_e32 v20, v20, v24
	global_store_dwordx2 v[28:29], v[32:33], off offset:3072 sc1
	v_mul_f32_e32 v21, v21, v25
	v_bfe_u32 v32, v20, 16, 1
	v_add3_u32 v20, v20, v32, s36
	v_bfe_u32 v32, v21, 16, 1
	v_lshrrev_b32_e32 v20, 16, v20
	v_add3_u32 v21, v21, v32, s36
	v_and_or_b32 v20, v21, s68, v20
	v_mul_f32_e32 v21, v22, v46
	v_mul_f32_e32 v21, v21, v26
	v_mul_f32_e32 v22, v23, v46
	v_mul_f32_e32 v22, v22, v27
	v_bfe_u32 v23, v21, 16, 1
	v_add3_u32 v21, v21, v23, s36
	v_bfe_u32 v23, v22, 16, 1
	v_lshrrev_b32_e32 v21, 16, v21
	v_add3_u32 v22, v22, v23, s36
	v_and_or_b32 v21, v22, s68, v21
	v_mul_f32_e32 v16, v16, v24
	global_store_dwordx2 v[30:31], v[20:21], off offset:1024 sc1
	v_mul_f32_e32 v17, v17, v25
	v_bfe_u32 v20, v16, 16, 1
	v_add3_u32 v16, v16, v20, s36
	v_bfe_u32 v20, v17, 16, 1
	v_lshrrev_b32_e32 v16, 16, v16
	v_add3_u32 v17, v17, v20, s36
	v_and_or_b32 v16, v17, s68, v16
	v_mul_f32_e32 v17, v18, v47
	v_mul_f32_e32 v17, v17, v26
	v_mul_f32_e32 v18, v19, v47
	v_mul_f32_e32 v18, v18, v27
	v_bfe_u32 v19, v17, 16, 1
	v_add3_u32 v17, v17, v19, s36
	v_bfe_u32 v19, v18, 16, 1
	v_lshrrev_b32_e32 v17, 16, v17
	v_add3_u32 v18, v18, v19, s36
	v_and_or_b32 v17, v18, s68, v17
	global_store_dwordx2 v[30:31], v[16:17], off offset:3072 sc1
	global_load_dwordx4 v[16:19], v[88:89], off offset:3072
	s_waitcnt vmcnt(0)
	v_mul_f32_e32 v12, v12, v16
	v_mul_f32_e32 v13, v13, v17
	v_bfe_u32 v20, v12, 16, 1
	v_add3_u32 v12, v12, v20, s36
	v_bfe_u32 v20, v13, 16, 1
	v_lshrrev_b32_e32 v12, 16, v12
	v_add3_u32 v13, v13, v20, s36
	v_and_or_b32 v12, v13, s68, v12
	v_mul_f32_e32 v13, v14, v44
	v_mul_f32_e32 v13, v13, v18
	v_mul_f32_e32 v14, v15, v44
	v_mul_f32_e32 v14, v14, v19
	v_bfe_u32 v15, v13, 16, 1
	v_add3_u32 v13, v13, v15, s36
	v_bfe_u32 v15, v14, 16, 1
	v_lshrrev_b32_e32 v13, 16, v13
	v_add3_u32 v14, v14, v15, s36
	v_and_or_b32 v13, v14, s68, v13
	v_mul_f32_e32 v8, v8, v16
	global_store_dwordx2 v[28:29], v[12:13], off offset:1536 sc1
	v_mul_f32_e32 v9, v9, v17
	v_bfe_u32 v12, v8, 16, 1
	v_add3_u32 v8, v8, v12, s36
	v_bfe_u32 v12, v9, 16, 1
	v_lshrrev_b32_e32 v8, 16, v8
	v_add3_u32 v9, v9, v12, s36
	v_and_or_b32 v8, v9, s68, v8
	v_mul_f32_e32 v9, v10, v45
	v_mul_f32_e32 v9, v9, v18
	v_mul_f32_e32 v10, v11, v45
	v_mul_f32_e32 v10, v10, v19
	v_bfe_u32 v11, v9, 16, 1
	v_add3_u32 v9, v9, v11, s36
	v_bfe_u32 v11, v10, 16, 1
	v_lshrrev_b32_e32 v9, 16, v9
	v_add3_u32 v10, v10, v11, s36
	v_and_or_b32 v9, v10, s68, v9
	v_mul_f32_e32 v4, v4, v16
	global_store_dwordx2 v[28:29], v[8:9], off offset:3584 sc1
	v_mul_f32_e32 v5, v5, v17
	v_bfe_u32 v8, v4, 16, 1
	v_add3_u32 v4, v4, v8, s36
	v_bfe_u32 v8, v5, 16, 1
	v_lshrrev_b32_e32 v4, 16, v4
	v_add3_u32 v5, v5, v8, s36
	v_and_or_b32 v4, v5, s68, v4
	v_mul_f32_e32 v5, v6, v46
	v_mul_f32_e32 v5, v5, v18
	v_mul_f32_e32 v6, v7, v46
	v_mul_f32_e32 v6, v6, v19
	v_bfe_u32 v7, v5, 16, 1
	v_add3_u32 v5, v5, v7, s36
	v_bfe_u32 v7, v6, 16, 1
	v_lshrrev_b32_e32 v5, 16, v5
	v_add3_u32 v6, v6, v7, s36
	v_and_or_b32 v5, v6, s68, v5
	v_mul_f32_e32 v0, v0, v16
	global_store_dwordx2 v[30:31], v[4:5], off offset:1536 sc1
	v_mul_f32_e32 v1, v1, v17
	v_bfe_u32 v4, v0, 16, 1
	v_add3_u32 v0, v0, v4, s36
	v_bfe_u32 v4, v1, 16, 1
	v_lshrrev_b32_e32 v0, 16, v0
	v_add3_u32 v1, v1, v4, s36
	v_and_or_b32 v0, v1, s68, v0
	v_mul_f32_e32 v1, v2, v47
	v_mul_f32_e32 v1, v1, v18
	v_mul_f32_e32 v2, v3, v47
	v_mul_f32_e32 v2, v2, v19
	v_bfe_u32 v3, v1, 16, 1
	v_add3_u32 v1, v1, v3, s36
	v_bfe_u32 v3, v2, 16, 1
	v_lshrrev_b32_e32 v1, 16, v1
	v_add3_u32 v2, v2, v3, s36
	v_and_or_b32 v1, v2, s68, v1
	global_store_dwordx2 v[30:31], v[0:1], off offset:3584 sc1
	s_branch .LBB0_1847
